# RWKV and HGRN scans: LDS tiles double-buffered (one barrier per 16-token block), XCD-barrier LDS state moved to 0xC800
# speedup vs baseline: 1.0962x; 1.0029x over previous
_Z6k_mega6Params:
	s_load_dwordx2 s[4:5], s[0:1], 0x160
	s_load_dwordx8 s[84:91], s[0:1], 0x140
	v_and_b32_e32 v148, 0x3ff, v0
	s_waitcnt lgkmcnt(0)
	v_writelane_b32 v159, s4, 0
	s_nop 1
	v_writelane_b32 v159, s5, 1
	v_cmp_eq_u32_e64 s[4:5], 0, v148
	s_mov_b64 s[6:7], exec
	s_nop 0
	v_writelane_b32 v159, s4, 2
	s_nop 1
	v_writelane_b32 v159, s5, 3
	s_and_b64 s[4:5], s[6:7], s[4:5]
	s_mov_b64 exec, s[4:5]
	v_mov_b32_e32 v2, 0
	v_mov_b32_e32 v3, v2
	v_mov_b32_e32 v4, v2
	v_mov_b32_e32 v5, v2
	ds_write_b128 v2, v[2:5] offset:51200
	s_or_b64 exec, exec, s[6:7]
	s_load_dwordx16 s[4:19], s[0:1], 0x40
	s_load_dwordx16 s[36:51], s[0:1], 0x100
	s_waitcnt lgkmcnt(0)
	s_barrier
	v_writelane_b32 v159, s4, 4
	s_load_dword s94, s[0:1], 0x168
	s_add_u32 s24, s0, 0x168
	v_writelane_b32 v159, s5, 5
	v_writelane_b32 v159, s6, 6
	v_writelane_b32 v159, s7, 7
	v_writelane_b32 v159, s8, 8
	v_writelane_b32 v159, s9, 9
	v_writelane_b32 v159, s10, 10
	v_writelane_b32 v159, s11, 11
	v_writelane_b32 v159, s12, 12
	v_writelane_b32 v159, s13, 13
	v_writelane_b32 v159, s14, 14
	v_writelane_b32 v159, s15, 15
	v_writelane_b32 v159, s16, 16
	v_writelane_b32 v159, s17, 17
	v_writelane_b32 v159, s18, 18
	v_writelane_b32 v159, s19, 19
	s_load_dwordx16 s[4:19], s[0:1], 0x80
	s_addc_u32 s25, s1, 0
	s_waitcnt lgkmcnt(0)
	v_writelane_b32 v159, s4, 20
	s_nop 1
	v_writelane_b32 v159, s5, 21
	v_writelane_b32 v159, s6, 22
	v_writelane_b32 v159, s7, 23
	v_writelane_b32 v159, s8, 24
	v_writelane_b32 v159, s9, 25
	v_writelane_b32 v159, s10, 26
	v_writelane_b32 v159, s11, 27
	v_writelane_b32 v159, s12, 28
	v_writelane_b32 v159, s13, 29
	v_writelane_b32 v159, s14, 30
	v_writelane_b32 v159, s15, 31
	v_writelane_b32 v159, s16, 32
	v_writelane_b32 v159, s17, 33
	v_writelane_b32 v159, s18, 34
	v_writelane_b32 v159, s19, 35
	s_load_dwordx16 s[4:19], s[0:1], 0xc0
	s_waitcnt lgkmcnt(0)
	v_writelane_b32 v159, s4, 36
	s_nop 1
	v_writelane_b32 v159, s5, 37
	v_writelane_b32 v159, s6, 38
	v_writelane_b32 v159, s7, 39
	v_writelane_b32 v159, s8, 40
	v_writelane_b32 v159, s9, 41
	v_writelane_b32 v159, s10, 42
	v_writelane_b32 v159, s11, 43
	v_writelane_b32 v159, s12, 44
	v_writelane_b32 v159, s13, 45
	v_writelane_b32 v159, s14, 46
	v_writelane_b32 v159, s15, 47
	v_writelane_b32 v159, s16, 48
	v_writelane_b32 v159, s17, 49
	v_writelane_b32 v159, s18, 50
	v_writelane_b32 v159, s19, 51
	s_mov_b64 s[4:5], exec
	v_readlane_b32 s6, v159, 2
	v_readlane_b32 s7, v159, 3
	s_and_b64 s[6:7], s[4:5], s[6:7]
	s_mov_b64 exec, s[6:7]
	s_cbranch_execz .LBB0_5
	s_mov_b64 s[6:7], exec
	v_mbcnt_lo_u32_b32 v1, s6, 0
	v_mbcnt_hi_u32_b32 v1, s7, v1
	v_cmp_eq_u32_e32 vcc, 0, v1
	s_getreg_b32 s8, hwreg(HW_REG_XCC_ID, 0, 4)
	s_and_b64 s[10:11], exec, vcc
	s_mov_b64 exec, s[10:11]
	s_cbranch_execz .LBB0_5
	s_bcnt1_i32_b64 s6, s[6:7]
	v_mov_b32_e32 v2, s6
	s_load_dwordx2 s[6:7], s[0:1], 0x160
	s_lshl_b32 s8, s8, 8
	s_and_b32 s8, s8, 0xf00
	v_mov_b32_e32 v1, s8
	s_waitcnt lgkmcnt(0)
	global_atomic_add v1, v2, s[6:7] offset:1024

.LBB0_105:
	v_readlane_b32 s8, v159, 0
	v_readlane_b32 s9, v159, 1
	s_waitcnt vmcnt(0)
	s_barrier
	s_mov_b64 s[2:3], exec
	v_readlane_b32 s0, v159, 2
	v_readlane_b32 s1, v159, 3
	s_and_b64 s[0:1], s[2:3], s[0:1]
	s_mov_b64 exec, s[0:1]
	s_cbranch_execz .Lxbc_215
	s_mov_b64 s[0:1], src_shared_base
	v_mov_b32_e32 v0, 0xc800
	v_mov_b32_e32 v1, s1
	s_waitcnt vmcnt(0) expcnt(0) lgkmcnt(0)
	s_getreg_b32 s0, hwreg(HW_REG_XCC_ID, 0, 4)
	flat_load_dword v2, v[0:1] sc0 sc1
	s_waitcnt vmcnt(0)
	v_mov_b32_e32 v0, 0xc804
	flat_load_dword v0, v[0:1] sc0 sc1
	s_waitcnt vmcnt(0)
	s_and_b32 s33, s0, 15
	s_waitcnt lgkmcnt(0)
	v_cmp_eq_u32_e32 vcc, 0, v2
	s_and_saveexec_b64 s[52:53], vcc
	s_cbranch_execz .Lxbc_186
	s_add_u32 s4, s8, 0x1000
	s_addc_u32 s5, s9, 0
	s_add_u32 s6, s8, 0x1100
	s_addc_u32 s7, s9, 0
	s_add_u32 s10, s8, 0x1200
	s_addc_u32 s11, s9, 0
	s_add_u32 s12, s8, 0x1300
	s_addc_u32 s13, s9, 0
	s_mov_b32 s22, 1
	s_mov_b64 s[0:1], 0
	v_mov_b64_e32 v[0:1], s[8:9]
	v_mov_b64_e32 v[2:3], s[4:5]
	v_mov_b64_e32 v[4:5], s[6:7]
	v_mov_b64_e32 v[6:7], s[10:11]
	v_mov_b64_e32 v[8:9], s[12:13]
	s_branch .Lxbc_176

.Lxbc_185:
	s_or_b64 exec, exec, s[0:1]
	s_cmp_eq_u32 s33, 15
	s_cselect_b64 vcc, -1, 0
	s_cmp_eq_u32 s33, 14
	s_cselect_b64 s[0:1], -1, 0
	s_cmp_eq_u32 s33, 13
	s_cselect_b64 s[4:5], -1, 0
	s_cmp_eq_u32 s33, 12
	s_cselect_b64 s[6:7], -1, 0
	s_cmp_eq_u32 s33, 11
	s_cselect_b64 s[10:11], -1, 0
	s_cmp_eq_u32 s33, 10
	s_cselect_b64 s[12:13], -1, 0
	s_cmp_eq_u32 s33, 9
	s_cselect_b64 s[14:15], -1, 0
	s_cmp_eq_u32 s33, 8
	s_cselect_b64 s[16:17], -1, 0
	s_cmp_eq_u32 s33, 7
	s_cselect_b64 s[18:19], -1, 0
	s_cmp_eq_u32 s33, 6
	s_cselect_b64 s[20:21], -1, 0
	s_cmp_eq_u32 s33, 5
	s_cselect_b64 s[22:23], -1, 0
	s_cmp_eq_u32 s33, 4
	s_cselect_b64 s[24:25], -1, 0
	s_cmp_eq_u32 s33, 3
	s_cselect_b64 s[26:27], -1, 0
	s_cmp_eq_u32 s33, 2
	s_cselect_b64 s[28:29], -1, 0
	s_cmp_eq_u32 s33, 1
	s_cselect_b64 s[30:31], -1, 0
	s_cmp_eq_u32 s33, 0
	s_cselect_b64 s[34:35], -1, 0
	v_cndmask_b32_e64 v0, 0, v25, s[34:35]
	v_cndmask_b32_e64 v0, v0, v10, s[30:31]
	v_cndmask_b32_e64 v0, v0, v11, s[28:29]
	v_cndmask_b32_e64 v0, v0, v12, s[26:27]
	v_cndmask_b32_e64 v0, v0, v13, s[24:25]
	v_cndmask_b32_e64 v0, v0, v14, s[22:23]
	v_cndmask_b32_e64 v0, v0, v15, s[20:21]
	v_cndmask_b32_e64 v0, v0, v16, s[18:19]
	v_cndmask_b32_e64 v0, v0, v17, s[16:17]
	v_cndmask_b32_e64 v0, v0, v18, s[14:15]
	v_cndmask_b32_e64 v0, v0, v19, s[12:13]
	v_cndmask_b32_e64 v0, v0, v20, s[10:11]
	v_cndmask_b32_e64 v0, v0, v21, s[6:7]
	v_cndmask_b32_e64 v0, v0, v22, s[4:5]
	v_cndmask_b32_e64 v0, v0, v23, s[0:1]
	v_cndmask_b32_e32 v0, v0, v24, vcc
	v_cmp_ne_u32_e32 vcc, 0, v25
	s_mov_b64 s[0:1], src_shared_base
	v_mov_b32_e32 v4, 0xc800
	v_cndmask_b32_e64 v1, 0, 1, vcc
	v_cmp_ne_u32_e32 vcc, 0, v10
	v_mov_b32_e32 v5, s1
	s_nop 0
	v_addc_co_u32_e32 v1, vcc, 0, v1, vcc
	v_cmp_ne_u32_e32 vcc, 0, v11
	s_nop 1
	v_cndmask_b32_e64 v2, 0, 1, vcc
	v_cmp_ne_u32_e32 vcc, 0, v12
	s_nop 1
	v_addc_co_u32_e32 v1, vcc, v1, v2, vcc
	v_cmp_ne_u32_e32 vcc, 0, v13
	s_nop 1
	v_cndmask_b32_e64 v2, 0, 1, vcc
	v_cmp_ne_u32_e32 vcc, 0, v14
	s_nop 1
	v_addc_co_u32_e32 v1, vcc, v1, v2, vcc
	v_cmp_ne_u32_e32 vcc, 0, v15
	s_nop 1
	v_cndmask_b32_e64 v2, 0, 1, vcc
	v_cmp_ne_u32_e32 vcc, 0, v16
	s_nop 1
	v_addc_co_u32_e32 v1, vcc, v1, v2, vcc
	v_cmp_ne_u32_e32 vcc, 0, v17
	s_nop 1
	v_cndmask_b32_e64 v2, 0, 1, vcc
	v_cmp_ne_u32_e32 vcc, 0, v18
	s_nop 1
	v_addc_co_u32_e32 v1, vcc, v1, v2, vcc
	v_cmp_ne_u32_e32 vcc, 0, v19
	s_nop 1
	v_cndmask_b32_e64 v2, 0, 1, vcc
	v_cmp_ne_u32_e32 vcc, 0, v20
	s_nop 1
	v_addc_co_u32_e32 v1, vcc, v1, v2, vcc
	v_cmp_ne_u32_e32 vcc, 0, v21
	s_nop 1
	v_cndmask_b32_e64 v2, 0, 1, vcc
	v_cmp_ne_u32_e32 vcc, 0, v22
	s_nop 1
	v_addc_co_u32_e32 v1, vcc, v1, v2, vcc
	v_cmp_ne_u32_e32 vcc, 0, v23
	s_nop 1
	v_cndmask_b32_e64 v2, 0, 1, vcc
	v_cmp_ne_u32_e32 vcc, 0, v24
	s_nop 1
	v_addc_co_u32_e32 v1, vcc, v1, v2, vcc
	v_max_u32_e32 v2, 1, v0
	v_max_u32_e32 v0, 1, v1
	flat_store_dword v[4:5], v2 sc0 sc1
	s_waitcnt vmcnt(0)
	v_mov_b32_e32 v4, 0xc804
	flat_store_dword v[4:5], v0 sc0 sc1
	s_waitcnt vmcnt(0)

.LBB0_345:
	v_add_u32_e32 v1, s4, v21
	v_mov_b64_e32 v[4:5], s[46:47]
	v_mad_i64_i32 v[32:33], s[0:1], v1, s56, v[4:5]
	s_lshl_b32 s12, s29, 1
	v_lshlrev_b32_e32 v2, 1, v38
	v_lshl_add_u64 v[4:5], v[32:33], 0, s[12:13]
	v_lshl_add_u64 v[4:5], v[4:5], 0, v[2:3]
	s_add_i32 s0, s29, s27
	v_add_co_u32_e32 v6, vcc, 0x1000, v4
	s_addk_i32 s0, 0x1300
	s_nop 0
	v_addc_co_u32_e32 v7, vcc, 0, v5, vcc
	v_or_b32_e32 v40, s0, v20
	v_add_co_u32_e32 v8, vcc, s55, v4
	v_lshlrev_b32_e32 v2, 1, v40
	s_nop 0
	v_addc_co_u32_e32 v9, vcc, 0, v5, vcc
	v_lshl_add_u64 v[32:33], v[32:33], 0, v[2:3]
	global_load_dwordx4 v[4:7], v[6:7], off offset:3584
	s_nop 0
	global_load_dwordx4 v[8:11], v[8:9], off offset:512
	v_lshlrev_b32_e32 v13, 4, v30
	global_load_ushort v39, v[32:33], off
	v_and_b32_e32 v2, 63, v30
	v_and_b32_e32 v13, 48, v13
	v_add_u32_e32 v13, v31, v13
	v_or_b32_e32 v2, 0x200, v2
	v_cmp_gt_u32_e32 vcc, 4, v20
	v_lshlrev_b32_e32 v44, 2, v31
	s_mov_b32 s30, 1
	v_cndmask_b32_e32 v2, v2, v13, vcc
	v_lshlrev_b32_e32 v13, 2, v38
	v_lshl_or_b32 v15, v21, 9, v13
	v_and_b32_e32 v13, 1, v30
	v_cmp_eq_u32_e64 s[0:1], 0, v13
	v_and_b32_e32 v13, 2, v30
	v_cmp_eq_u32_e64 s[4:5], 0, v13
	v_and_b32_e32 v13, -16, v30
	v_cndmask_b32_e64 v41, 0, 16, vcc
	v_lshlrev_b32_e32 v45, 2, v2
	v_or_b32_e32 v2, v13, v20
	s_mov_b32 s31, 0
	v_lshlrev_b32_e32 v17, 2, v30
	v_lshlrev_b32_e32 v21, 4, v20
	v_lshlrev_b32_e32 v46, 2, v2
	v_pk_add_f32 v[30:31], v[22:23], 1.0 op_sel_hi:[1,0] neg_lo:[1,0] neg_hi:[1,0]
	v_pk_add_f32 v[32:33], v[24:25], 1.0 op_sel_hi:[1,0] neg_lo:[1,0] neg_hi:[1,0]
	v_pk_add_f32 v[34:35], v[26:27], 1.0 op_sel_hi:[1,0] neg_lo:[1,0] neg_hi:[1,0]
	v_pk_add_f32 v[36:37], v[28:29], 1.0 op_sel_hi:[1,0] neg_lo:[1,0] neg_hi:[1,0]
	v_lshlrev_b32_e32 v47, 4, v41
	v_lshlrev_b32_e32 v48, 5, v41
	v_mul_u32_u24_e32 v49, 48, v41
	s_lshl_b32 s59, s28, 8
	v_lshlrev_b32_e32 v38, 1, v38
	v_lshlrev_b32_e32 v40, 1, v40
	v_lshlrev_b32_e32 v2, 1, v20
	v_add_u32_e32 v50, 0x6000, v44
	v_mov_b32_e32 v51, v1
	s_movk_i32 s77, 0x7400
	s_movk_i32 s78, 0x5400
	s_barrier
	s_branch .LBB0_347
.LBB0_346:
	ds_read_b128 v[60:63], v21 offset:8192
	ds_read_b128 v[64:67], v21 offset:8448
	ds_read_b128 v[68:71], v21
	ds_read_b128 v[72:75], v21 offset:256
	ds_read2_b32 v[92:93], v50 offset1:16
	ds_read_b128 v[76:79], v21 offset:8704
	ds_read_b128 v[80:83], v21 offset:8960
	ds_read_b128 v[84:87], v21 offset:512
	ds_read_b128 v[88:91], v21 offset:768
	v_lshl_add_u32 v41, s60, 2, v45
	s_waitcnt lgkmcnt(4)
	v_sub_f32_e32 v53, v53, v92
	v_fma_f32 v94, v53, v60, v92
	v_sub_f32_e32 v53, v54, v92
	v_fma_f32 v95, v53, v61, v92
	v_sub_f32_e32 v53, v55, v92
	v_fma_f32 v96, v53, v62, v92
	v_sub_f32_e32 v53, v56, v92
	v_fma_f32 v97, v53, v63, v92
	v_sub_f32_e32 v53, v57, v92
	v_fma_f32 v98, v53, v64, v92
	v_sub_f32_e32 v53, v58, v92
	v_fma_f32 v99, v53, v65, v92
	v_sub_f32_e32 v53, v59, v92
	v_sub_f32_e32 v52, v52, v92
	v_fma_f32 v100, v53, v66, v92
	v_fma_f32 v92, v52, v67, v92
	s_nop 0
	v_mul_f32_e32 v52, v71, v97
	v_mul_f32_e32 v53, v75, v92
	v_fmac_f32_e32 v52, v96, v70
	v_fmac_f32_e32 v53, v100, v74
	v_fmac_f32_e32 v52, v95, v69
	v_fmac_f32_e32 v53, v99, v73
	s_nop 0
	v_fmac_f32_e32 v52, v94, v68
	v_fmac_f32_e32 v53, v98, v72
	v_add_f32_e32 v101, v52, v53
	ds_read_b128 v[52:55], v21 offset:9216
	ds_read_b128 v[56:59], v21 offset:9472
	ds_read_b128 v[60:63], v21 offset:1024
	ds_read_b128 v[64:67], v21 offset:1280
	ds_read_b32 v102, v44 offset:24704
	v_sub_f32_e32 v68, v94, v93
	s_waitcnt lgkmcnt(8)
	v_fma_f32 v94, v68, v76, v93
	v_sub_f32_e32 v68, v95, v93
	v_fma_f32 v95, v68, v77, v93
	v_sub_f32_e32 v68, v96, v93
	v_fma_f32 v96, v68, v78, v93
	v_sub_f32_e32 v68, v97, v93
	v_fma_f32 v97, v68, v79, v93
	v_sub_f32_e32 v68, v98, v93
	s_waitcnt lgkmcnt(7)
	v_fma_f32 v98, v68, v80, v93
	v_sub_f32_e32 v68, v99, v93
	v_fma_f32 v99, v68, v81, v93
	v_sub_f32_e32 v68, v100, v93
	v_fma_f32 v100, v68, v82, v93
	v_sub_f32_e32 v68, v92, v93
	v_fmac_f32_e32 v93, v68, v83
	s_waitcnt lgkmcnt(6)
	v_mul_f32_e32 v68, v87, v97
	s_waitcnt lgkmcnt(5)
	v_mul_f32_e32 v69, v91, v93
	v_fmac_f32_e32 v68, v96, v86
	v_fmac_f32_e32 v69, v100, v90
	v_fmac_f32_e32 v68, v95, v85
	v_fmac_f32_e32 v69, v99, v89
	s_nop 0
	v_fmac_f32_e32 v68, v94, v84
	v_fmac_f32_e32 v69, v98, v88
	v_add_f32_e32 v84, v68, v69
	ds_read_b128 v[68:71], v21 offset:9728
	ds_read_b128 v[72:75], v21 offset:9984
	ds_read_b128 v[76:79], v21 offset:1536
	ds_read_b128 v[80:83], v21 offset:1792
	ds_read_b32 v85, v44 offset:24768
	s_waitcnt lgkmcnt(5)
	v_sub_f32_e32 v86, v94, v102
	v_fma_f32 v86, v86, v52, v102
	v_sub_f32_e32 v52, v95, v102
	v_fma_f32 v87, v52, v53, v102
	v_sub_f32_e32 v52, v96, v102
	v_fma_f32 v88, v52, v54, v102
	v_sub_f32_e32 v52, v97, v102
	v_fma_f32 v89, v52, v55, v102
	v_sub_f32_e32 v52, v98, v102
	v_fma_f32 v90, v52, v56, v102
	v_sub_f32_e32 v52, v99, v102
	v_fma_f32 v91, v52, v57, v102
	v_sub_f32_e32 v52, v100, v102
	v_fma_f32 v92, v52, v58, v102
	v_sub_f32_e32 v52, v93, v102
	v_fmac_f32_e32 v102, v52, v59
	s_nop 0
	v_mul_f32_e32 v52, v63, v89
	v_mul_f32_e32 v53, v67, v102
	v_fmac_f32_e32 v52, v88, v62
	v_fmac_f32_e32 v53, v92, v66
	v_fmac_f32_e32 v52, v87, v61
	v_fmac_f32_e32 v53, v91, v65
	s_nop 0
	v_fmac_f32_e32 v52, v86, v60
	v_fmac_f32_e32 v53, v90, v64
	v_add_f32_e32 v93, v52, v53
	ds_read_b128 v[52:55], v21 offset:10240
	ds_read_b128 v[56:59], v21 offset:10496
	ds_read_b128 v[60:63], v21 offset:2048
	ds_read_b128 v[64:67], v21 offset:2304
	ds_read_b32 v94, v44 offset:24832
	s_waitcnt lgkmcnt(5)
	v_sub_f32_e32 v86, v86, v85
	v_fma_f32 v86, v86, v68, v85
	v_sub_f32_e32 v68, v87, v85
	v_fma_f32 v87, v68, v69, v85
	v_sub_f32_e32 v68, v88, v85
	v_fma_f32 v88, v68, v70, v85
	v_sub_f32_e32 v68, v89, v85
	v_fma_f32 v89, v68, v71, v85
	v_sub_f32_e32 v68, v90, v85
	v_fma_f32 v90, v68, v72, v85
	v_sub_f32_e32 v68, v91, v85
	v_fma_f32 v91, v68, v73, v85
	v_sub_f32_e32 v68, v92, v85
	v_fma_f32 v92, v68, v74, v85
	v_sub_f32_e32 v68, v102, v85
	v_fmac_f32_e32 v85, v68, v75
	s_nop 0
	v_mul_f32_e32 v68, v79, v89
	v_mul_f32_e32 v69, v83, v85
	v_fmac_f32_e32 v68, v88, v78
	v_fmac_f32_e32 v69, v92, v82
	v_fmac_f32_e32 v68, v87, v77
	v_fmac_f32_e32 v69, v91, v81
	v_cndmask_b32_e64 v70, v101, v84, s[0:1]
	v_fmac_f32_e32 v68, v86, v76
	v_fmac_f32_e32 v69, v90, v80
	v_add_f32_e32 v68, v68, v69
	v_cndmask_b32_e64 v69, v84, v101, s[0:1]
	v_cndmask_b32_e64 v71, v68, v93, s[0:1]
	v_cndmask_b32_e64 v68, v93, v68, s[0:1]
	v_add_f32_dpp v69, v70, v69 quad_perm:[1,0,3,2] row_mask:0xf bank_mask:0xf bound_ctrl:1
	s_nop 0
	v_add_f32_dpp v68, v68, v71 quad_perm:[1,0,3,2] row_mask:0xf bank_mask:0xf bound_ctrl:1
	v_cndmask_b32_e64 v70, v68, v69, s[4:5]
	v_cndmask_b32_e64 v68, v69, v68, s[4:5]
	s_nop 1
	v_add_f32_dpp v68, v68, v70 quad_perm:[2,3,0,1] row_mask:0xf bank_mask:0xf bound_ctrl:1
	s_nop 1
	v_add_f32_dpp v68, v68, v68 row_ror:4 row_mask:0xf bank_mask:0xf bound_ctrl:1
	s_nop 1
	v_add_f32_dpp v68, v68, v68 row_ror:8 row_mask:0xf bank_mask:0xf bound_ctrl:1
	ds_write_b32 v41, v68 offset:25600
	ds_read_b128 v[68:71], v21 offset:10752
	ds_read_b128 v[72:75], v21 offset:11008
	ds_read_b128 v[76:79], v21 offset:2560
	ds_read_b128 v[80:83], v21 offset:2816
	ds_read_b32 v84, v44 offset:24896
	s_waitcnt lgkmcnt(6)
	v_sub_f32_e32 v86, v86, v94
	v_fma_f32 v86, v86, v52, v94
	v_sub_f32_e32 v52, v87, v94
	v_fma_f32 v87, v52, v53, v94
	v_sub_f32_e32 v52, v88, v94
	v_fma_f32 v88, v52, v54, v94
	v_sub_f32_e32 v52, v89, v94
	v_fma_f32 v89, v52, v55, v94
	v_sub_f32_e32 v52, v90, v94
	v_fma_f32 v90, v52, v56, v94
	v_sub_f32_e32 v52, v91, v94
	v_fma_f32 v91, v52, v57, v94
	v_sub_f32_e32 v52, v92, v94
	v_fma_f32 v92, v52, v58, v94
	v_sub_f32_e32 v52, v85, v94
	v_fmac_f32_e32 v94, v52, v59
	s_nop 0
	v_mul_f32_e32 v52, v63, v89
	v_mul_f32_e32 v53, v67, v94
	v_fmac_f32_e32 v52, v88, v62
	v_fmac_f32_e32 v53, v92, v66
	v_fmac_f32_e32 v52, v87, v61
	v_fmac_f32_e32 v53, v91, v65
	s_nop 0
	v_fmac_f32_e32 v52, v86, v60
	v_fmac_f32_e32 v53, v90, v64
	v_add_f32_e32 v85, v52, v53
	ds_read_b128 v[52:55], v21 offset:11264
	ds_read_b128 v[56:59], v21 offset:11520
	ds_read_b128 v[60:63], v21 offset:3072
	ds_read_b128 v[64:67], v21 offset:3328
	ds_read_b32 v93, v44 offset:24960
	s_waitcnt lgkmcnt(5)
	v_sub_f32_e32 v86, v86, v84
	v_fma_f32 v86, v86, v68, v84
	v_sub_f32_e32 v68, v87, v84
	v_fma_f32 v87, v68, v69, v84
	v_sub_f32_e32 v68, v88, v84
	v_fma_f32 v88, v68, v70, v84
	v_sub_f32_e32 v68, v89, v84
	v_fma_f32 v89, v68, v71, v84
	v_sub_f32_e32 v68, v90, v84
	v_fma_f32 v90, v68, v72, v84
	v_sub_f32_e32 v68, v91, v84
	v_fma_f32 v91, v68, v73, v84
	v_sub_f32_e32 v68, v92, v84
	v_fma_f32 v92, v68, v74, v84
	v_sub_f32_e32 v68, v94, v84
	v_fmac_f32_e32 v84, v68, v75
	s_nop 0
	v_mul_f32_e32 v68, v79, v89
	v_mul_f32_e32 v69, v83, v84
	v_fmac_f32_e32 v68, v88, v78
	v_fmac_f32_e32 v69, v92, v82
	v_fmac_f32_e32 v68, v87, v77
	v_fmac_f32_e32 v69, v91, v81
	s_nop 0
	v_fmac_f32_e32 v68, v86, v76
	v_fmac_f32_e32 v69, v90, v80
	v_add_f32_e32 v94, v68, v69
	ds_read_b128 v[68:71], v21 offset:11776
	ds_read_b128 v[72:75], v21 offset:12032
	ds_read_b128 v[76:79], v21 offset:3584
	ds_read_b128 v[80:83], v21 offset:3840
	ds_read_b32 v95, v44 offset:25024
	s_waitcnt lgkmcnt(5)
	v_sub_f32_e32 v86, v86, v93
	v_fma_f32 v86, v86, v52, v93
	v_sub_f32_e32 v52, v87, v93
	v_fma_f32 v87, v52, v53, v93
	v_sub_f32_e32 v52, v88, v93
	v_fma_f32 v88, v52, v54, v93
	v_sub_f32_e32 v52, v89, v93
	v_fma_f32 v89, v52, v55, v93
	v_sub_f32_e32 v52, v90, v93
	v_fma_f32 v90, v52, v56, v93
	v_sub_f32_e32 v52, v91, v93
	v_fma_f32 v91, v52, v57, v93
	v_sub_f32_e32 v52, v92, v93
	v_fma_f32 v92, v52, v58, v93
	v_sub_f32_e32 v52, v84, v93
	v_fmac_f32_e32 v93, v52, v59
	s_nop 0
	v_mul_f32_e32 v52, v63, v89
	v_mul_f32_e32 v53, v67, v93
	v_fmac_f32_e32 v52, v88, v62
	v_fmac_f32_e32 v53, v92, v66
	v_fmac_f32_e32 v52, v87, v61
	v_fmac_f32_e32 v53, v91, v65
	s_nop 0
	v_fmac_f32_e32 v52, v86, v60
	v_fmac_f32_e32 v53, v90, v64
	v_add_f32_e32 v84, v52, v53
	ds_read_b128 v[52:55], v21 offset:12288
	ds_read_b128 v[56:59], v21 offset:12544
	ds_read_b128 v[60:63], v21 offset:4096
	ds_read_b128 v[64:67], v21 offset:4352
	ds_read_b32 v96, v44 offset:25088
	s_waitcnt lgkmcnt(5)
	v_sub_f32_e32 v86, v86, v95
	v_fma_f32 v86, v86, v68, v95
	v_sub_f32_e32 v68, v87, v95
	v_fma_f32 v87, v68, v69, v95
	v_sub_f32_e32 v68, v88, v95
	v_fma_f32 v88, v68, v70, v95
	v_sub_f32_e32 v68, v89, v95
	v_fma_f32 v89, v68, v71, v95
	v_sub_f32_e32 v68, v90, v95
	v_fma_f32 v90, v68, v72, v95
	v_sub_f32_e32 v68, v91, v95
	v_fma_f32 v91, v68, v73, v95
	v_sub_f32_e32 v68, v92, v95
	v_fma_f32 v92, v68, v74, v95
	v_sub_f32_e32 v68, v93, v95
	v_fmac_f32_e32 v95, v68, v75
	s_nop 0
	v_mul_f32_e32 v68, v79, v89
	v_mul_f32_e32 v69, v83, v95
	v_fmac_f32_e32 v68, v88, v78
	v_fmac_f32_e32 v69, v92, v82
	v_fmac_f32_e32 v68, v87, v77
	v_fmac_f32_e32 v69, v91, v81
	v_cndmask_b32_e64 v70, v85, v94, s[0:1]
	v_fmac_f32_e32 v68, v86, v76
	v_fmac_f32_e32 v69, v90, v80
	v_add_f32_e32 v68, v68, v69
	v_cndmask_b32_e64 v69, v94, v85, s[0:1]
	v_cndmask_b32_e64 v71, v68, v84, s[0:1]
	v_cndmask_b32_e64 v68, v84, v68, s[0:1]
	v_add_f32_dpp v69, v70, v69 quad_perm:[1,0,3,2] row_mask:0xf bank_mask:0xf bound_ctrl:1
	s_nop 0
	v_add_f32_dpp v68, v68, v71 quad_perm:[1,0,3,2] row_mask:0xf bank_mask:0xf bound_ctrl:1
	v_cndmask_b32_e64 v70, v68, v69, s[4:5]
	v_cndmask_b32_e64 v68, v69, v68, s[4:5]
	v_add_u32_e32 v69, v41, v47
	s_nop 0
	v_add_f32_dpp v68, v68, v70 quad_perm:[2,3,0,1] row_mask:0xf bank_mask:0xf bound_ctrl:1
	s_nop 1
	v_add_f32_dpp v68, v68, v68 row_ror:4 row_mask:0xf bank_mask:0xf bound_ctrl:1
	s_nop 1
	v_add_f32_dpp v68, v68, v68 row_ror:8 row_mask:0xf bank_mask:0xf bound_ctrl:1
	ds_write_b32 v69, v68 offset:25600
	ds_read_b128 v[68:71], v21 offset:12800
	ds_read_b128 v[72:75], v21 offset:13056
	ds_read_b128 v[76:79], v21 offset:4608
	ds_read_b128 v[80:83], v21 offset:4864
	ds_read_b32 v84, v44 offset:25152
	s_waitcnt lgkmcnt(6)
	v_sub_f32_e32 v85, v86, v96
	v_fma_f32 v85, v85, v52, v96
	v_sub_f32_e32 v52, v87, v96
	v_fma_f32 v86, v52, v53, v96
	v_sub_f32_e32 v52, v88, v96
	v_fma_f32 v87, v52, v54, v96
	v_sub_f32_e32 v52, v89, v96
	v_fma_f32 v88, v52, v55, v96
	v_sub_f32_e32 v52, v90, v96
	v_fma_f32 v89, v52, v56, v96
	v_sub_f32_e32 v52, v91, v96
	v_fma_f32 v90, v52, v57, v96
	v_sub_f32_e32 v52, v92, v96
	v_fma_f32 v91, v52, v58, v96
	v_sub_f32_e32 v52, v95, v96
	v_fmac_f32_e32 v96, v52, v59
	s_nop 0
	v_mul_f32_e32 v52, v63, v88
	v_mul_f32_e32 v53, v67, v96
	v_fmac_f32_e32 v52, v87, v62
	v_fmac_f32_e32 v53, v91, v66
	v_fmac_f32_e32 v52, v86, v61
	v_fmac_f32_e32 v53, v90, v65
	s_nop 0
	v_fmac_f32_e32 v52, v85, v60
	v_fmac_f32_e32 v53, v89, v64
	v_add_f32_e32 v92, v52, v53
	ds_read_b128 v[52:55], v21 offset:13312
	ds_read_b128 v[56:59], v21 offset:13568
	ds_read_b128 v[60:63], v21 offset:5120
	ds_read_b128 v[64:67], v21 offset:5376
	ds_read_b32 v93, v44 offset:25216
	s_waitcnt lgkmcnt(5)
	v_sub_f32_e32 v85, v85, v84
	v_fma_f32 v85, v85, v68, v84
	v_sub_f32_e32 v68, v86, v84
	v_fma_f32 v86, v68, v69, v84
	v_sub_f32_e32 v68, v87, v84
	v_fma_f32 v87, v68, v70, v84
	v_sub_f32_e32 v68, v88, v84
	v_fma_f32 v88, v68, v71, v84
	v_sub_f32_e32 v68, v89, v84
	v_fma_f32 v89, v68, v72, v84
	v_sub_f32_e32 v68, v90, v84
	v_fma_f32 v90, v68, v73, v84
	v_sub_f32_e32 v68, v91, v84
	v_fma_f32 v91, v68, v74, v84
	v_sub_f32_e32 v68, v96, v84
	v_fmac_f32_e32 v84, v68, v75
	s_nop 0
	v_mul_f32_e32 v68, v79, v88
	v_mul_f32_e32 v69, v83, v84
	v_fmac_f32_e32 v68, v87, v78
	v_fmac_f32_e32 v69, v91, v82
	v_fmac_f32_e32 v68, v86, v77
	v_fmac_f32_e32 v69, v90, v81
	s_nop 0
	v_fmac_f32_e32 v68, v85, v76
	v_fmac_f32_e32 v69, v89, v80
	v_add_f32_e32 v94, v68, v69
	ds_read_b128 v[68:71], v21 offset:13824
	ds_read_b128 v[72:75], v21 offset:14080
	ds_read_b128 v[76:79], v21 offset:5632
	ds_read_b128 v[80:83], v21 offset:5888
	ds_read_b32 v95, v44 offset:25280
	s_waitcnt lgkmcnt(5)
	v_sub_f32_e32 v85, v85, v93
	v_fma_f32 v85, v85, v52, v93
	v_sub_f32_e32 v52, v86, v93
	v_fma_f32 v86, v52, v53, v93
	v_sub_f32_e32 v52, v87, v93
	v_fma_f32 v87, v52, v54, v93
	v_sub_f32_e32 v52, v88, v93
	v_fma_f32 v88, v52, v55, v93
	v_sub_f32_e32 v52, v89, v93
	v_fma_f32 v89, v52, v56, v93
	v_sub_f32_e32 v52, v90, v93
	v_fma_f32 v90, v52, v57, v93
	v_sub_f32_e32 v52, v91, v93
	v_fma_f32 v91, v52, v58, v93
	v_sub_f32_e32 v52, v84, v93
	v_fmac_f32_e32 v93, v52, v59
	s_nop 0
	v_mul_f32_e32 v52, v63, v88
	v_mul_f32_e32 v53, v67, v93
	v_fmac_f32_e32 v52, v87, v62
	v_fmac_f32_e32 v53, v91, v66
	v_fmac_f32_e32 v52, v86, v61
	v_fmac_f32_e32 v53, v90, v65
	s_nop 0
	v_fmac_f32_e32 v52, v85, v60
	v_fmac_f32_e32 v53, v89, v64
	v_add_f32_e32 v84, v52, v53
	ds_read_b128 v[52:55], v21 offset:14336
	ds_read_b128 v[56:59], v21 offset:14592
	ds_read_b128 v[60:63], v21 offset:6144
	ds_read_b128 v[64:67], v21 offset:6400
	ds_read_b32 v96, v44 offset:25344
	s_waitcnt lgkmcnt(5)
	v_sub_f32_e32 v85, v85, v95
	v_fma_f32 v85, v85, v68, v95
	v_sub_f32_e32 v68, v86, v95
	v_fma_f32 v86, v68, v69, v95
	v_sub_f32_e32 v68, v87, v95
	v_fma_f32 v87, v68, v70, v95
	v_sub_f32_e32 v68, v88, v95
	v_fma_f32 v88, v68, v71, v95
	v_sub_f32_e32 v68, v89, v95
	v_fma_f32 v89, v68, v72, v95
	v_sub_f32_e32 v68, v90, v95
	v_fma_f32 v90, v68, v73, v95
	v_sub_f32_e32 v68, v91, v95
	v_fma_f32 v91, v68, v74, v95
	v_sub_f32_e32 v68, v93, v95
	v_fmac_f32_e32 v95, v68, v75
	s_nop 0
	v_mul_f32_e32 v68, v79, v88
	v_mul_f32_e32 v69, v83, v95
	v_fmac_f32_e32 v68, v87, v78
	v_fmac_f32_e32 v69, v91, v82
	v_fmac_f32_e32 v68, v86, v77
	v_fmac_f32_e32 v69, v90, v81
	v_cndmask_b32_e64 v70, v92, v94, s[0:1]
	v_fmac_f32_e32 v68, v85, v76
	v_fmac_f32_e32 v69, v89, v80
	v_add_f32_e32 v68, v68, v69
	v_cndmask_b32_e64 v69, v94, v92, s[0:1]
	v_cndmask_b32_e64 v71, v68, v84, s[0:1]
	v_cndmask_b32_e64 v68, v84, v68, s[0:1]
	v_add_f32_dpp v69, v70, v69 quad_perm:[1,0,3,2] row_mask:0xf bank_mask:0xf bound_ctrl:1
	s_nop 0
	v_add_f32_dpp v68, v68, v71 quad_perm:[1,0,3,2] row_mask:0xf bank_mask:0xf bound_ctrl:1
	v_cndmask_b32_e64 v70, v68, v69, s[4:5]
	v_cndmask_b32_e64 v68, v69, v68, s[4:5]
	v_add_u32_e32 v69, v41, v48
	s_nop 0
	v_add_f32_dpp v68, v68, v70 quad_perm:[2,3,0,1] row_mask:0xf bank_mask:0xf bound_ctrl:1
	s_nop 1
	v_add_f32_dpp v68, v68, v68 row_ror:4 row_mask:0xf bank_mask:0xf bound_ctrl:1
	s_nop 1
	v_add_f32_dpp v68, v68, v68 row_ror:8 row_mask:0xf bank_mask:0xf bound_ctrl:1
	ds_write_b32 v69, v68 offset:25600
	ds_read_b128 v[68:71], v21 offset:14848
	ds_read_b128 v[72:75], v21 offset:15104
	ds_read_b128 v[76:79], v21 offset:6656
	ds_read_b128 v[80:83], v21 offset:6912
	ds_read_b32 v92, v44 offset:25408
	s_waitcnt lgkmcnt(6)
	v_sub_f32_e32 v84, v85, v96
	v_fma_f32 v52, v84, v52, v96
	v_sub_f32_e32 v84, v86, v96
	v_fma_f32 v53, v84, v53, v96
	v_sub_f32_e32 v84, v87, v96
	v_fma_f32 v93, v84, v54, v96
	v_sub_f32_e32 v54, v88, v96
	v_fma_f32 v88, v54, v55, v96
	v_sub_f32_e32 v54, v89, v96
	v_fma_f32 v89, v54, v56, v96
	v_sub_f32_e32 v54, v90, v96
	v_fma_f32 v90, v54, v57, v96
	v_sub_f32_e32 v54, v91, v96
	v_fma_f32 v91, v54, v58, v96
	v_sub_f32_e32 v54, v95, v96
	v_fmac_f32_e32 v96, v54, v59
	s_nop 0
	v_mul_f32_e32 v54, v63, v88
	v_mul_f32_e32 v55, v67, v96
	v_fmac_f32_e32 v54, v93, v62
	v_fmac_f32_e32 v55, v91, v66
	v_fmac_f32_e32 v54, v53, v61
	v_fmac_f32_e32 v55, v90, v65
	s_nop 0
	v_fmac_f32_e32 v54, v52, v60
	v_fmac_f32_e32 v55, v89, v64
	v_add_f32_e32 v94, v54, v55
	ds_read_b128 v[54:57], v21 offset:15360
	ds_read_b128 v[58:61], v21 offset:15616
	ds_read_b128 v[62:65], v21 offset:7168
	ds_read_b128 v[84:87], v21 offset:7424
	ds_read_b32 v95, v44 offset:25472
	s_waitcnt lgkmcnt(5)
	v_sub_f32_e32 v52, v52, v92
	v_fma_f32 v97, v52, v68, v92
	v_sub_f32_e32 v52, v53, v92
	v_fma_f32 v53, v52, v69, v92
	v_sub_f32_e32 v52, v93, v92
	v_fma_f32 v93, v52, v70, v92
	v_sub_f32_e32 v52, v88, v92
	v_fma_f32 v88, v52, v71, v92
	v_sub_f32_e32 v52, v89, v92
	v_fma_f32 v89, v52, v72, v92
	v_sub_f32_e32 v52, v90, v92
	v_fma_f32 v90, v52, v73, v92
	v_sub_f32_e32 v52, v91, v92
	v_fma_f32 v91, v52, v74, v92
	v_sub_f32_e32 v52, v96, v92
	v_fmac_f32_e32 v92, v52, v75
	s_nop 0
	v_mul_f32_e32 v52, v79, v88
	v_mul_f32_e32 v66, v83, v92
	v_fmac_f32_e32 v52, v93, v78
	v_fmac_f32_e32 v66, v91, v82
	v_fmac_f32_e32 v52, v53, v77
	v_fmac_f32_e32 v66, v90, v81
	s_nop 0
	v_fmac_f32_e32 v52, v97, v76
	v_fmac_f32_e32 v66, v89, v80
	v_add_f32_e32 v82, v52, v66
	ds_read_b128 v[66:69], v21 offset:15872
	ds_read_b128 v[70:73], v21 offset:16128
	ds_read_b128 v[74:77], v21 offset:7680
	ds_read_b128 v[78:81], v21 offset:7936
	ds_read_b32 v52, v44 offset:25536
	s_waitcnt lgkmcnt(5)
	v_sub_f32_e32 v53, v53, v95
	v_fma_f32 v55, v53, v55, v95
	v_sub_f32_e32 v53, v93, v95
	v_fma_f32 v56, v53, v56, v95
	v_sub_f32_e32 v53, v88, v95
	v_fma_f32 v57, v53, v57, v95
	v_sub_f32_e32 v53, v89, v95
	v_fma_f32 v58, v53, v58, v95
	v_sub_f32_e32 v53, v90, v95
	v_fma_f32 v59, v53, v59, v95
	v_sub_f32_e32 v53, v91, v95
	v_sub_f32_e32 v83, v97, v95
	v_fma_f32 v60, v53, v60, v95
	v_sub_f32_e32 v53, v92, v95
	v_fma_f32 v54, v83, v54, v95
	v_fmac_f32_e32 v95, v53, v61
	s_nop 0
	v_mul_f32_e32 v53, v65, v57
	v_mul_f32_e32 v61, v87, v95
	v_fmac_f32_e32 v53, v56, v64
	v_fmac_f32_e32 v61, v60, v86
	v_fmac_f32_e32 v53, v55, v63
	v_fmac_f32_e32 v61, v59, v85
	s_nop 0
	v_fmac_f32_e32 v53, v54, v62
	v_fmac_f32_e32 v61, v58, v84
	v_add_f32_e32 v61, v53, v61
	s_waitcnt lgkmcnt(0)
	v_sub_f32_e32 v53, v54, v52
	v_sub_f32_e32 v54, v55, v52
	v_sub_f32_e32 v55, v56, v52
	v_sub_f32_e32 v56, v57, v52
	v_sub_f32_e32 v57, v58, v52
	v_sub_f32_e32 v58, v59, v52
	v_sub_f32_e32 v59, v60, v52
	v_sub_f32_e32 v60, v95, v52
	v_fma_f32 v53, v53, v66, v52
	v_fma_f32 v54, v54, v67, v52
	v_fma_f32 v55, v55, v68, v52
	v_fma_f32 v56, v56, v69, v52
	v_fma_f32 v57, v57, v70, v52
	v_fma_f32 v58, v58, v71, v52
	v_fma_f32 v59, v59, v72, v52
	v_fmac_f32_e32 v52, v60, v73
	s_nop 0
	v_mul_f32_e32 v60, v77, v56
	v_mul_f32_e32 v62, v81, v52
	v_fmac_f32_e32 v60, v55, v76
	v_fmac_f32_e32 v62, v59, v80
	v_fmac_f32_e32 v60, v54, v75
	v_fmac_f32_e32 v62, v58, v79
	v_cndmask_b32_e64 v63, v94, v82, s[0:1]
	v_fmac_f32_e32 v60, v53, v74
	v_fmac_f32_e32 v62, v57, v78
	v_add_f32_e32 v60, v60, v62
	v_cndmask_b32_e64 v62, v82, v94, s[0:1]
	v_cndmask_b32_e64 v64, v60, v61, s[0:1]
	v_cndmask_b32_e64 v60, v61, v60, s[0:1]
	v_add_f32_dpp v61, v63, v62 quad_perm:[1,0,3,2] row_mask:0xf bank_mask:0xf bound_ctrl:1
	v_add_u32_e32 v41, v41, v49
	v_add_f32_dpp v60, v60, v64 quad_perm:[1,0,3,2] row_mask:0xf bank_mask:0xf bound_ctrl:1
	v_cndmask_b32_e64 v62, v60, v61, s[4:5]
	v_cndmask_b32_e64 v60, v61, v60, s[4:5]
	s_nop 1
	v_add_f32_dpp v60, v60, v62 quad_perm:[2,3,0,1] row_mask:0xf bank_mask:0xf bound_ctrl:1
	s_nop 1
	v_add_f32_dpp v60, v60, v60 row_ror:4 row_mask:0xf bank_mask:0xf bound_ctrl:1
	s_nop 1
	v_add_f32_dpp v60, v60, v60 row_ror:8 row_mask:0xf bank_mask:0xf bound_ctrl:1
	ds_write_b32 v41, v60 offset:25600
	s_addk_i32 s31, 0x100
	s_add_i32 s30, s30, 1
	s_cmp_lg_u32 s59, s31
	v_add_u32_e32 v51, 16, v51
	s_waitcnt lgkmcnt(0)
	s_cbranch_scc0 .Lhg0_exitb
.LBB0_347:
	v_add_u32_e32 v15, s77, v15
	v_add_u32_e32 v17, s78, v17
	s_waitcnt vmcnt(0)
	v_lshlrev_b32_e32 v41, 16, v8
	v_mul_f32_e32 v41, 0xbfb8aa3b, v41
	v_and_b32_e32 v61, 0xffff0000, v8
	v_exp_f32_e32 v41, v41
	v_mul_f32_e32 v61, 0xbfb8aa3b, v61
	v_exp_f32_e32 v62, v61
	v_and_b32_e32 v63, 0xffff0000, v9
	v_add_f32_e32 v41, 1.0, v41
	v_rcp_f32_e32 v68, v41
	v_add_f32_e32 v41, 1.0, v62
	v_rcp_f32_e32 v69, v41
	v_lshlrev_b32_e32 v41, 16, v9
	v_mul_f32_e32 v41, 0xbfb8aa3b, v41
	v_exp_f32_e32 v41, v41
	v_mul_f32_e32 v63, 0xbfb8aa3b, v63
	v_exp_f32_e32 v64, v63
	v_and_b32_e32 v65, 0xffff0000, v10
	v_add_f32_e32 v41, 1.0, v41
	v_rcp_f32_e32 v70, v41
	v_add_f32_e32 v41, 1.0, v64
	v_rcp_f32_e32 v71, v41
	v_lshlrev_b32_e32 v41, 16, v10
	v_mul_f32_e32 v41, 0xbfb8aa3b, v41
	v_exp_f32_e32 v41, v41
	v_mul_f32_e32 v65, 0xbfb8aa3b, v65
	v_exp_f32_e32 v66, v65
	v_and_b32_e32 v67, 0xffff0000, v11
	v_add_f32_e32 v41, 1.0, v41
	v_rcp_f32_e32 v72, v41
	v_add_f32_e32 v41, 1.0, v66
	v_rcp_f32_e32 v73, v41
	v_lshlrev_b32_e32 v41, 16, v11
	v_mul_f32_e32 v41, 0xbfb8aa3b, v41
	v_exp_f32_e32 v41, v41
	v_mul_f32_e32 v67, 0xbfb8aa3b, v67
	v_exp_f32_e32 v75, v67
	v_lshlrev_b32_e32 v60, 16, v4
	v_add_f32_e32 v41, 1.0, v41
	v_rcp_f32_e32 v74, v41
	v_add_f32_e32 v41, 1.0, v75
	v_rcp_f32_e32 v75, v41
	v_and_b32_e32 v61, 0xffff0000, v4
	v_lshlrev_b32_e32 v62, 16, v5
	v_and_b32_e32 v63, 0xffff0000, v5
	v_lshlrev_b32_e32 v64, 16, v6
	v_and_b32_e32 v65, 0xffff0000, v6
	v_lshlrev_b32_e32 v66, 16, v7
	v_and_b32_e32 v67, 0xffff0000, v7
	s_and_b32 s60, s31, 0x100
	ds_write_b128 v15, v[60:63]
	ds_write_b128 v15, v[64:67] offset:16
	v_pk_fma_f32 v[60:61], v[30:31], v[68:69], v[22:23]
	v_pk_fma_f32 v[62:63], v[32:33], v[70:71], v[24:25]
	ds_write_b128 v15, v[60:63] offset:8192
	v_pk_fma_f32 v[60:61], v[34:35], v[72:73], v[26:27]
	v_pk_fma_f32 v[62:63], v[36:37], v[74:75], v[28:29]
	v_lshlrev_b32_e32 v41, 16, v39
	s_cmp_eq_u32 s31, 0
	ds_write_b128 v15, v[60:63] offset:8208
	ds_write_b32 v17, v41 offset:24576
	s_waitcnt lgkmcnt(0)
	s_barrier
	v_add_u32_e32 v21, s77, v21
	v_add_u32_e32 v44, s78, v44
	v_add_u32_e32 v50, s78, v50
	s_mul_i32 s77, s77, -1
	s_mul_i32 s78, s78, -1
	s_cbranch_scc1 .LBB0_349
	v_mov_b64_e32 v[60:61], s[46:47]
	v_mad_i64_i32 v[60:61], s[62:63], v51, s56, v[60:61]
	s_lshl_b32 s12, s29, 1
	v_lshl_add_u64 v[60:61], v[60:61], 0, s[12:13]
	s_lshl_b32 s12, s27, 1
	v_lshl_add_u64 v[60:61], v[60:61], 0, s[12:13]
	s_xor_b32 s12, s60, 0x100
	v_lshl_add_u32 v41, s12, 2, v46
	ds_read_b32 v41, v41 offset:25600
	v_lshl_add_u64 v[60:61], v[60:61], 0, v[2:3]
	v_add_co_u32_e32 v60, vcc, 0xfffd9000, v60
	s_waitcnt lgkmcnt(0)
	v_cvt_pk_bf16_f32 v41, v41, s0
	v_addc_co_u32_e32 v61, vcc, -1, v61, vcc
	global_store_short v[60:61], v41, off offset:-2560

.Lhg0_exitb:
	s_barrier
	s_branch .LBB0_351

.LBB0_389:
	v_add_u32_e32 v1, s8, v24
	v_mov_b64_e32 v[12:13], s[46:47]
	v_mad_i64_i32 v[26:27], s[2:3], v1, s56, v[12:13]
	v_mov_b64_e32 v[12:13], s[88:89]
	v_mad_i64_i32 v[14:15], s[2:3], v1, s58, v[12:13]
	s_lshl_b32 s2, s5, 6
	s_lshl_b32 s12, s5, 7
	v_lshl_add_u64 v[16:17], v[26:27], 0, s[12:13]
	v_lshlrev_b32_e32 v12, 1, v0
	v_mov_b32_e32 v13, v3
	s_or_b32 s3, s7, s2
	v_lshl_add_u64 v[16:17], v[16:17], 0, v[12:13]
	v_or_b32_e32 v2, s3, v10
	v_add_co_u32_e32 v18, vcc, s57, v16
	v_lshl_add_u64 v[14:15], v[14:15], 0, s[12:13]
	v_or_b32_e32 v28, 0xc00, v2
	v_addc_co_u32_e32 v19, vcc, 0, v17, vcc
	v_lshl_add_u64 v[22:23], v[14:15], 0, v[12:13]
	v_lshlrev_b32_e32 v2, 1, v28
	global_load_dwordx2 v[16:17], v[16:17], off offset:1024
	s_nop 0
	global_load_dwordx2 v[20:21], v[18:19], off offset:1024
	global_load_dwordx2 v[14:15], v[22:23], off
	s_nop 0
	global_load_dwordx2 v[18:19], v[22:23], off offset:1024
	s_nop 0
	global_load_dwordx2 v[22:23], v[22:23], off offset:2048
	v_lshl_add_u64 v[26:27], v[26:27], 0, v[2:3]
	global_load_ushort v27, v[26:27], off
	v_and_b32_e32 v2, 63, v11
	v_or_b32_e32 v2, 0x200, v2
	v_cmp_eq_u32_e32 vcc, 0, v10
	v_lshlrev_b32_e32 v30, 2, v0
	v_lshlrev_b32_e32 v32, 2, v11
	v_and_b32_e32 v11, -16, v11
	s_add_u32 s24, s88, s12
	v_cndmask_b32_e32 v2, v2, v25, vcc
	v_cndmask_b32_e64 v26, 0, 16, vcc
	v_lshl_or_b32 v31, v24, 8, v30
	v_or_b32_e32 v24, v11, v10
	s_addc_u32 s25, s89, 0
	s_mov_b32 s3, 1
	s_mov_b32 s8, 0
	v_lshlrev_b32_e32 v33, 2, v25
	v_mul_u32_u24_e32 v34, 60, v26
	v_lshlrev_b32_e32 v35, 2, v24
	v_lshlrev_b32_e32 v36, 2, v2
	v_lshlrev_b32_e32 v37, 3, v26
	v_mul_u32_u24_e32 v38, 12, v26
	v_lshlrev_b32_e32 v39, 4, v26
	v_mul_u32_u24_e32 v40, 20, v26
	v_mul_u32_u24_e32 v41, 24, v26
	v_mul_u32_u24_e32 v44, 28, v26
	v_lshlrev_b32_e32 v45, 5, v26
	v_mul_u32_u24_e32 v46, 36, v26
	v_mul_u32_u24_e32 v47, 40, v26
	v_mul_u32_u24_e32 v48, 44, v26
	v_mul_u32_u24_e32 v49, 48, v26
	v_mul_u32_u24_e32 v50, 52, v26
	v_mul_u32_u24_e32 v51, 56, v26
	v_lshl_add_u64 v[24:25], s[24:25], 0, v[12:13]
	v_mul_i32_i24_e32 v52, 0xffffffc8, v26
	s_lshl_b32 s9, s6, 8
	v_lshlrev_b32_e32 v26, 1, v28
	v_mov_b32_e32 v28, v1
	s_movk_i32 s76, 0x6400
	s_barrier
	s_branch .LBB0_391
.LBB0_390:
	v_add_u32_e32 v2, 0x5000, v33
	ds_read2_b32 v[94:95], v2 offset1:16
	ds_read_b128 v[54:57], v30 offset:12288
	ds_read_b128 v[58:61], v30 offset:12544
	ds_read_b128 v[62:65], v30 offset:4096
	ds_read_b128 v[66:69], v30 offset:4352
	ds_read_b128 v[70:73], v30 offset:16384
	ds_read_b128 v[74:77], v30 offset:16640
	ds_read_b128 v[78:81], v30 offset:8192
	ds_read_b128 v[82:85], v30 offset:8448
	ds_read_b128 v[86:89], v30
	ds_read_b128 v[90:93], v30 offset:256
	v_lshl_add_u32 v13, s24, 2, v36
	v_add_u32_e32 v2, v13, v34
	s_waitcnt lgkmcnt(9)
	v_mul_f32_e32 v29, v7, v57
	v_fmac_f32_e32 v29, v6, v56
	v_fmac_f32_e32 v29, v5, v55
	v_fmac_f32_e32 v29, v4, v54
	s_waitcnt lgkmcnt(3)
	v_mul_f32_e32 v53, v78, v94
	v_mul_f32_e32 v96, v79, v94
	v_add_f32_dpp v29, v29, v29 quad_perm:[1,0,3,2] row_mask:0xf bank_mask:0xf bound_ctrl:1
	v_mul_f32_e32 v97, v80, v94
	v_mul_f32_e32 v94, v81, v94
	v_add_f32_dpp v29, v29, v29 quad_perm:[2,3,0,1] row_mask:0xf bank_mask:0xf bound_ctrl:1
	s_nop 1
	v_add_f32_dpp v29, v29, v29 row_half_mirror row_mask:0xf bank_mask:0xf bound_ctrl:1
	s_nop 1
	v_add_f32_dpp v29, v29, v29 row_mirror row_mask:0xf bank_mask:0xf bound_ctrl:1
	v_fmac_f32_e32 v94, v29, v73
	v_fmac_f32_e32 v97, v29, v72
	v_fmac_f32_e32 v94, v7, v65
	v_fmac_f32_e32 v53, v29, v70
	v_fmac_f32_e32 v96, v29, v71
	v_fmac_f32_e32 v97, v6, v64
	v_fmac_f32_e32 v96, v5, v63
	s_waitcnt lgkmcnt(1)
	v_mul_f32_e32 v29, v89, v94
	v_fmac_f32_e32 v53, v4, v62
	v_fmac_f32_e32 v29, v97, v88
	s_nop 0
	v_fmac_f32_e32 v29, v96, v87
	v_fmac_f32_e32 v29, v53, v86
	ds_read_b128 v[4:7], v30 offset:12800
	ds_read_b128 v[54:57], v30 offset:8704
	ds_read_b128 v[62:65], v30 offset:4608
	ds_read_b128 v[70:73], v30 offset:512
	ds_read_b128 v[78:81], v30 offset:16896
	ds_read_b32 v98, v33 offset:20608
	v_mul_f32_e32 v61, v61, v94
	v_fmac_f32_e32 v61, v97, v60
	v_fmac_f32_e32 v61, v96, v59
	v_fmac_f32_e32 v61, v53, v58
	v_add_f32_dpp v29, v29, v29 quad_perm:[1,0,3,2] row_mask:0xf bank_mask:0xf bound_ctrl:1
	v_mul_f32_e32 v99, v82, v95
	v_add_f32_dpp v58, v61, v61 quad_perm:[1,0,3,2] row_mask:0xf bank_mask:0xf bound_ctrl:1
	v_add_f32_dpp v29, v29, v29 quad_perm:[2,3,0,1] row_mask:0xf bank_mask:0xf bound_ctrl:1
	s_nop 0
	v_add_f32_dpp v58, v58, v58 quad_perm:[2,3,0,1] row_mask:0xf bank_mask:0xf bound_ctrl:1
	v_add_f32_dpp v29, v29, v29 row_half_mirror row_mask:0xf bank_mask:0xf bound_ctrl:1
	s_nop 0
	v_add_f32_dpp v58, v58, v58 row_half_mirror row_mask:0xf bank_mask:0xf bound_ctrl:1
	v_add_f32_dpp v29, v29, v29 row_mirror row_mask:0xf bank_mask:0xf bound_ctrl:1
	ds_write_b32 v13, v29 offset:21504
	s_nop 0
	v_add_f32_dpp v29, v58, v58 row_mirror row_mask:0xf bank_mask:0xf bound_ctrl:1
	v_fmac_f32_e32 v99, v29, v74
	v_fmac_f32_e32 v99, v53, v66
	v_mul_f32_e32 v53, v83, v95
	v_fmac_f32_e32 v53, v29, v75
	v_fmac_f32_e32 v53, v96, v67
	v_mul_f32_e32 v96, v84, v95
	v_mul_f32_e32 v95, v85, v95
	v_fmac_f32_e32 v95, v29, v77
	v_fmac_f32_e32 v96, v29, v76
	v_fmac_f32_e32 v95, v94, v69
	v_fmac_f32_e32 v96, v97, v68
	s_waitcnt lgkmcnt(7)
	v_mul_f32_e32 v29, v93, v95
	v_fmac_f32_e32 v29, v96, v92
	v_fmac_f32_e32 v29, v53, v91
	v_fmac_f32_e32 v29, v99, v90
	ds_read_b128 v[58:61], v30 offset:13056
	ds_read_b128 v[66:69], v30 offset:8960
	ds_read_b128 v[74:77], v30 offset:4864
	ds_read_b128 v[82:85], v30 offset:768
	ds_read_b128 v[86:89], v30 offset:17152
	ds_read_b32 v90, v33 offset:20672
	s_waitcnt lgkmcnt(12)
	v_mul_f32_e32 v7, v7, v95
	v_fmac_f32_e32 v7, v96, v6
	v_fmac_f32_e32 v7, v53, v5
	v_fmac_f32_e32 v7, v99, v4
	s_waitcnt lgkmcnt(7)
	v_mul_f32_e32 v91, v55, v98
	v_mul_f32_e32 v92, v57, v98
	v_add_f32_dpp v4, v7, v7 quad_perm:[1,0,3,2] row_mask:0xf bank_mask:0xf bound_ctrl:1
	v_add_f32_dpp v5, v29, v29 quad_perm:[1,0,3,2] row_mask:0xf bank_mask:0xf bound_ctrl:1
	v_mul_f32_e32 v29, v54, v98
	v_add_f32_dpp v4, v4, v4 quad_perm:[2,3,0,1] row_mask:0xf bank_mask:0xf bound_ctrl:1
	v_add_f32_dpp v5, v5, v5 quad_perm:[2,3,0,1] row_mask:0xf bank_mask:0xf bound_ctrl:1
	v_add_u32_e32 v6, v2, v52
	v_add_f32_dpp v4, v4, v4 row_half_mirror row_mask:0xf bank_mask:0xf bound_ctrl:1
	v_add_f32_dpp v5, v5, v5 row_half_mirror row_mask:0xf bank_mask:0xf bound_ctrl:1
	s_nop 0
	v_add_f32_dpp v4, v4, v4 row_mirror row_mask:0xf bank_mask:0xf bound_ctrl:1
	v_fmac_f32_e32 v91, v4, v79
	v_fmac_f32_e32 v91, v53, v63
	v_mul_f32_e32 v53, v56, v98
	v_fmac_f32_e32 v92, v4, v81
	v_fmac_f32_e32 v53, v4, v80
	v_fmac_f32_e32 v92, v95, v65
	v_fmac_f32_e32 v53, v96, v64
	v_fmac_f32_e32 v29, v4, v78
	v_mul_f32_e32 v93, v73, v92
	v_add_f32_dpp v5, v5, v5 row_mirror row_mask:0xf bank_mask:0xf bound_ctrl:1
	v_fmac_f32_e32 v93, v53, v72
	v_fmac_f32_e32 v29, v99, v62
	ds_write_b32 v6, v5 offset:21504
	v_fmac_f32_e32 v93, v91, v71
	s_nop 0
	v_fmac_f32_e32 v93, v29, v70
	ds_read_b128 v[4:7], v30 offset:13312
	ds_read_b128 v[54:57], v30 offset:9216
	ds_read_b128 v[62:65], v30 offset:5120
	ds_read_b128 v[70:73], v30 offset:1024
	ds_read_b128 v[78:81], v30 offset:17408
	ds_read_b32 v94, v33 offset:20736
	s_waitcnt lgkmcnt(12)
	v_mul_f32_e32 v61, v61, v92
	v_fmac_f32_e32 v61, v53, v60
	v_fmac_f32_e32 v61, v91, v59
	v_fmac_f32_e32 v61, v29, v58
	v_add_f32_dpp v59, v93, v93 quad_perm:[1,0,3,2] row_mask:0xf bank_mask:0xf bound_ctrl:1
	s_waitcnt lgkmcnt(7)
	v_mul_f32_e32 v93, v66, v90
	v_add_f32_dpp v58, v61, v61 quad_perm:[1,0,3,2] row_mask:0xf bank_mask:0xf bound_ctrl:1
	v_add_f32_dpp v59, v59, v59 quad_perm:[2,3,0,1] row_mask:0xf bank_mask:0xf bound_ctrl:1
	v_add_u32_e32 v60, v13, v37
	v_add_f32_dpp v58, v58, v58 quad_perm:[2,3,0,1] row_mask:0xf bank_mask:0xf bound_ctrl:1
	v_add_f32_dpp v59, v59, v59 row_half_mirror row_mask:0xf bank_mask:0xf bound_ctrl:1
	s_nop 0
	v_add_f32_dpp v58, v58, v58 row_half_mirror row_mask:0xf bank_mask:0xf bound_ctrl:1
	v_add_f32_dpp v59, v59, v59 row_mirror row_mask:0xf bank_mask:0xf bound_ctrl:1
	ds_write_b32 v60, v59 offset:21504
	v_add_f32_dpp v58, v58, v58 row_mirror row_mask:0xf bank_mask:0xf bound_ctrl:1
	v_fmac_f32_e32 v93, v58, v86
	v_fmac_f32_e32 v93, v29, v74
	v_mul_f32_e32 v29, v67, v90
	v_fmac_f32_e32 v29, v58, v87
	v_fmac_f32_e32 v29, v91, v75
	v_mul_f32_e32 v91, v68, v90
	v_fmac_f32_e32 v91, v58, v88
	v_fmac_f32_e32 v91, v53, v76
	v_mul_f32_e32 v53, v69, v90
	v_fmac_f32_e32 v53, v58, v89
	v_fmac_f32_e32 v53, v92, v77
	s_nop 0
	v_mul_f32_e32 v90, v85, v53
	v_fmac_f32_e32 v90, v91, v84
	v_fmac_f32_e32 v90, v29, v83
	v_fmac_f32_e32 v90, v93, v82
	ds_read_b128 v[58:61], v30 offset:13568
	ds_read_b128 v[66:69], v30 offset:9472
	ds_read_b128 v[74:77], v30 offset:5376
	ds_read_b128 v[82:85], v30 offset:1280
	ds_read_b128 v[86:89], v30 offset:17664
	ds_read_b32 v92, v33 offset:20800
	s_waitcnt lgkmcnt(12)
	v_mul_f32_e32 v7, v7, v53
	v_fmac_f32_e32 v7, v91, v6
	v_fmac_f32_e32 v7, v29, v5
	v_fmac_f32_e32 v7, v93, v4
	v_add_f32_dpp v5, v90, v90 quad_perm:[1,0,3,2] row_mask:0xf bank_mask:0xf bound_ctrl:1
	s_waitcnt lgkmcnt(7)
	v_mul_f32_e32 v90, v54, v94
	v_add_f32_dpp v4, v7, v7 quad_perm:[1,0,3,2] row_mask:0xf bank_mask:0xf bound_ctrl:1
	v_add_f32_dpp v5, v5, v5 quad_perm:[2,3,0,1] row_mask:0xf bank_mask:0xf bound_ctrl:1
	v_add_u32_e32 v6, v13, v38
	v_add_f32_dpp v4, v4, v4 quad_perm:[2,3,0,1] row_mask:0xf bank_mask:0xf bound_ctrl:1
	v_add_f32_dpp v5, v5, v5 row_half_mirror row_mask:0xf bank_mask:0xf bound_ctrl:1
	s_nop 0
	v_add_f32_dpp v4, v4, v4 row_half_mirror row_mask:0xf bank_mask:0xf bound_ctrl:1
	v_add_f32_dpp v5, v5, v5 row_mirror row_mask:0xf bank_mask:0xf bound_ctrl:1
	ds_write_b32 v6, v5 offset:21504
	v_add_f32_dpp v4, v4, v4 row_mirror row_mask:0xf bank_mask:0xf bound_ctrl:1
	v_fmac_f32_e32 v90, v4, v78
	v_fmac_f32_e32 v90, v93, v62
	v_mul_f32_e32 v93, v55, v94
	v_fmac_f32_e32 v93, v4, v79
	v_fmac_f32_e32 v93, v29, v63
	v_mul_f32_e32 v29, v56, v94
	v_fmac_f32_e32 v29, v4, v80
	v_fmac_f32_e32 v29, v91, v64
	v_mul_f32_e32 v91, v57, v94
	v_fmac_f32_e32 v91, v4, v81
	v_fmac_f32_e32 v91, v53, v65
	s_nop 0
	v_mul_f32_e32 v53, v73, v91
	v_fmac_f32_e32 v53, v29, v72
	v_fmac_f32_e32 v53, v93, v71
	v_fmac_f32_e32 v53, v90, v70
	ds_read_b128 v[4:7], v30 offset:13824
	ds_read_b128 v[54:57], v30 offset:9728
	ds_read_b128 v[62:65], v30 offset:5632
	ds_read_b128 v[70:73], v30 offset:1536
	ds_read_b128 v[78:81], v30 offset:17920
	ds_read_b32 v94, v33 offset:20864
	s_waitcnt lgkmcnt(12)
	v_mul_f32_e32 v61, v61, v91
	v_fmac_f32_e32 v61, v29, v60
	v_fmac_f32_e32 v61, v93, v59
	v_fmac_f32_e32 v61, v90, v58
	v_add_f32_dpp v53, v53, v53 quad_perm:[1,0,3,2] row_mask:0xf bank_mask:0xf bound_ctrl:1
	v_add_u32_e32 v59, v13, v39
	v_add_f32_dpp v58, v61, v61 quad_perm:[1,0,3,2] row_mask:0xf bank_mask:0xf bound_ctrl:1
	v_add_f32_dpp v53, v53, v53 quad_perm:[2,3,0,1] row_mask:0xf bank_mask:0xf bound_ctrl:1
	s_waitcnt lgkmcnt(7)
	v_mul_f32_e32 v95, v66, v92
	v_add_f32_dpp v58, v58, v58 quad_perm:[2,3,0,1] row_mask:0xf bank_mask:0xf bound_ctrl:1
	v_add_f32_dpp v53, v53, v53 row_half_mirror row_mask:0xf bank_mask:0xf bound_ctrl:1
	s_nop 0
	v_add_f32_dpp v58, v58, v58 row_half_mirror row_mask:0xf bank_mask:0xf bound_ctrl:1
	v_add_f32_dpp v53, v53, v53 row_mirror row_mask:0xf bank_mask:0xf bound_ctrl:1
	ds_write_b32 v59, v53 offset:21504
	s_nop 0
	v_add_f32_dpp v53, v58, v58 row_mirror row_mask:0xf bank_mask:0xf bound_ctrl:1
	v_fmac_f32_e32 v95, v53, v86
	v_fmac_f32_e32 v95, v90, v74
	v_mul_f32_e32 v90, v67, v92
	v_fmac_f32_e32 v90, v53, v87
	v_fmac_f32_e32 v90, v93, v75
	v_mul_f32_e32 v93, v68, v92
	v_fmac_f32_e32 v93, v53, v88
	v_fmac_f32_e32 v93, v29, v76
	v_mul_f32_e32 v29, v69, v92
	v_fmac_f32_e32 v29, v53, v89
	v_fmac_f32_e32 v29, v91, v77
	s_nop 0
	v_mul_f32_e32 v53, v85, v29
	v_fmac_f32_e32 v53, v93, v84
	v_fmac_f32_e32 v53, v90, v83
	v_fmac_f32_e32 v53, v95, v82
	ds_read_b128 v[58:61], v30 offset:14080
	ds_read_b128 v[66:69], v30 offset:9984
	ds_read_b128 v[74:77], v30 offset:5888
	ds_read_b128 v[82:85], v30 offset:1792
	ds_read_b128 v[86:89], v30 offset:18176
	ds_read_b32 v91, v33 offset:20928
	s_waitcnt lgkmcnt(12)
	v_mul_f32_e32 v7, v7, v29
	v_fmac_f32_e32 v7, v93, v6
	v_fmac_f32_e32 v7, v90, v5
	v_fmac_f32_e32 v7, v95, v4
	s_waitcnt lgkmcnt(7)
	v_mul_f32_e32 v92, v55, v94
	v_add_f32_dpp v5, v53, v53 quad_perm:[1,0,3,2] row_mask:0xf bank_mask:0xf bound_ctrl:1
	v_add_f32_dpp v4, v7, v7 quad_perm:[1,0,3,2] row_mask:0xf bank_mask:0xf bound_ctrl:1
	v_mul_f32_e32 v53, v54, v94
	v_add_f32_dpp v5, v5, v5 quad_perm:[2,3,0,1] row_mask:0xf bank_mask:0xf bound_ctrl:1
	v_add_f32_dpp v4, v4, v4 quad_perm:[2,3,0,1] row_mask:0xf bank_mask:0xf bound_ctrl:1
	v_add_u32_e32 v6, v13, v40
	v_add_f32_dpp v5, v5, v5 row_half_mirror row_mask:0xf bank_mask:0xf bound_ctrl:1
	v_add_f32_dpp v4, v4, v4 row_half_mirror row_mask:0xf bank_mask:0xf bound_ctrl:1
	s_nop 0
	v_add_f32_dpp v5, v5, v5 row_mirror row_mask:0xf bank_mask:0xf bound_ctrl:1
	v_add_f32_dpp v4, v4, v4 row_mirror row_mask:0xf bank_mask:0xf bound_ctrl:1
	v_fmac_f32_e32 v92, v4, v79
	v_fmac_f32_e32 v92, v90, v63
	v_mul_f32_e32 v90, v56, v94
	v_fmac_f32_e32 v90, v4, v80
	v_fmac_f32_e32 v90, v93, v64
	v_mul_f32_e32 v93, v57, v94
	v_fmac_f32_e32 v93, v4, v81
	v_fmac_f32_e32 v93, v29, v65
	v_fmac_f32_e32 v53, v4, v78
	v_mul_f32_e32 v29, v73, v93
	v_fmac_f32_e32 v53, v95, v62
	v_fmac_f32_e32 v29, v90, v72
	ds_write_b32 v6, v5 offset:21504
	v_fmac_f32_e32 v29, v92, v71
	s_nop 0
	v_fmac_f32_e32 v29, v53, v70
	ds_read_b128 v[4:7], v30 offset:14336
	ds_read_b128 v[54:57], v30 offset:10240
	ds_read_b128 v[62:65], v30 offset:6144
	ds_read_b128 v[70:73], v30 offset:2048
	ds_read_b128 v[78:81], v30 offset:18432
	ds_read_b32 v94, v33 offset:20992
	s_waitcnt lgkmcnt(12)
	v_mul_f32_e32 v61, v61, v93
	v_fmac_f32_e32 v61, v90, v60
	v_fmac_f32_e32 v61, v92, v59
	v_fmac_f32_e32 v61, v53, v58
	v_add_f32_dpp v29, v29, v29 quad_perm:[1,0,3,2] row_mask:0xf bank_mask:0xf bound_ctrl:1
	v_add_u32_e32 v59, v13, v41
	v_add_f32_dpp v58, v61, v61 quad_perm:[1,0,3,2] row_mask:0xf bank_mask:0xf bound_ctrl:1
	v_add_f32_dpp v29, v29, v29 quad_perm:[2,3,0,1] row_mask:0xf bank_mask:0xf bound_ctrl:1
	s_waitcnt lgkmcnt(7)
	v_mul_f32_e32 v95, v66, v91
	v_add_f32_dpp v58, v58, v58 quad_perm:[2,3,0,1] row_mask:0xf bank_mask:0xf bound_ctrl:1
	v_add_f32_dpp v29, v29, v29 row_half_mirror row_mask:0xf bank_mask:0xf bound_ctrl:1
	s_nop 0
	v_add_f32_dpp v58, v58, v58 row_half_mirror row_mask:0xf bank_mask:0xf bound_ctrl:1
	v_add_f32_dpp v29, v29, v29 row_mirror row_mask:0xf bank_mask:0xf bound_ctrl:1
	ds_write_b32 v59, v29 offset:21504
	s_nop 0
	v_add_f32_dpp v29, v58, v58 row_mirror row_mask:0xf bank_mask:0xf bound_ctrl:1
	v_fmac_f32_e32 v95, v29, v86
	v_fmac_f32_e32 v95, v53, v74
	v_mul_f32_e32 v53, v67, v91
	v_fmac_f32_e32 v53, v29, v87
	v_fmac_f32_e32 v53, v92, v75
	v_mul_f32_e32 v92, v68, v91
	v_fmac_f32_e32 v92, v29, v88
	v_fmac_f32_e32 v92, v90, v76
	v_mul_f32_e32 v90, v69, v91
	v_fmac_f32_e32 v90, v29, v89
	v_fmac_f32_e32 v90, v93, v77
	s_nop 0
	v_mul_f32_e32 v29, v85, v90
	v_fmac_f32_e32 v29, v92, v84
	v_fmac_f32_e32 v29, v53, v83
	v_fmac_f32_e32 v29, v95, v82
	ds_read_b128 v[58:61], v30 offset:14592
	ds_read_b128 v[66:69], v30 offset:10496
	ds_read_b128 v[74:77], v30 offset:6400
	ds_read_b128 v[82:85], v30 offset:2304
	ds_read_b128 v[86:89], v30 offset:18688
	ds_read_b32 v91, v33 offset:21056
	s_waitcnt lgkmcnt(12)
	v_mul_f32_e32 v7, v7, v90
	v_fmac_f32_e32 v7, v92, v6
	v_fmac_f32_e32 v7, v53, v5
	v_fmac_f32_e32 v7, v95, v4
	s_waitcnt lgkmcnt(7)
	v_mul_f32_e32 v93, v55, v94
	v_add_f32_dpp v5, v29, v29 quad_perm:[1,0,3,2] row_mask:0xf bank_mask:0xf bound_ctrl:1
	v_add_f32_dpp v4, v7, v7 quad_perm:[1,0,3,2] row_mask:0xf bank_mask:0xf bound_ctrl:1
	v_mul_f32_e32 v29, v54, v94
	v_add_f32_dpp v5, v5, v5 quad_perm:[2,3,0,1] row_mask:0xf bank_mask:0xf bound_ctrl:1
	v_add_f32_dpp v4, v4, v4 quad_perm:[2,3,0,1] row_mask:0xf bank_mask:0xf bound_ctrl:1
	v_add_u32_e32 v6, v13, v44
	v_add_f32_dpp v5, v5, v5 row_half_mirror row_mask:0xf bank_mask:0xf bound_ctrl:1
	v_add_f32_dpp v4, v4, v4 row_half_mirror row_mask:0xf bank_mask:0xf bound_ctrl:1
	s_nop 0
	v_add_f32_dpp v5, v5, v5 row_mirror row_mask:0xf bank_mask:0xf bound_ctrl:1
	v_add_f32_dpp v4, v4, v4 row_mirror row_mask:0xf bank_mask:0xf bound_ctrl:1
	v_fmac_f32_e32 v93, v4, v79
	v_fmac_f32_e32 v93, v53, v63
	v_mul_f32_e32 v53, v56, v94
	v_fmac_f32_e32 v53, v4, v80
	v_fmac_f32_e32 v53, v92, v64
	v_mul_f32_e32 v92, v57, v94
	v_fmac_f32_e32 v92, v4, v81
	v_fmac_f32_e32 v92, v90, v65
	v_fmac_f32_e32 v29, v4, v78
	v_mul_f32_e32 v90, v73, v92
	v_fmac_f32_e32 v29, v95, v62
	v_fmac_f32_e32 v90, v53, v72
	ds_write_b32 v6, v5 offset:21504
	v_fmac_f32_e32 v90, v93, v71
	s_nop 0
	v_fmac_f32_e32 v90, v29, v70
	ds_read_b128 v[4:7], v30 offset:14848
	ds_read_b128 v[54:57], v30 offset:10752
	ds_read_b128 v[62:65], v30 offset:6656
	ds_read_b128 v[70:73], v30 offset:2560
	ds_read_b128 v[78:81], v30 offset:18944
	ds_read_b32 v94, v33 offset:21120
	s_waitcnt lgkmcnt(12)
	v_mul_f32_e32 v61, v61, v92
	v_fmac_f32_e32 v61, v53, v60
	v_fmac_f32_e32 v61, v93, v59
	v_fmac_f32_e32 v61, v29, v58
	v_add_f32_dpp v59, v90, v90 quad_perm:[1,0,3,2] row_mask:0xf bank_mask:0xf bound_ctrl:1
	s_waitcnt lgkmcnt(7)
	v_mul_f32_e32 v90, v66, v91
	v_add_f32_dpp v58, v61, v61 quad_perm:[1,0,3,2] row_mask:0xf bank_mask:0xf bound_ctrl:1
	v_add_f32_dpp v59, v59, v59 quad_perm:[2,3,0,1] row_mask:0xf bank_mask:0xf bound_ctrl:1
	v_add_u32_e32 v60, v13, v45
	v_add_f32_dpp v58, v58, v58 quad_perm:[2,3,0,1] row_mask:0xf bank_mask:0xf bound_ctrl:1
	v_add_f32_dpp v59, v59, v59 row_half_mirror row_mask:0xf bank_mask:0xf bound_ctrl:1
	s_nop 0
	v_add_f32_dpp v58, v58, v58 row_half_mirror row_mask:0xf bank_mask:0xf bound_ctrl:1
	v_add_f32_dpp v59, v59, v59 row_mirror row_mask:0xf bank_mask:0xf bound_ctrl:1
	ds_write_b32 v60, v59 offset:21504
	v_add_f32_dpp v58, v58, v58 row_mirror row_mask:0xf bank_mask:0xf bound_ctrl:1
	v_fmac_f32_e32 v90, v58, v86
	v_fmac_f32_e32 v90, v29, v74
	v_mul_f32_e32 v29, v67, v91
	v_fmac_f32_e32 v29, v58, v87
	v_fmac_f32_e32 v29, v93, v75
	v_mul_f32_e32 v93, v68, v91
	v_fmac_f32_e32 v93, v58, v88
	v_fmac_f32_e32 v93, v53, v76
	v_mul_f32_e32 v53, v69, v91
	v_fmac_f32_e32 v53, v58, v89
	v_fmac_f32_e32 v53, v92, v77
	s_nop 0
	v_mul_f32_e32 v91, v85, v53
	v_fmac_f32_e32 v91, v93, v84
	v_fmac_f32_e32 v91, v29, v83
	v_fmac_f32_e32 v91, v90, v82
	ds_read_b128 v[58:61], v30 offset:15104
	ds_read_b128 v[66:69], v30 offset:11008
	ds_read_b128 v[74:77], v30 offset:6912
	ds_read_b128 v[82:85], v30 offset:2816
	ds_read_b128 v[86:89], v30 offset:19200
	ds_read_b32 v92, v33 offset:21184
	s_waitcnt lgkmcnt(12)
	v_mul_f32_e32 v7, v7, v53
	v_fmac_f32_e32 v7, v93, v6
	v_fmac_f32_e32 v7, v29, v5
	v_fmac_f32_e32 v7, v90, v4
	v_add_f32_dpp v5, v91, v91 quad_perm:[1,0,3,2] row_mask:0xf bank_mask:0xf bound_ctrl:1
	s_waitcnt lgkmcnt(7)
	v_mul_f32_e32 v91, v54, v94
	v_add_f32_dpp v4, v7, v7 quad_perm:[1,0,3,2] row_mask:0xf bank_mask:0xf bound_ctrl:1
	v_add_f32_dpp v5, v5, v5 quad_perm:[2,3,0,1] row_mask:0xf bank_mask:0xf bound_ctrl:1
	v_add_u32_e32 v6, v13, v46
	v_add_f32_dpp v4, v4, v4 quad_perm:[2,3,0,1] row_mask:0xf bank_mask:0xf bound_ctrl:1
	v_add_f32_dpp v5, v5, v5 row_half_mirror row_mask:0xf bank_mask:0xf bound_ctrl:1
	s_nop 0
	v_add_f32_dpp v4, v4, v4 row_half_mirror row_mask:0xf bank_mask:0xf bound_ctrl:1
	v_add_f32_dpp v5, v5, v5 row_mirror row_mask:0xf bank_mask:0xf bound_ctrl:1
	ds_write_b32 v6, v5 offset:21504
	v_add_f32_dpp v4, v4, v4 row_mirror row_mask:0xf bank_mask:0xf bound_ctrl:1
	v_fmac_f32_e32 v91, v4, v78
	v_fmac_f32_e32 v91, v90, v62
	v_mul_f32_e32 v90, v55, v94
	v_fmac_f32_e32 v90, v4, v79
	v_fmac_f32_e32 v90, v29, v63
	v_mul_f32_e32 v29, v56, v94
	v_fmac_f32_e32 v29, v4, v80
	v_fmac_f32_e32 v29, v93, v64
	v_mul_f32_e32 v93, v57, v94
	v_fmac_f32_e32 v93, v4, v81
	v_fmac_f32_e32 v93, v53, v65
	s_nop 0
	v_mul_f32_e32 v53, v73, v93
	v_fmac_f32_e32 v53, v29, v72
	v_fmac_f32_e32 v53, v90, v71
	v_fmac_f32_e32 v53, v91, v70
	ds_read_b128 v[4:7], v30 offset:15360
	ds_read_b128 v[54:57], v30 offset:11264
	ds_read_b128 v[62:65], v30 offset:7168
	ds_read_b128 v[70:73], v30 offset:3072
	ds_read_b128 v[78:81], v30 offset:19456
	ds_read_b32 v94, v33 offset:21248
	s_waitcnt lgkmcnt(12)
	v_mul_f32_e32 v61, v61, v93
	v_fmac_f32_e32 v61, v29, v60
	v_fmac_f32_e32 v61, v90, v59
	v_fmac_f32_e32 v61, v91, v58
	v_add_f32_dpp v53, v53, v53 quad_perm:[1,0,3,2] row_mask:0xf bank_mask:0xf bound_ctrl:1
	v_add_u32_e32 v59, v13, v47
	v_add_f32_dpp v58, v61, v61 quad_perm:[1,0,3,2] row_mask:0xf bank_mask:0xf bound_ctrl:1
	v_add_f32_dpp v53, v53, v53 quad_perm:[2,3,0,1] row_mask:0xf bank_mask:0xf bound_ctrl:1
	s_waitcnt lgkmcnt(7)
	v_mul_f32_e32 v95, v66, v92
	v_add_f32_dpp v58, v58, v58 quad_perm:[2,3,0,1] row_mask:0xf bank_mask:0xf bound_ctrl:1
	v_add_f32_dpp v53, v53, v53 row_half_mirror row_mask:0xf bank_mask:0xf bound_ctrl:1
	s_nop 0
	v_add_f32_dpp v58, v58, v58 row_half_mirror row_mask:0xf bank_mask:0xf bound_ctrl:1
	v_add_f32_dpp v53, v53, v53 row_mirror row_mask:0xf bank_mask:0xf bound_ctrl:1
	ds_write_b32 v59, v53 offset:21504
	s_nop 0
	v_add_f32_dpp v53, v58, v58 row_mirror row_mask:0xf bank_mask:0xf bound_ctrl:1
	v_fmac_f32_e32 v95, v53, v86
	v_fmac_f32_e32 v95, v91, v74
	v_mul_f32_e32 v91, v67, v92
	v_fmac_f32_e32 v91, v53, v87
	v_fmac_f32_e32 v91, v90, v75
	v_mul_f32_e32 v90, v68, v92
	v_fmac_f32_e32 v90, v53, v88
	v_fmac_f32_e32 v90, v29, v76
	v_mul_f32_e32 v29, v69, v92
	v_fmac_f32_e32 v29, v53, v89
	v_fmac_f32_e32 v29, v93, v77
	s_nop 0
	v_mul_f32_e32 v53, v85, v29
	v_fmac_f32_e32 v53, v90, v84
	v_fmac_f32_e32 v53, v91, v83
	v_fmac_f32_e32 v53, v95, v82
	ds_read_b128 v[58:61], v30 offset:15616
	ds_read_b128 v[66:69], v30 offset:11520
	ds_read_b128 v[74:77], v30 offset:7424
	ds_read_b128 v[82:85], v30 offset:3328
	ds_read_b128 v[86:89], v30 offset:19712
	ds_read_b32 v92, v33 offset:21312
	s_waitcnt lgkmcnt(12)
	v_mul_f32_e32 v7, v7, v29
	v_fmac_f32_e32 v7, v90, v6
	v_fmac_f32_e32 v7, v91, v5
	v_fmac_f32_e32 v7, v95, v4
	s_waitcnt lgkmcnt(7)
	v_mul_f32_e32 v93, v55, v94
	v_add_f32_dpp v5, v53, v53 quad_perm:[1,0,3,2] row_mask:0xf bank_mask:0xf bound_ctrl:1
	v_add_f32_dpp v4, v7, v7 quad_perm:[1,0,3,2] row_mask:0xf bank_mask:0xf bound_ctrl:1
	v_mul_f32_e32 v53, v54, v94
	v_add_f32_dpp v5, v5, v5 quad_perm:[2,3,0,1] row_mask:0xf bank_mask:0xf bound_ctrl:1
	v_add_f32_dpp v4, v4, v4 quad_perm:[2,3,0,1] row_mask:0xf bank_mask:0xf bound_ctrl:1
	v_add_u32_e32 v6, v13, v48
	v_add_f32_dpp v5, v5, v5 row_half_mirror row_mask:0xf bank_mask:0xf bound_ctrl:1
	v_add_f32_dpp v4, v4, v4 row_half_mirror row_mask:0xf bank_mask:0xf bound_ctrl:1
	s_nop 0
	v_add_f32_dpp v5, v5, v5 row_mirror row_mask:0xf bank_mask:0xf bound_ctrl:1
	v_add_f32_dpp v4, v4, v4 row_mirror row_mask:0xf bank_mask:0xf bound_ctrl:1
	v_fmac_f32_e32 v93, v4, v79
	v_fmac_f32_e32 v93, v91, v63
	v_mul_f32_e32 v91, v56, v94
	v_fmac_f32_e32 v91, v4, v80
	v_fmac_f32_e32 v91, v90, v64
	v_mul_f32_e32 v90, v57, v94
	v_fmac_f32_e32 v90, v4, v81
	v_fmac_f32_e32 v90, v29, v65
	v_fmac_f32_e32 v53, v4, v78
	v_mul_f32_e32 v29, v73, v90
	v_fmac_f32_e32 v53, v95, v62
	v_fmac_f32_e32 v29, v91, v72
	ds_write_b32 v6, v5 offset:21504
	v_fmac_f32_e32 v29, v93, v71
	s_nop 0
	v_fmac_f32_e32 v29, v53, v70
	ds_read_b128 v[4:7], v30 offset:15872
	ds_read_b128 v[54:57], v30 offset:11776
	ds_read_b128 v[62:65], v30 offset:7680
	ds_read_b128 v[70:73], v30 offset:3584
	ds_read_b128 v[78:81], v30 offset:19968
	ds_read_b32 v94, v33 offset:21376
	s_waitcnt lgkmcnt(12)
	v_mul_f32_e32 v61, v61, v90
	v_fmac_f32_e32 v61, v91, v60
	v_fmac_f32_e32 v61, v93, v59
	v_fmac_f32_e32 v61, v53, v58
	v_add_f32_dpp v29, v29, v29 quad_perm:[1,0,3,2] row_mask:0xf bank_mask:0xf bound_ctrl:1
	v_add_u32_e32 v59, v13, v49
	v_add_f32_dpp v58, v61, v61 quad_perm:[1,0,3,2] row_mask:0xf bank_mask:0xf bound_ctrl:1
	v_add_f32_dpp v29, v29, v29 quad_perm:[2,3,0,1] row_mask:0xf bank_mask:0xf bound_ctrl:1
	s_waitcnt lgkmcnt(7)
	v_mul_f32_e32 v95, v66, v92
	v_add_f32_dpp v58, v58, v58 quad_perm:[2,3,0,1] row_mask:0xf bank_mask:0xf bound_ctrl:1
	v_add_f32_dpp v29, v29, v29 row_half_mirror row_mask:0xf bank_mask:0xf bound_ctrl:1
	s_nop 0
	v_add_f32_dpp v58, v58, v58 row_half_mirror row_mask:0xf bank_mask:0xf bound_ctrl:1
	v_add_f32_dpp v29, v29, v29 row_mirror row_mask:0xf bank_mask:0xf bound_ctrl:1
	ds_write_b32 v59, v29 offset:21504
	s_nop 0
	v_add_f32_dpp v29, v58, v58 row_mirror row_mask:0xf bank_mask:0xf bound_ctrl:1
	v_fmac_f32_e32 v95, v29, v86
	v_fmac_f32_e32 v95, v53, v74
	v_mul_f32_e32 v53, v67, v92
	v_fmac_f32_e32 v53, v29, v87
	v_fmac_f32_e32 v53, v93, v75
	v_mul_f32_e32 v93, v68, v92
	v_fmac_f32_e32 v93, v29, v88
	v_fmac_f32_e32 v93, v91, v76
	v_mul_f32_e32 v91, v69, v92
	v_fmac_f32_e32 v91, v29, v89
	v_fmac_f32_e32 v91, v90, v77
	s_nop 0
	v_mul_f32_e32 v29, v85, v91
	v_fmac_f32_e32 v29, v93, v84
	v_fmac_f32_e32 v29, v53, v83
	v_fmac_f32_e32 v29, v95, v82
	ds_read_b128 v[58:61], v30 offset:16128
	ds_read_b128 v[66:69], v30 offset:12032
	ds_read_b128 v[74:77], v30 offset:7936
	ds_read_b128 v[82:85], v30 offset:3840
	ds_read_b128 v[86:89], v30 offset:20224
	ds_read_b32 v90, v33 offset:21440
	s_waitcnt lgkmcnt(12)
	v_mul_f32_e32 v7, v7, v91
	v_fmac_f32_e32 v7, v93, v6
	v_fmac_f32_e32 v7, v53, v5
	v_fmac_f32_e32 v7, v95, v4
	v_add_f32_dpp v5, v29, v29 quad_perm:[1,0,3,2] row_mask:0xf bank_mask:0xf bound_ctrl:1
	s_waitcnt lgkmcnt(7)
	v_mul_f32_e32 v29, v57, v94
	v_add_f32_dpp v4, v7, v7 quad_perm:[1,0,3,2] row_mask:0xf bank_mask:0xf bound_ctrl:1
	v_add_f32_dpp v5, v5, v5 quad_perm:[2,3,0,1] row_mask:0xf bank_mask:0xf bound_ctrl:1
	v_add_u32_e32 v6, v13, v50
	v_add_f32_dpp v4, v4, v4 quad_perm:[2,3,0,1] row_mask:0xf bank_mask:0xf bound_ctrl:1
	v_add_f32_dpp v5, v5, v5 row_half_mirror row_mask:0xf bank_mask:0xf bound_ctrl:1
	v_mul_f32_e32 v7, v56, v94
	v_add_f32_dpp v4, v4, v4 row_half_mirror row_mask:0xf bank_mask:0xf bound_ctrl:1
	v_add_f32_dpp v5, v5, v5 row_mirror row_mask:0xf bank_mask:0xf bound_ctrl:1
	ds_write_b32 v6, v5 offset:21504
	v_add_f32_dpp v4, v4, v4 row_mirror row_mask:0xf bank_mask:0xf bound_ctrl:1
	v_fmac_f32_e32 v29, v4, v81
	v_mul_f32_e32 v5, v54, v94
	v_mul_f32_e32 v6, v55, v94
	v_fmac_f32_e32 v7, v4, v80
	v_fmac_f32_e32 v29, v91, v65
	v_fmac_f32_e32 v5, v4, v78
	v_fmac_f32_e32 v6, v4, v79
	v_fmac_f32_e32 v7, v93, v64
	v_fmac_f32_e32 v6, v53, v63
	v_mul_f32_e32 v4, v73, v29
	v_fmac_f32_e32 v5, v95, v62
	v_fmac_f32_e32 v4, v7, v72
	s_nop 0
	v_fmac_f32_e32 v4, v6, v71
	v_fmac_f32_e32 v4, v5, v70
	s_waitcnt lgkmcnt(6)
	v_mul_f32_e32 v53, v61, v29
	v_fmac_f32_e32 v53, v7, v60
	v_fmac_f32_e32 v53, v6, v59
	v_fmac_f32_e32 v53, v5, v58
	v_add_f32_dpp v4, v4, v4 quad_perm:[1,0,3,2] row_mask:0xf bank_mask:0xf bound_ctrl:1
	v_add_u32_e32 v13, v13, v51
	v_add_f32_dpp v53, v53, v53 quad_perm:[1,0,3,2] row_mask:0xf bank_mask:0xf bound_ctrl:1
	v_add_f32_dpp v4, v4, v4 quad_perm:[2,3,0,1] row_mask:0xf bank_mask:0xf bound_ctrl:1
	s_nop 0
	v_add_f32_dpp v53, v53, v53 quad_perm:[2,3,0,1] row_mask:0xf bank_mask:0xf bound_ctrl:1
	v_add_f32_dpp v4, v4, v4 row_half_mirror row_mask:0xf bank_mask:0xf bound_ctrl:1
	s_nop 0
	v_add_f32_dpp v53, v53, v53 row_half_mirror row_mask:0xf bank_mask:0xf bound_ctrl:1
	v_add_f32_dpp v4, v4, v4 row_mirror row_mask:0xf bank_mask:0xf bound_ctrl:1
	ds_write_b32 v13, v4 offset:21504
	v_add_f32_dpp v13, v53, v53 row_mirror row_mask:0xf bank_mask:0xf bound_ctrl:1
	s_waitcnt lgkmcnt(2)
	v_mul_f32_e32 v4, v66, v90
	v_fmac_f32_e32 v4, v13, v86
	v_fmac_f32_e32 v4, v5, v74
	v_mul_f32_e32 v5, v67, v90
	v_fmac_f32_e32 v5, v13, v87
	v_fmac_f32_e32 v5, v6, v75
	v_mul_f32_e32 v6, v68, v90
	v_fmac_f32_e32 v6, v13, v88
	v_fmac_f32_e32 v6, v7, v76
	v_mul_f32_e32 v7, v69, v90
	v_fmac_f32_e32 v7, v13, v89
	v_fmac_f32_e32 v7, v29, v77
	s_nop 0
	v_mul_f32_e32 v13, v85, v7
	v_fmac_f32_e32 v13, v6, v84
	v_fmac_f32_e32 v13, v5, v83
	v_fmac_f32_e32 v13, v4, v82
	s_nop 1
	v_add_f32_dpp v13, v13, v13 quad_perm:[1,0,3,2] row_mask:0xf bank_mask:0xf bound_ctrl:1
	s_nop 1
	v_add_f32_dpp v13, v13, v13 quad_perm:[2,3,0,1] row_mask:0xf bank_mask:0xf bound_ctrl:1
	s_nop 1
	v_add_f32_dpp v13, v13, v13 row_half_mirror row_mask:0xf bank_mask:0xf bound_ctrl:1
	s_nop 1
	v_add_f32_dpp v13, v13, v13 row_mirror row_mask:0xf bank_mask:0xf bound_ctrl:1
	ds_write_b32 v2, v13 offset:21504
	s_addk_i32 s8, 0x100
	s_add_i32 s3, s3, 1
	s_cmp_lg_u32 s9, s8
	v_add_u32_e32 v28, 16, v28
	s_waitcnt lgkmcnt(0)
	s_cbranch_scc0 .Lrw0_exitb
.LBB0_391:
	v_add_u32_e32 v31, s76, v31
	v_add_u32_e32 v32, s76, v32
	s_waitcnt vmcnt(2)
	v_and_b32_e32 v55, 0xffff0000, v16
	v_lshlrev_b32_e32 v54, 16, v16
	v_and_b32_e32 v57, 0xffff0000, v17
	v_lshlrev_b32_e32 v56, 16, v17
	s_waitcnt vmcnt(3)
	v_lshlrev_b32_e32 v2, 16, v14
	ds_write_b128 v31, v[54:57]
	s_waitcnt vmcnt(1)
	v_and_b32_e32 v55, 0xffff0000, v20
	v_lshlrev_b32_e32 v54, 16, v20
	v_and_b32_e32 v57, 0xffff0000, v21
	v_lshlrev_b32_e32 v56, 16, v21
	v_mul_f32_e32 v2, 0x3fb8aa3b, v2
	ds_write_b128 v31, v[54:57] offset:8192
	v_exp_f32_e32 v54, v2
	v_and_b32_e32 v2, 0xffff0000, v14
	v_mul_f32_e32 v2, 0x3fb8aa3b, v2
	v_exp_f32_e32 v55, v2
	v_lshlrev_b32_e32 v2, 16, v15
	v_mul_f32_e32 v2, 0x3fb8aa3b, v2
	v_exp_f32_e32 v56, v2
	v_and_b32_e32 v2, 0xffff0000, v15
	v_mul_f32_e32 v2, 0x3fb8aa3b, v2
	v_exp_f32_e32 v57, v2
	s_waitcnt vmcnt(2)
	v_and_b32_e32 v2, 0xffff0000, v18
	v_lshlrev_b32_e32 v13, 16, v18
	s_and_b32 s24, s8, 0x100
	ds_write_b128 v31, v[54:57] offset:4096
	v_xor_b32_e32 v55, 0x80000000, v2
	v_xor_b32_e32 v54, 0x80000000, v13
	v_and_b32_e32 v2, 0xffff0000, v19
	v_lshlrev_b32_e32 v13, 16, v19
	v_xor_b32_e32 v57, 0x80000000, v2
	v_xor_b32_e32 v56, 0x80000000, v13
	v_ashrrev_i32_e32 v29, 31, v28
	ds_write_b128 v31, v[54:57] offset:12288
	s_waitcnt vmcnt(1)
	v_and_b32_e32 v55, 0xffff0000, v22
	v_lshlrev_b32_e32 v54, 16, v22
	v_and_b32_e32 v57, 0xffff0000, v23
	v_lshlrev_b32_e32 v56, 16, v23
	s_waitcnt vmcnt(0)
	v_lshlrev_b32_e32 v2, 16, v27
	s_cmp_eq_u32 s8, 0
	ds_write_b128 v31, v[54:57] offset:16384
	ds_write_b32 v32, v2 offset:20480
	s_waitcnt lgkmcnt(0)
	s_barrier
	v_add_u32_e32 v30, s76, v30
	v_add_u32_e32 v33, s76, v33
	s_mul_i32 s76, s76, -1
	s_cbranch_scc1 .LBB0_393
	s_xor_b32 s12, s24, 0x100
	v_lshl_add_u32 v2, s12, 2, v35
	ds_read_b32 v2, v2 offset:21504
	v_lshlrev_b64 v[54:55], 10, v[28:29]
	s_lshl_b32 s12, s7, 1
	v_lshl_add_u64 v[54:55], s[86:87], 0, v[54:55]
	v_lshl_add_u64 v[54:55], v[54:55], 0, s[12:13]
	s_waitcnt lgkmcnt(0)
	v_cvt_pk_bf16_f32 v13, v2, s0
	v_lshlrev_b32_e32 v2, 1, v10
	v_lshl_add_u64 v[54:55], v[54:55], 0, v[2:3]
	s_lshl_b32 s12, s2, 1
	v_lshl_add_u64 v[54:55], v[54:55], 0, s[12:13]
	v_add_co_u32_e32 v54, vcc, 0xffffc000, v54
	s_nop 1
	v_addc_co_u32_e32 v55, vcc, -1, v55, vcc
	global_store_short v[54:55], v13, off

.LBB0_774:
	v_readlane_b32 s8, v159, 0
	v_readlane_b32 s9, v159, 1
	s_waitcnt vmcnt(0)
	s_waitcnt lgkmcnt(0)
	s_barrier
	s_mov_b64 s[2:3], exec
	v_readlane_b32 s0, v159, 2
	v_readlane_b32 s1, v159, 3
	s_and_b64 s[0:1], s[2:3], s[0:1]
	s_mov_b64 exec, s[0:1]
	s_cbranch_execz .LBB0_818
	s_mov_b64 s[0:1], src_shared_base
	v_mov_b32_e32 v0, 0xc800
	v_mov_b32_e32 v1, s1
	s_waitcnt vmcnt(0) expcnt(0) lgkmcnt(0)
	s_getreg_b32 s0, hwreg(HW_REG_XCC_ID, 0, 4)
	flat_load_dword v2, v[0:1] sc0 sc1
	s_waitcnt vmcnt(0)
	v_mov_b32_e32 v0, 0xc804
	flat_load_dword v0, v[0:1] sc0 sc1
	s_waitcnt vmcnt(0)
	s_and_b32 s33, s0, 15
	s_waitcnt lgkmcnt(0)
	v_cmp_eq_u32_e32 vcc, 0, v2
	s_and_saveexec_b64 s[36:37], vcc
	s_cbranch_execz .LBB0_789
	s_add_u32 s4, s8, 0x1000
	s_addc_u32 s5, s9, 0
	s_add_u32 s6, s8, 0x1100
	s_addc_u32 s7, s9, 0
	s_add_u32 s10, s8, 0x1200
	s_addc_u32 s11, s9, 0
	s_add_u32 s12, s8, 0x1300
	s_addc_u32 s13, s9, 0
	s_mov_b32 s22, 1
	s_mov_b64 s[0:1], 0
	v_mov_b64_e32 v[0:1], s[8:9]
	v_mov_b64_e32 v[2:3], s[4:5]
	v_mov_b64_e32 v[4:5], s[6:7]
	v_mov_b64_e32 v[6:7], s[10:11]
	v_mov_b64_e32 v[8:9], s[12:13]
	s_branch .LBB0_779

.LBB0_874:
	v_readlane_b32 s8, v159, 0
	v_readlane_b32 s9, v159, 1
	s_waitcnt vmcnt(0)
	s_barrier
	s_mov_b64 s[2:3], exec
	v_readlane_b32 s0, v159, 2
	v_readlane_b32 s1, v159, 3
	s_and_b64 s[0:1], s[2:3], s[0:1]
	s_mov_b64 exec, s[0:1]
	s_cbranch_execz .LBB0_918
	s_mov_b64 s[0:1], src_shared_base
	v_mov_b32_e32 v0, 0xc800
	v_mov_b32_e32 v1, s1
	s_waitcnt vmcnt(0) expcnt(0) lgkmcnt(0)
	s_getreg_b32 s0, hwreg(HW_REG_XCC_ID, 0, 4)
	flat_load_dword v2, v[0:1] sc0 sc1
	s_waitcnt vmcnt(0)
	v_mov_b32_e32 v0, 0xc804
	flat_load_dword v0, v[0:1] sc0 sc1
	s_waitcnt vmcnt(0)
	s_and_b32 s33, s0, 15
	s_waitcnt lgkmcnt(0)
	v_cmp_eq_u32_e32 vcc, 0, v2
	s_and_saveexec_b64 s[36:37], vcc
	s_cbranch_execz .LBB0_889
	s_add_u32 s4, s8, 0x1000
	s_addc_u32 s5, s9, 0
	s_add_u32 s6, s8, 0x1100
	s_addc_u32 s7, s9, 0
	s_add_u32 s10, s8, 0x1200
	s_addc_u32 s11, s9, 0
	s_add_u32 s12, s8, 0x1300
	s_addc_u32 s13, s9, 0
	s_mov_b32 s22, 1
	s_mov_b64 s[0:1], 0
	v_mov_b64_e32 v[0:1], s[8:9]
	v_mov_b64_e32 v[2:3], s[4:5]
	v_mov_b64_e32 v[4:5], s[6:7]
	v_mov_b64_e32 v[6:7], s[10:11]
	v_mov_b64_e32 v[8:9], s[12:13]
	s_branch .LBB0_879

.LBB0_986:
	s_or_b64 exec, exec, s[0:1]
	s_cmp_eq_u32 s33, 15
	s_cselect_b64 vcc, -1, 0
	s_cmp_eq_u32 s33, 14
	s_cselect_b64 s[0:1], -1, 0
	s_cmp_eq_u32 s33, 13
	s_cselect_b64 s[4:5], -1, 0
	s_cmp_eq_u32 s33, 12
	s_cselect_b64 s[6:7], -1, 0
	s_cmp_eq_u32 s33, 11
	s_cselect_b64 s[10:11], -1, 0
	s_cmp_eq_u32 s33, 10
	s_cselect_b64 s[12:13], -1, 0
	s_cmp_eq_u32 s33, 9
	s_cselect_b64 s[14:15], -1, 0
	s_cmp_eq_u32 s33, 8
	s_cselect_b64 s[16:17], -1, 0
	s_cmp_eq_u32 s33, 7
	s_cselect_b64 s[18:19], -1, 0
	s_cmp_eq_u32 s33, 6
	s_cselect_b64 s[20:21], -1, 0
	s_cmp_eq_u32 s33, 5
	s_cselect_b64 s[22:23], -1, 0
	s_cmp_eq_u32 s33, 4
	s_cselect_b64 s[24:25], -1, 0
	s_cmp_eq_u32 s33, 3
	s_cselect_b64 s[26:27], -1, 0
	s_cmp_eq_u32 s33, 2
	s_cselect_b64 s[28:29], -1, 0
	s_cmp_eq_u32 s33, 1
	s_cselect_b64 s[30:31], -1, 0
	s_cmp_eq_u32 s33, 0
	s_cselect_b64 s[34:35], -1, 0
	v_cndmask_b32_e64 v0, 0, v25, s[34:35]
	v_cndmask_b32_e64 v0, v0, v10, s[30:31]
	v_cndmask_b32_e64 v0, v0, v11, s[28:29]
	v_cndmask_b32_e64 v0, v0, v12, s[26:27]
	v_cndmask_b32_e64 v0, v0, v13, s[24:25]
	v_cndmask_b32_e64 v0, v0, v14, s[22:23]
	v_cndmask_b32_e64 v0, v0, v15, s[20:21]
	v_cndmask_b32_e64 v0, v0, v16, s[18:19]
	v_cndmask_b32_e64 v0, v0, v17, s[16:17]
	v_cndmask_b32_e64 v0, v0, v18, s[14:15]
	v_cndmask_b32_e64 v0, v0, v19, s[12:13]
	v_cndmask_b32_e64 v0, v0, v20, s[10:11]
	v_cndmask_b32_e64 v0, v0, v21, s[6:7]
	v_cndmask_b32_e64 v0, v0, v22, s[4:5]
	v_cndmask_b32_e64 v0, v0, v23, s[0:1]
	v_cndmask_b32_e32 v0, v0, v24, vcc
	v_cmp_ne_u32_e32 vcc, 0, v25
	s_mov_b64 s[38:39], src_shared_base
	v_mov_b32_e32 v4, 0xc800
	v_cndmask_b32_e64 v1, 0, 1, vcc
	v_cmp_ne_u32_e32 vcc, 0, v10
	v_mov_b32_e32 v5, s39
	s_nop 0
	v_addc_co_u32_e32 v1, vcc, 0, v1, vcc
	v_cmp_ne_u32_e32 vcc, 0, v11
	s_nop 1
	v_cndmask_b32_e64 v2, 0, 1, vcc
	v_cmp_ne_u32_e32 vcc, 0, v12
	s_nop 1
	v_addc_co_u32_e32 v1, vcc, v1, v2, vcc
	v_cmp_ne_u32_e32 vcc, 0, v13
	s_nop 1
	v_cndmask_b32_e64 v2, 0, 1, vcc
	v_cmp_ne_u32_e32 vcc, 0, v14
	s_nop 1
	v_addc_co_u32_e32 v1, vcc, v1, v2, vcc
	v_cmp_ne_u32_e32 vcc, 0, v15
	s_nop 1
	v_cndmask_b32_e64 v2, 0, 1, vcc
	v_cmp_ne_u32_e32 vcc, 0, v16
	s_nop 1
	v_addc_co_u32_e32 v1, vcc, v1, v2, vcc
	v_cmp_ne_u32_e32 vcc, 0, v17
	s_nop 1
	v_cndmask_b32_e64 v2, 0, 1, vcc
	v_cmp_ne_u32_e32 vcc, 0, v18
	s_nop 1
	v_addc_co_u32_e32 v1, vcc, v1, v2, vcc
	v_cmp_ne_u32_e32 vcc, 0, v19
	s_nop 1
	v_cndmask_b32_e64 v2, 0, 1, vcc
	v_cmp_ne_u32_e32 vcc, 0, v20
	s_nop 1
	v_addc_co_u32_e32 v1, vcc, v1, v2, vcc
	v_cmp_ne_u32_e32 vcc, 0, v21
	s_nop 1
	v_cndmask_b32_e64 v2, 0, 1, vcc
	v_cmp_ne_u32_e32 vcc, 0, v22
	s_nop 1
	v_addc_co_u32_e32 v1, vcc, v1, v2, vcc
	v_cmp_ne_u32_e32 vcc, 0, v23
	s_nop 1
	v_cndmask_b32_e64 v2, 0, 1, vcc
	v_cmp_ne_u32_e32 vcc, 0, v24
	s_nop 1
	v_addc_co_u32_e32 v1, vcc, v1, v2, vcc
	v_max_u32_e32 v2, 1, v0
	v_max_u32_e32 v0, 1, v1
	flat_store_dword v[4:5], v2 sc0 sc1
	s_waitcnt vmcnt(0)
	v_mov_b32_e32 v4, 0xc804
	flat_store_dword v[4:5], v0 sc0 sc1
	s_waitcnt vmcnt(0)

.LBB0_1048:
	v_add_u32_e32 v1, s4, v21
	v_mov_b64_e32 v[4:5], s[46:47]
	v_mad_i64_i32 v[32:33], s[0:1], v1, s50, v[4:5]
	s_lshl_b32 s14, s29, 1
	v_lshlrev_b32_e32 v2, 1, v38
	v_lshl_add_u64 v[4:5], v[32:33], 0, s[14:15]
	v_lshl_add_u64 v[4:5], v[4:5], 0, v[2:3]
	s_add_i32 s0, s29, s27
	v_add_co_u32_e32 v6, vcc, 0x1000, v4
	s_addk_i32 s0, 0x1300
	s_nop 0
	v_addc_co_u32_e32 v7, vcc, 0, v5, vcc
	v_or_b32_e32 v40, s0, v20
	v_add_co_u32_e32 v8, vcc, s39, v4
	v_lshlrev_b32_e32 v2, 1, v40
	s_nop 0
	v_addc_co_u32_e32 v9, vcc, 0, v5, vcc
	v_lshl_add_u64 v[32:33], v[32:33], 0, v[2:3]
	global_load_dwordx4 v[4:7], v[6:7], off offset:3584
	s_nop 0
	global_load_dwordx4 v[8:11], v[8:9], off offset:512
	v_lshlrev_b32_e32 v13, 4, v30
	global_load_ushort v39, v[32:33], off
	v_and_b32_e32 v2, 63, v30
	v_and_b32_e32 v13, 48, v13
	v_add_u32_e32 v13, v31, v13
	v_or_b32_e32 v2, 0x200, v2
	v_cmp_gt_u32_e32 vcc, 4, v20
	v_lshlrev_b32_e32 v43, 2, v31
	s_mov_b32 s30, 1
	v_cndmask_b32_e32 v2, v2, v13, vcc
	v_lshlrev_b32_e32 v13, 2, v38
	v_lshl_or_b32 v15, v21, 9, v13
	v_and_b32_e32 v13, 1, v30
	v_cmp_eq_u32_e64 s[0:1], 0, v13
	v_and_b32_e32 v13, 2, v30
	v_cmp_eq_u32_e64 s[4:5], 0, v13
	v_and_b32_e32 v13, -16, v30
	v_cndmask_b32_e64 v41, 0, 16, vcc
	v_lshlrev_b32_e32 v44, 2, v2
	v_or_b32_e32 v2, v13, v20
	s_mov_b32 s31, 0
	v_lshlrev_b32_e32 v17, 2, v30
	v_lshlrev_b32_e32 v21, 4, v20
	v_lshlrev_b32_e32 v45, 2, v2
	v_pk_add_f32 v[30:31], v[22:23], 1.0 op_sel_hi:[1,0] neg_lo:[1,0] neg_hi:[1,0]
	v_pk_add_f32 v[32:33], v[24:25], 1.0 op_sel_hi:[1,0] neg_lo:[1,0] neg_hi:[1,0]
	v_pk_add_f32 v[34:35], v[26:27], 1.0 op_sel_hi:[1,0] neg_lo:[1,0] neg_hi:[1,0]
	v_pk_add_f32 v[36:37], v[28:29], 1.0 op_sel_hi:[1,0] neg_lo:[1,0] neg_hi:[1,0]
	v_lshlrev_b32_e32 v46, 4, v41
	v_lshlrev_b32_e32 v47, 5, v41
	v_mul_u32_u24_e32 v48, 48, v41
	s_lshl_b32 s53, s28, 8
	v_lshlrev_b32_e32 v38, 1, v38
	v_lshlrev_b32_e32 v40, 1, v40
	v_lshlrev_b32_e32 v2, 1, v20
	v_add_u32_e32 v49, 0x6000, v43
	v_mov_b32_e32 v50, v1
	s_movk_i32 s77, 0x7400
	s_movk_i32 s78, 0x5400
	s_barrier
	s_branch .LBB0_1050
.LBB0_1049:
	ds_read_b128 v[60:63], v21 offset:8192
	ds_read_b128 v[64:67], v21 offset:8448
	ds_read_b128 v[68:71], v21
	ds_read_b128 v[72:75], v21 offset:256
	ds_read2_b32 v[92:93], v49 offset1:16
	ds_read_b128 v[76:79], v21 offset:8704
	ds_read_b128 v[80:83], v21 offset:8960
	ds_read_b128 v[84:87], v21 offset:512
	ds_read_b128 v[88:91], v21 offset:768
	v_lshl_add_u32 v41, s54, 2, v44
	s_waitcnt lgkmcnt(4)
	v_sub_f32_e32 v52, v52, v92
	v_fma_f32 v94, v52, v60, v92
	v_sub_f32_e32 v52, v54, v92
	v_fma_f32 v95, v52, v61, v92
	v_sub_f32_e32 v52, v56, v92
	v_fma_f32 v96, v52, v62, v92
	v_sub_f32_e32 v52, v58, v92
	v_fma_f32 v97, v52, v63, v92
	v_sub_f32_e32 v52, v57, v92
	v_fma_f32 v98, v52, v64, v92
	v_sub_f32_e32 v52, v55, v92
	v_sub_f32_e32 v51, v51, v92
	v_fma_f32 v99, v52, v65, v92
	v_sub_f32_e32 v52, v53, v92
	v_fma_f32 v51, v51, v67, v92
	v_fma_f32 v100, v52, v66, v92
	v_mul_f32_e32 v52, v71, v97
	v_mul_f32_e32 v53, v75, v51
	s_nop 0
	v_fmac_f32_e32 v52, v96, v70
	v_fmac_f32_e32 v53, v100, v74
	v_fmac_f32_e32 v52, v95, v69
	v_fmac_f32_e32 v53, v99, v73
	v_fmac_f32_e32 v52, v94, v68
	v_fmac_f32_e32 v53, v98, v72
	v_add_f32_e32 v92, v52, v53
	ds_read_b128 v[52:55], v21 offset:9216
	ds_read_b128 v[56:59], v21 offset:9472
	ds_read_b128 v[60:63], v21 offset:1024
	ds_read_b128 v[64:67], v21 offset:1280
	ds_read_b32 v101, v43 offset:24704
	v_sub_f32_e32 v68, v94, v93
	s_waitcnt lgkmcnt(8)
	v_fma_f32 v94, v68, v76, v93
	v_sub_f32_e32 v68, v95, v93
	v_fma_f32 v95, v68, v77, v93
	v_sub_f32_e32 v68, v96, v93
	v_fma_f32 v96, v68, v78, v93
	v_sub_f32_e32 v68, v97, v93
	v_fma_f32 v97, v68, v79, v93
	v_sub_f32_e32 v68, v98, v93
	s_waitcnt lgkmcnt(7)
	v_fma_f32 v98, v68, v80, v93
	v_sub_f32_e32 v68, v99, v93
	v_fma_f32 v99, v68, v81, v93
	v_sub_f32_e32 v68, v100, v93
	v_sub_f32_e32 v51, v51, v93
	v_fma_f32 v100, v68, v82, v93
	v_fmac_f32_e32 v93, v51, v83
	s_waitcnt lgkmcnt(6)
	v_mul_f32_e32 v51, v87, v97
	s_waitcnt lgkmcnt(5)
	v_mul_f32_e32 v68, v91, v93
	v_fmac_f32_e32 v51, v96, v86
	v_fmac_f32_e32 v68, v100, v90
	v_fmac_f32_e32 v51, v95, v85
	v_fmac_f32_e32 v68, v99, v89
	s_nop 0
	v_fmac_f32_e32 v51, v94, v84
	v_fmac_f32_e32 v68, v98, v88
	v_add_f32_e32 v51, v51, v68
	ds_read_b128 v[68:71], v21 offset:9728
	ds_read_b128 v[72:75], v21 offset:9984
	ds_read_b128 v[76:79], v21 offset:1536
	ds_read_b128 v[80:83], v21 offset:1792
	ds_read_b32 v84, v43 offset:24768
	s_waitcnt lgkmcnt(5)
	v_sub_f32_e32 v85, v94, v101
	v_fma_f32 v85, v85, v52, v101
	v_sub_f32_e32 v52, v95, v101
	v_fma_f32 v86, v52, v53, v101
	v_sub_f32_e32 v52, v96, v101
	v_fma_f32 v87, v52, v54, v101
	v_sub_f32_e32 v52, v97, v101
	v_fma_f32 v88, v52, v55, v101
	v_sub_f32_e32 v52, v98, v101
	v_fma_f32 v89, v52, v56, v101
	v_sub_f32_e32 v52, v99, v101
	v_fma_f32 v90, v52, v57, v101
	v_sub_f32_e32 v52, v100, v101
	v_fma_f32 v91, v52, v58, v101
	v_sub_f32_e32 v52, v93, v101
	v_fmac_f32_e32 v101, v52, v59
	s_nop 0
	v_mul_f32_e32 v52, v63, v88
	v_mul_f32_e32 v53, v67, v101
	v_fmac_f32_e32 v52, v87, v62
	v_fmac_f32_e32 v53, v91, v66
	v_fmac_f32_e32 v52, v86, v61
	v_fmac_f32_e32 v53, v90, v65
	s_nop 0
	v_fmac_f32_e32 v52, v85, v60
	v_fmac_f32_e32 v53, v89, v64
	v_add_f32_e32 v93, v52, v53
	ds_read_b128 v[52:55], v21 offset:10240
	ds_read_b128 v[56:59], v21 offset:10496
	ds_read_b128 v[60:63], v21 offset:2048
	ds_read_b128 v[64:67], v21 offset:2304
	ds_read_b32 v94, v43 offset:24832
	s_waitcnt lgkmcnt(5)
	v_sub_f32_e32 v85, v85, v84
	v_fma_f32 v85, v85, v68, v84
	v_sub_f32_e32 v68, v86, v84
	v_fma_f32 v86, v68, v69, v84
	v_sub_f32_e32 v68, v87, v84
	v_fma_f32 v87, v68, v70, v84
	v_sub_f32_e32 v68, v88, v84
	v_fma_f32 v88, v68, v71, v84
	v_sub_f32_e32 v68, v89, v84
	v_fma_f32 v89, v68, v72, v84
	v_sub_f32_e32 v68, v90, v84
	v_fma_f32 v90, v68, v73, v84
	v_sub_f32_e32 v68, v91, v84
	v_fma_f32 v91, v68, v74, v84
	v_sub_f32_e32 v68, v101, v84
	v_fmac_f32_e32 v84, v68, v75
	s_nop 0
	v_mul_f32_e32 v68, v79, v88
	v_mul_f32_e32 v69, v83, v84
	v_fmac_f32_e32 v68, v87, v78
	v_fmac_f32_e32 v69, v91, v82
	v_fmac_f32_e32 v68, v86, v77
	v_fmac_f32_e32 v69, v90, v81
	s_nop 0
	v_fmac_f32_e32 v68, v85, v76
	v_fmac_f32_e32 v69, v89, v80
	v_add_f32_e32 v68, v68, v69
	v_cndmask_b32_e64 v69, v51, v92, s[0:1]
	v_cndmask_b32_e64 v51, v92, v51, s[0:1]
	v_cndmask_b32_e64 v70, v68, v93, s[0:1]
	v_cndmask_b32_e64 v68, v93, v68, s[0:1]
	v_add_f32_dpp v51, v51, v69 quad_perm:[1,0,3,2] row_mask:0xf bank_mask:0xf bound_ctrl:1
	s_nop 0
	v_add_f32_dpp v68, v68, v70 quad_perm:[1,0,3,2] row_mask:0xf bank_mask:0xf bound_ctrl:1
	v_cndmask_b32_e64 v69, v68, v51, s[4:5]
	v_cndmask_b32_e64 v51, v51, v68, s[4:5]
	s_nop 1
	v_add_f32_dpp v51, v51, v69 quad_perm:[2,3,0,1] row_mask:0xf bank_mask:0xf bound_ctrl:1
	s_nop 1
	v_add_f32_dpp v51, v51, v51 row_ror:4 row_mask:0xf bank_mask:0xf bound_ctrl:1
	s_nop 1
	v_add_f32_dpp v51, v51, v51 row_ror:8 row_mask:0xf bank_mask:0xf bound_ctrl:1
	ds_write_b32 v41, v51 offset:25600
	ds_read_b128 v[68:71], v21 offset:10752
	ds_read_b128 v[72:75], v21 offset:11008
	ds_read_b128 v[76:79], v21 offset:2560
	ds_read_b128 v[80:83], v21 offset:2816
	ds_read_b32 v51, v43 offset:24896
	s_waitcnt lgkmcnt(6)
	v_sub_f32_e32 v85, v85, v94
	v_fma_f32 v85, v85, v52, v94
	v_sub_f32_e32 v52, v86, v94
	v_fma_f32 v86, v52, v53, v94
	v_sub_f32_e32 v52, v87, v94
	v_fma_f32 v87, v52, v54, v94
	v_sub_f32_e32 v52, v88, v94
	v_fma_f32 v88, v52, v55, v94
	v_sub_f32_e32 v52, v89, v94
	v_fma_f32 v89, v52, v56, v94
	v_sub_f32_e32 v52, v90, v94
	v_fma_f32 v90, v52, v57, v94
	v_sub_f32_e32 v52, v91, v94
	v_fma_f32 v91, v52, v58, v94
	v_sub_f32_e32 v52, v84, v94
	v_fmac_f32_e32 v94, v52, v59
	s_nop 0
	v_mul_f32_e32 v52, v63, v88
	v_mul_f32_e32 v53, v67, v94
	v_fmac_f32_e32 v52, v87, v62
	v_fmac_f32_e32 v53, v91, v66
	v_fmac_f32_e32 v52, v86, v61
	v_fmac_f32_e32 v53, v90, v65
	s_nop 0
	v_fmac_f32_e32 v52, v85, v60
	v_fmac_f32_e32 v53, v89, v64
	v_add_f32_e32 v84, v52, v53
	ds_read_b128 v[52:55], v21 offset:11264
	ds_read_b128 v[56:59], v21 offset:11520
	ds_read_b128 v[60:63], v21 offset:3072
	ds_read_b128 v[64:67], v21 offset:3328
	ds_read_b32 v92, v43 offset:24960
	s_waitcnt lgkmcnt(5)
	v_sub_f32_e32 v85, v85, v51
	v_fma_f32 v85, v85, v68, v51
	v_sub_f32_e32 v68, v86, v51
	v_fma_f32 v86, v68, v69, v51
	v_sub_f32_e32 v68, v87, v51
	v_fma_f32 v87, v68, v70, v51
	v_sub_f32_e32 v68, v88, v51
	v_fma_f32 v88, v68, v71, v51
	v_sub_f32_e32 v68, v89, v51
	v_fma_f32 v89, v68, v72, v51
	v_sub_f32_e32 v68, v90, v51
	v_fma_f32 v90, v68, v73, v51
	v_sub_f32_e32 v68, v91, v51
	v_fma_f32 v91, v68, v74, v51
	v_sub_f32_e32 v68, v94, v51
	v_fmac_f32_e32 v51, v68, v75
	s_nop 0
	v_mul_f32_e32 v68, v79, v88
	v_mul_f32_e32 v69, v83, v51
	v_fmac_f32_e32 v68, v87, v78
	v_fmac_f32_e32 v69, v91, v82
	v_fmac_f32_e32 v68, v86, v77
	v_fmac_f32_e32 v69, v90, v81
	s_nop 0
	v_fmac_f32_e32 v68, v85, v76
	v_fmac_f32_e32 v69, v89, v80
	v_add_f32_e32 v93, v68, v69
	ds_read_b128 v[68:71], v21 offset:11776
	ds_read_b128 v[72:75], v21 offset:12032
	ds_read_b128 v[76:79], v21 offset:3584
	ds_read_b128 v[80:83], v21 offset:3840
	ds_read_b32 v94, v43 offset:25024
	s_waitcnt lgkmcnt(5)
	v_sub_f32_e32 v85, v85, v92
	v_fma_f32 v85, v85, v52, v92
	v_sub_f32_e32 v52, v86, v92
	v_fma_f32 v86, v52, v53, v92
	v_sub_f32_e32 v52, v87, v92
	v_fma_f32 v87, v52, v54, v92
	v_sub_f32_e32 v52, v88, v92
	v_fma_f32 v88, v52, v55, v92
	v_sub_f32_e32 v52, v89, v92
	v_fma_f32 v89, v52, v56, v92
	v_sub_f32_e32 v52, v90, v92
	v_fma_f32 v90, v52, v57, v92
	v_sub_f32_e32 v52, v91, v92
	v_sub_f32_e32 v51, v51, v92
	v_fma_f32 v91, v52, v58, v92
	v_fmac_f32_e32 v92, v51, v59
	s_nop 0
	v_mul_f32_e32 v51, v63, v88
	v_mul_f32_e32 v52, v67, v92
	v_fmac_f32_e32 v51, v87, v62
	v_fmac_f32_e32 v52, v91, v66
	v_fmac_f32_e32 v51, v86, v61
	v_fmac_f32_e32 v52, v90, v65
	s_nop 0
	v_fmac_f32_e32 v51, v85, v60
	v_fmac_f32_e32 v52, v89, v64
	v_add_f32_e32 v51, v51, v52
	ds_read_b128 v[52:55], v21 offset:12288
	ds_read_b128 v[56:59], v21 offset:12544
	ds_read_b128 v[60:63], v21 offset:4096
	ds_read_b128 v[64:67], v21 offset:4352
	ds_read_b32 v95, v43 offset:25088
	s_waitcnt lgkmcnt(5)
	v_sub_f32_e32 v85, v85, v94
	v_fma_f32 v85, v85, v68, v94
	v_sub_f32_e32 v68, v86, v94
	v_fma_f32 v86, v68, v69, v94
	v_sub_f32_e32 v68, v87, v94
	v_fma_f32 v87, v68, v70, v94
	v_sub_f32_e32 v68, v88, v94
	v_fma_f32 v88, v68, v71, v94
	v_sub_f32_e32 v68, v89, v94
	v_fma_f32 v89, v68, v72, v94
	v_sub_f32_e32 v68, v90, v94
	v_fma_f32 v90, v68, v73, v94
	v_sub_f32_e32 v68, v91, v94
	v_fma_f32 v91, v68, v74, v94
	v_sub_f32_e32 v68, v92, v94
	v_fmac_f32_e32 v94, v68, v75
	s_nop 0
	v_mul_f32_e32 v68, v79, v88
	v_mul_f32_e32 v69, v83, v94
	v_fmac_f32_e32 v68, v87, v78
	v_fmac_f32_e32 v69, v91, v82
	v_fmac_f32_e32 v68, v86, v77
	v_fmac_f32_e32 v69, v90, v81
	v_cndmask_b32_e64 v70, v84, v93, s[0:1]
	v_fmac_f32_e32 v68, v85, v76
	v_fmac_f32_e32 v69, v89, v80
	v_add_f32_e32 v68, v68, v69
	v_cndmask_b32_e64 v69, v93, v84, s[0:1]
	v_cndmask_b32_e64 v71, v68, v51, s[0:1]
	v_cndmask_b32_e64 v51, v51, v68, s[0:1]
	v_add_f32_dpp v68, v70, v69 quad_perm:[1,0,3,2] row_mask:0xf bank_mask:0xf bound_ctrl:1
	s_nop 0
	v_add_f32_dpp v51, v51, v71 quad_perm:[1,0,3,2] row_mask:0xf bank_mask:0xf bound_ctrl:1
	v_cndmask_b32_e64 v69, v51, v68, s[4:5]
	v_cndmask_b32_e64 v51, v68, v51, s[4:5]
	v_add_u32_e32 v68, v41, v46
	s_nop 0
	v_add_f32_dpp v51, v51, v69 quad_perm:[2,3,0,1] row_mask:0xf bank_mask:0xf bound_ctrl:1
	s_nop 1
	v_add_f32_dpp v51, v51, v51 row_ror:4 row_mask:0xf bank_mask:0xf bound_ctrl:1
	s_nop 1
	v_add_f32_dpp v51, v51, v51 row_ror:8 row_mask:0xf bank_mask:0xf bound_ctrl:1
	ds_write_b32 v68, v51 offset:25600
	ds_read_b128 v[68:71], v21 offset:12800
	ds_read_b128 v[72:75], v21 offset:13056
	ds_read_b128 v[76:79], v21 offset:4608
	ds_read_b128 v[80:83], v21 offset:4864
	ds_read_b32 v51, v43 offset:25152
	s_waitcnt lgkmcnt(6)
	v_sub_f32_e32 v84, v85, v95
	v_fma_f32 v84, v84, v52, v95
	v_sub_f32_e32 v52, v86, v95
	v_fma_f32 v85, v52, v53, v95
	v_sub_f32_e32 v52, v87, v95
	v_fma_f32 v86, v52, v54, v95
	v_sub_f32_e32 v52, v88, v95
	v_fma_f32 v87, v52, v55, v95
	v_sub_f32_e32 v52, v89, v95
	v_fma_f32 v88, v52, v56, v95
	v_sub_f32_e32 v52, v90, v95
	v_fma_f32 v89, v52, v57, v95
	v_sub_f32_e32 v52, v91, v95
	v_fma_f32 v90, v52, v58, v95
	v_sub_f32_e32 v52, v94, v95
	v_fmac_f32_e32 v95, v52, v59
	s_nop 0
	v_mul_f32_e32 v52, v63, v87
	v_mul_f32_e32 v53, v67, v95
	v_fmac_f32_e32 v52, v86, v62
	v_fmac_f32_e32 v53, v90, v66
	v_fmac_f32_e32 v52, v85, v61
	v_fmac_f32_e32 v53, v89, v65
	s_nop 0
	v_fmac_f32_e32 v52, v84, v60
	v_fmac_f32_e32 v53, v88, v64
	v_add_f32_e32 v91, v52, v53
	ds_read_b128 v[52:55], v21 offset:13312
	ds_read_b128 v[56:59], v21 offset:13568
	ds_read_b128 v[60:63], v21 offset:5120
	ds_read_b128 v[64:67], v21 offset:5376
	ds_read_b32 v92, v43 offset:25216
	s_waitcnt lgkmcnt(5)
	v_sub_f32_e32 v84, v84, v51
	v_fma_f32 v84, v84, v68, v51
	v_sub_f32_e32 v68, v85, v51
	v_fma_f32 v85, v68, v69, v51
	v_sub_f32_e32 v68, v86, v51
	v_fma_f32 v86, v68, v70, v51
	v_sub_f32_e32 v68, v87, v51
	v_fma_f32 v87, v68, v71, v51
	v_sub_f32_e32 v68, v88, v51
	v_fma_f32 v88, v68, v72, v51
	v_sub_f32_e32 v68, v89, v51
	v_fma_f32 v89, v68, v73, v51
	v_sub_f32_e32 v68, v90, v51
	v_fma_f32 v90, v68, v74, v51
	v_sub_f32_e32 v68, v95, v51
	v_fmac_f32_e32 v51, v68, v75
	s_nop 0
	v_mul_f32_e32 v68, v79, v87
	v_mul_f32_e32 v69, v83, v51
	v_fmac_f32_e32 v68, v86, v78
	v_fmac_f32_e32 v69, v90, v82
	v_fmac_f32_e32 v68, v85, v77
	v_fmac_f32_e32 v69, v89, v81
	s_nop 0
	v_fmac_f32_e32 v68, v84, v76
	v_fmac_f32_e32 v69, v88, v80
	v_add_f32_e32 v93, v68, v69
	ds_read_b128 v[68:71], v21 offset:13824
	ds_read_b128 v[72:75], v21 offset:14080
	ds_read_b128 v[76:79], v21 offset:5632
	ds_read_b128 v[80:83], v21 offset:5888
	ds_read_b32 v94, v43 offset:25280
	s_waitcnt lgkmcnt(5)
	v_sub_f32_e32 v84, v84, v92
	v_fma_f32 v84, v84, v52, v92
	v_sub_f32_e32 v52, v85, v92
	v_fma_f32 v85, v52, v53, v92
	v_sub_f32_e32 v52, v86, v92
	v_fma_f32 v86, v52, v54, v92
	v_sub_f32_e32 v52, v87, v92
	v_fma_f32 v87, v52, v55, v92
	v_sub_f32_e32 v52, v88, v92
	v_fma_f32 v88, v52, v56, v92
	v_sub_f32_e32 v52, v89, v92
	v_fma_f32 v89, v52, v57, v92
	v_sub_f32_e32 v52, v90, v92
	v_sub_f32_e32 v51, v51, v92
	v_fma_f32 v90, v52, v58, v92
	v_fmac_f32_e32 v92, v51, v59
	s_nop 0
	v_mul_f32_e32 v51, v63, v87
	v_mul_f32_e32 v52, v67, v92
	v_fmac_f32_e32 v51, v86, v62
	v_fmac_f32_e32 v52, v90, v66
	v_fmac_f32_e32 v51, v85, v61
	v_fmac_f32_e32 v52, v89, v65
	s_nop 0
	v_fmac_f32_e32 v51, v84, v60
	v_fmac_f32_e32 v52, v88, v64
	v_add_f32_e32 v51, v51, v52
	ds_read_b128 v[52:55], v21 offset:14336
	ds_read_b128 v[56:59], v21 offset:14592
	ds_read_b128 v[60:63], v21 offset:6144
	ds_read_b128 v[64:67], v21 offset:6400
	ds_read_b32 v95, v43 offset:25344
	s_waitcnt lgkmcnt(5)
	v_sub_f32_e32 v84, v84, v94
	v_fma_f32 v84, v84, v68, v94
	v_sub_f32_e32 v68, v85, v94
	v_fma_f32 v85, v68, v69, v94
	v_sub_f32_e32 v68, v86, v94
	v_fma_f32 v86, v68, v70, v94
	v_sub_f32_e32 v68, v87, v94
	v_fma_f32 v87, v68, v71, v94
	v_sub_f32_e32 v68, v88, v94
	v_fma_f32 v88, v68, v72, v94
	v_sub_f32_e32 v68, v89, v94
	v_fma_f32 v89, v68, v73, v94
	v_sub_f32_e32 v68, v90, v94
	v_fma_f32 v90, v68, v74, v94
	v_sub_f32_e32 v68, v92, v94
	v_fmac_f32_e32 v94, v68, v75
	s_nop 0
	v_mul_f32_e32 v68, v79, v87
	v_mul_f32_e32 v69, v83, v94
	v_fmac_f32_e32 v68, v86, v78
	v_fmac_f32_e32 v69, v90, v82
	v_fmac_f32_e32 v68, v85, v77
	v_fmac_f32_e32 v69, v89, v81
	v_cndmask_b32_e64 v70, v91, v93, s[0:1]
	v_fmac_f32_e32 v68, v84, v76
	v_fmac_f32_e32 v69, v88, v80
	v_add_f32_e32 v68, v68, v69
	v_cndmask_b32_e64 v69, v93, v91, s[0:1]
	v_cndmask_b32_e64 v71, v68, v51, s[0:1]
	v_cndmask_b32_e64 v51, v51, v68, s[0:1]
	v_add_f32_dpp v68, v70, v69 quad_perm:[1,0,3,2] row_mask:0xf bank_mask:0xf bound_ctrl:1
	s_nop 0
	v_add_f32_dpp v51, v51, v71 quad_perm:[1,0,3,2] row_mask:0xf bank_mask:0xf bound_ctrl:1
	v_cndmask_b32_e64 v69, v51, v68, s[4:5]
	v_cndmask_b32_e64 v51, v68, v51, s[4:5]
	v_add_u32_e32 v68, v41, v47
	s_nop 0
	v_add_f32_dpp v51, v51, v69 quad_perm:[2,3,0,1] row_mask:0xf bank_mask:0xf bound_ctrl:1
	s_nop 1
	v_add_f32_dpp v51, v51, v51 row_ror:4 row_mask:0xf bank_mask:0xf bound_ctrl:1
	s_nop 1
	v_add_f32_dpp v51, v51, v51 row_ror:8 row_mask:0xf bank_mask:0xf bound_ctrl:1
	ds_write_b32 v68, v51 offset:25600
	ds_read_b128 v[68:71], v21 offset:14848
	ds_read_b128 v[72:75], v21 offset:15104
	ds_read_b128 v[76:79], v21 offset:6656
	ds_read_b128 v[80:83], v21 offset:6912
	ds_read_b32 v91, v43 offset:25408
	s_waitcnt lgkmcnt(6)
	v_sub_f32_e32 v51, v84, v95
	v_fma_f32 v51, v51, v52, v95
	v_sub_f32_e32 v52, v85, v95
	v_fma_f32 v84, v52, v53, v95
	v_sub_f32_e32 v52, v86, v95
	v_fma_f32 v85, v52, v54, v95
	v_sub_f32_e32 v52, v87, v95
	v_fma_f32 v86, v52, v55, v95
	v_sub_f32_e32 v52, v88, v95
	v_fma_f32 v87, v52, v56, v95
	v_sub_f32_e32 v52, v89, v95
	v_fma_f32 v88, v52, v57, v95
	v_sub_f32_e32 v52, v90, v95
	v_fma_f32 v89, v52, v58, v95
	v_sub_f32_e32 v52, v94, v95
	v_fmac_f32_e32 v95, v52, v59
	s_nop 0
	v_mul_f32_e32 v52, v63, v86
	v_mul_f32_e32 v53, v67, v95
	v_fmac_f32_e32 v52, v85, v62
	v_fmac_f32_e32 v53, v89, v66
	v_fmac_f32_e32 v52, v84, v61
	v_fmac_f32_e32 v53, v88, v65
	s_nop 0
	v_fmac_f32_e32 v52, v51, v60
	v_fmac_f32_e32 v53, v87, v64
	v_add_f32_e32 v90, v52, v53
	ds_read_b128 v[52:55], v21 offset:15360
	ds_read_b128 v[56:59], v21 offset:15616
	ds_read_b128 v[60:63], v21 offset:7168
	ds_read_b128 v[64:67], v21 offset:7424
	ds_read_b32 v92, v43 offset:25472
	s_waitcnt lgkmcnt(5)
	v_sub_f32_e32 v51, v51, v91
	v_fma_f32 v93, v51, v68, v91
	v_sub_f32_e32 v51, v84, v91
	v_fma_f32 v84, v51, v69, v91
	v_sub_f32_e32 v51, v85, v91
	v_fma_f32 v85, v51, v70, v91
	v_sub_f32_e32 v51, v86, v91
	v_fma_f32 v86, v51, v71, v91
	v_sub_f32_e32 v51, v87, v91
	v_fma_f32 v87, v51, v72, v91
	v_sub_f32_e32 v51, v88, v91
	v_fma_f32 v88, v51, v73, v91
	v_sub_f32_e32 v51, v89, v91
	v_fma_f32 v89, v51, v74, v91
	v_sub_f32_e32 v51, v95, v91
	v_fmac_f32_e32 v91, v51, v75
	s_nop 0
	v_mul_f32_e32 v51, v79, v86
	v_mul_f32_e32 v68, v83, v91
	v_fmac_f32_e32 v51, v85, v78
	v_fmac_f32_e32 v68, v89, v82
	v_fmac_f32_e32 v51, v84, v77
	v_fmac_f32_e32 v68, v88, v81
	s_nop 0
	v_fmac_f32_e32 v51, v93, v76
	v_fmac_f32_e32 v68, v87, v80
	v_add_f32_e32 v94, v51, v68
	ds_read_b128 v[68:71], v21 offset:15872
	ds_read_b128 v[72:75], v21 offset:16128
	ds_read_b128 v[76:79], v21 offset:7680
	ds_read_b128 v[80:83], v21 offset:7936
	ds_read_b32 v51, v43 offset:25536
	s_waitcnt lgkmcnt(5)
	v_sub_f32_e32 v84, v84, v92
	v_fma_f32 v53, v84, v53, v92
	v_sub_f32_e32 v84, v85, v92
	v_fma_f32 v84, v84, v54, v92
	v_sub_f32_e32 v54, v86, v92
	v_fma_f32 v55, v54, v55, v92
	v_sub_f32_e32 v54, v87, v92
	v_fma_f32 v85, v54, v56, v92
	v_sub_f32_e32 v54, v88, v92
	v_fma_f32 v86, v54, v57, v92
	v_sub_f32_e32 v54, v89, v92
	v_sub_f32_e32 v93, v93, v92
	v_fma_f32 v87, v54, v58, v92
	v_sub_f32_e32 v54, v91, v92
	v_fma_f32 v52, v93, v52, v92
	v_fmac_f32_e32 v92, v54, v59
	s_nop 0
	v_mul_f32_e32 v54, v63, v55
	v_mul_f32_e32 v56, v67, v92
	v_fmac_f32_e32 v54, v84, v62
	v_fmac_f32_e32 v56, v87, v66
	v_fmac_f32_e32 v54, v53, v61
	v_fmac_f32_e32 v56, v86, v65
	s_nop 0
	v_fmac_f32_e32 v54, v52, v60
	v_fmac_f32_e32 v56, v85, v64
	v_add_f32_e32 v59, v54, v56
	s_waitcnt lgkmcnt(0)
	v_sub_f32_e32 v53, v53, v51
	v_fma_f32 v54, v53, v69, v51
	v_sub_f32_e32 v53, v84, v51
	v_fma_f32 v56, v53, v70, v51
	v_sub_f32_e32 v53, v55, v51
	v_fma_f32 v58, v53, v71, v51
	v_sub_f32_e32 v53, v85, v51
	v_fma_f32 v57, v53, v72, v51
	v_sub_f32_e32 v53, v86, v51
	v_sub_f32_e32 v52, v52, v51
	v_fma_f32 v55, v53, v73, v51
	v_sub_f32_e32 v53, v87, v51
	v_sub_f32_e32 v60, v92, v51
	v_fma_f32 v52, v52, v68, v51
	v_fma_f32 v53, v53, v74, v51
	v_fmac_f32_e32 v51, v60, v75
	s_nop 0
	v_mul_f32_e32 v60, v79, v58
	v_mul_f32_e32 v61, v83, v51
	v_fmac_f32_e32 v60, v56, v78
	v_fmac_f32_e32 v61, v53, v82
	v_fmac_f32_e32 v60, v54, v77
	v_fmac_f32_e32 v61, v55, v81
	v_cndmask_b32_e64 v62, v90, v94, s[0:1]
	v_fmac_f32_e32 v60, v52, v76
	v_fmac_f32_e32 v61, v57, v80
	v_add_f32_e32 v60, v60, v61
	v_cndmask_b32_e64 v61, v94, v90, s[0:1]
	v_cndmask_b32_e64 v63, v60, v59, s[0:1]
	v_cndmask_b32_e64 v59, v59, v60, s[0:1]
	v_add_f32_dpp v60, v62, v61 quad_perm:[1,0,3,2] row_mask:0xf bank_mask:0xf bound_ctrl:1
	v_add_u32_e32 v41, v41, v48
	v_add_f32_dpp v59, v59, v63 quad_perm:[1,0,3,2] row_mask:0xf bank_mask:0xf bound_ctrl:1
	v_cndmask_b32_e64 v61, v59, v60, s[4:5]
	v_cndmask_b32_e64 v59, v60, v59, s[4:5]
	s_nop 1
	v_add_f32_dpp v59, v59, v61 quad_perm:[2,3,0,1] row_mask:0xf bank_mask:0xf bound_ctrl:1
	s_nop 1
	v_add_f32_dpp v59, v59, v59 row_ror:4 row_mask:0xf bank_mask:0xf bound_ctrl:1
	s_nop 1
	v_add_f32_dpp v59, v59, v59 row_ror:8 row_mask:0xf bank_mask:0xf bound_ctrl:1
	ds_write_b32 v41, v59 offset:25600
	s_addk_i32 s31, 0x100
	s_add_i32 s30, s30, 1
	s_cmp_lg_u32 s53, s31
	v_add_u32_e32 v50, 16, v50
	s_waitcnt lgkmcnt(0)
	s_cbranch_scc0 .Lhg1_exitb
.LBB0_1050:
	v_add_u32_e32 v15, s77, v15
	v_add_u32_e32 v17, s78, v17
	s_waitcnt vmcnt(0)
	v_lshlrev_b32_e32 v41, 16, v8
	v_mul_f32_e32 v41, 0xbfb8aa3b, v41
	v_and_b32_e32 v59, 0xffff0000, v8
	v_exp_f32_e32 v41, v41
	v_mul_f32_e32 v59, 0xbfb8aa3b, v59
	v_exp_f32_e32 v59, v59
	v_lshlrev_b32_e32 v60, 16, v4
	v_add_f32_e32 v41, 1.0, v41
	v_rcp_f32_e32 v68, v41
	v_add_f32_e32 v41, 1.0, v59
	v_rcp_f32_e32 v69, v41
	v_lshlrev_b32_e32 v41, 16, v9
	v_mul_f32_e32 v41, 0xbfb8aa3b, v41
	v_and_b32_e32 v59, 0xffff0000, v9
	v_exp_f32_e32 v41, v41
	v_mul_f32_e32 v59, 0xbfb8aa3b, v59
	v_exp_f32_e32 v59, v59
	v_and_b32_e32 v61, 0xffff0000, v4
	v_add_f32_e32 v41, 1.0, v41
	v_rcp_f32_e32 v70, v41
	v_add_f32_e32 v41, 1.0, v59
	v_rcp_f32_e32 v71, v41
	v_lshlrev_b32_e32 v41, 16, v10
	v_mul_f32_e32 v41, 0xbfb8aa3b, v41
	v_and_b32_e32 v59, 0xffff0000, v10
	v_exp_f32_e32 v41, v41
	v_mul_f32_e32 v59, 0xbfb8aa3b, v59
	v_exp_f32_e32 v59, v59
	v_lshlrev_b32_e32 v62, 16, v5
	v_add_f32_e32 v41, 1.0, v41
	v_rcp_f32_e32 v72, v41
	v_add_f32_e32 v41, 1.0, v59
	v_rcp_f32_e32 v73, v41
	v_lshlrev_b32_e32 v41, 16, v11
	v_mul_f32_e32 v41, 0xbfb8aa3b, v41
	v_and_b32_e32 v59, 0xffff0000, v11
	v_exp_f32_e32 v41, v41
	v_mul_f32_e32 v59, 0xbfb8aa3b, v59
	v_exp_f32_e32 v59, v59
	v_and_b32_e32 v63, 0xffff0000, v5
	v_add_f32_e32 v41, 1.0, v41
	v_rcp_f32_e32 v74, v41
	v_add_f32_e32 v41, 1.0, v59
	v_rcp_f32_e32 v75, v41
	v_lshlrev_b32_e32 v64, 16, v6
	v_and_b32_e32 v65, 0xffff0000, v6
	v_lshlrev_b32_e32 v66, 16, v7
	v_and_b32_e32 v67, 0xffff0000, v7
	s_and_b32 s54, s31, 0x100
	ds_write_b128 v15, v[60:63]
	ds_write_b128 v15, v[64:67] offset:16
	v_pk_fma_f32 v[60:61], v[30:31], v[68:69], v[22:23]
	v_pk_fma_f32 v[62:63], v[32:33], v[70:71], v[24:25]
	ds_write_b128 v15, v[60:63] offset:8192
	v_pk_fma_f32 v[60:61], v[34:35], v[72:73], v[26:27]
	v_pk_fma_f32 v[62:63], v[36:37], v[74:75], v[28:29]
	v_lshlrev_b32_e32 v41, 16, v39
	s_cmp_eq_u32 s31, 0
	ds_write_b128 v15, v[60:63] offset:8208
	ds_write_b32 v17, v41 offset:24576
	s_waitcnt lgkmcnt(0)
	s_barrier
	v_add_u32_e32 v21, s77, v21
	v_add_u32_e32 v43, s78, v43
	v_add_u32_e32 v49, s78, v49
	s_mul_i32 s77, s77, -1
	s_mul_i32 s78, s78, -1
	s_cbranch_scc1 .LBB0_1052
	v_mov_b64_e32 v[60:61], s[46:47]
	v_mad_i64_i32 v[60:61], s[56:57], v50, s50, v[60:61]
	s_lshl_b32 s14, s29, 1
	v_lshl_add_u64 v[60:61], v[60:61], 0, s[14:15]
	s_lshl_b32 s14, s27, 1
	v_lshl_add_u64 v[60:61], v[60:61], 0, s[14:15]
	s_xor_b32 s14, s54, 0x100
	v_lshl_add_u32 v41, s14, 2, v45
	ds_read_b32 v41, v41 offset:25600
	v_lshl_add_u64 v[60:61], v[60:61], 0, v[2:3]
	v_add_co_u32_e32 v60, vcc, 0xfffd9000, v60
	s_waitcnt lgkmcnt(0)
	v_cvt_pk_bf16_f32 v41, v41, s0
	v_addc_co_u32_e32 v61, vcc, -1, v61, vcc
	global_store_short v[60:61], v41, off offset:-2560

.LBB0_1092:
	v_add_u32_e32 v1, s10, v24
	v_mov_b64_e32 v[12:13], s[46:47]
	v_mad_i64_i32 v[26:27], s[2:3], v1, s50, v[12:13]
	v_mov_b64_e32 v[12:13], s[88:89]
	v_mad_i64_i32 v[14:15], s[2:3], v1, s52, v[12:13]
	s_lshl_b32 s2, s5, 6
	s_lshl_b32 s14, s5, 7
	v_lshl_add_u64 v[16:17], v[26:27], 0, s[14:15]
	v_lshlrev_b32_e32 v12, 1, v0
	v_mov_b32_e32 v13, v3
	s_or_b32 s3, s9, s2
	v_lshl_add_u64 v[16:17], v[16:17], 0, v[12:13]
	v_or_b32_e32 v2, s3, v10
	v_add_co_u32_e32 v18, vcc, s51, v16
	v_lshl_add_u64 v[14:15], v[14:15], 0, s[14:15]
	v_or_b32_e32 v28, 0xc00, v2
	v_addc_co_u32_e32 v19, vcc, 0, v17, vcc
	v_lshl_add_u64 v[22:23], v[14:15], 0, v[12:13]
	v_lshlrev_b32_e32 v2, 1, v28
	global_load_dwordx2 v[16:17], v[16:17], off offset:1024
	s_nop 0
	global_load_dwordx2 v[20:21], v[18:19], off offset:1024
	global_load_dwordx2 v[14:15], v[22:23], off
	s_nop 0
	global_load_dwordx2 v[18:19], v[22:23], off offset:1024
	s_nop 0
	global_load_dwordx2 v[22:23], v[22:23], off offset:2048
	v_lshl_add_u64 v[26:27], v[26:27], 0, v[2:3]
	global_load_ushort v27, v[26:27], off
	v_and_b32_e32 v2, 63, v11
	v_or_b32_e32 v2, 0x200, v2
	v_cmp_eq_u32_e32 vcc, 0, v10
	v_lshlrev_b32_e32 v30, 2, v0
	v_lshlrev_b32_e32 v32, 2, v11
	v_and_b32_e32 v11, -16, v11
	s_add_u32 s24, s88, s14
	v_cndmask_b32_e32 v2, v2, v25, vcc
	v_cndmask_b32_e64 v26, 0, 16, vcc
	v_lshl_or_b32 v31, v24, 8, v30
	v_or_b32_e32 v24, v11, v10
	s_addc_u32 s25, s89, 0
	s_mov_b32 s3, 1
	s_mov_b32 s10, 0
	v_lshlrev_b32_e32 v33, 2, v25
	v_mul_u32_u24_e32 v34, 60, v26
	v_lshlrev_b32_e32 v35, 2, v24
	v_lshlrev_b32_e32 v36, 2, v2
	v_lshlrev_b32_e32 v37, 3, v26
	v_mul_u32_u24_e32 v38, 12, v26
	v_lshlrev_b32_e32 v39, 4, v26
	v_mul_u32_u24_e32 v40, 20, v26
	v_mul_u32_u24_e32 v41, 24, v26
	v_mul_u32_u24_e32 v43, 28, v26
	v_lshlrev_b32_e32 v44, 5, v26
	v_mul_u32_u24_e32 v45, 36, v26
	v_mul_u32_u24_e32 v46, 40, v26
	v_mul_u32_u24_e32 v47, 44, v26
	v_mul_u32_u24_e32 v48, 48, v26
	v_mul_u32_u24_e32 v49, 52, v26
	v_mul_u32_u24_e32 v50, 56, v26
	v_lshl_add_u64 v[24:25], s[24:25], 0, v[12:13]
	v_mul_i32_i24_e32 v51, 0xffffffc8, v26
	s_lshl_b32 s11, s8, 8
	v_lshlrev_b32_e32 v26, 1, v28
	v_mov_b32_e32 v28, v1
	s_movk_i32 s76, 0x6400
	s_barrier
	s_branch .LBB0_1094
.LBB0_1093:
	v_add_u32_e32 v2, 0x5000, v33
	ds_read2_b32 v[92:93], v2 offset1:16
	ds_read_b128 v[52:55], v30 offset:12288
	ds_read_b128 v[56:59], v30 offset:12544
	ds_read_b128 v[60:63], v30 offset:4096
	ds_read_b128 v[64:67], v30 offset:4352
	ds_read_b128 v[68:71], v30 offset:16384
	ds_read_b128 v[72:75], v30 offset:16640
	ds_read_b128 v[76:79], v30 offset:8192
	ds_read_b128 v[80:83], v30 offset:8448
	ds_read_b128 v[84:87], v30
	ds_read_b128 v[88:91], v30 offset:256
	v_lshl_add_u32 v13, s24, 2, v36
	v_add_u32_e32 v2, v13, v34
	s_waitcnt lgkmcnt(9)
	v_mul_f32_e32 v29, v7, v55
	v_fmac_f32_e32 v29, v6, v54
	v_fmac_f32_e32 v29, v5, v53
	v_fmac_f32_e32 v29, v4, v52
	s_waitcnt lgkmcnt(3)
	v_mul_f32_e32 v94, v76, v92
	v_mul_f32_e32 v95, v77, v92
	v_add_f32_dpp v29, v29, v29 quad_perm:[1,0,3,2] row_mask:0xf bank_mask:0xf bound_ctrl:1
	v_mul_f32_e32 v96, v78, v92
	v_mul_f32_e32 v92, v79, v92
	v_add_f32_dpp v29, v29, v29 quad_perm:[2,3,0,1] row_mask:0xf bank_mask:0xf bound_ctrl:1
	s_nop 1
	v_add_f32_dpp v29, v29, v29 row_half_mirror row_mask:0xf bank_mask:0xf bound_ctrl:1
	s_nop 1
	v_add_f32_dpp v29, v29, v29 row_mirror row_mask:0xf bank_mask:0xf bound_ctrl:1
	v_fmac_f32_e32 v92, v29, v71
	v_fmac_f32_e32 v96, v29, v70
	v_fmac_f32_e32 v92, v7, v63
	v_fmac_f32_e32 v94, v29, v68
	v_fmac_f32_e32 v95, v29, v69
	v_fmac_f32_e32 v96, v6, v62
	v_fmac_f32_e32 v95, v5, v61
	s_waitcnt lgkmcnt(1)
	v_mul_f32_e32 v29, v87, v92
	v_fmac_f32_e32 v94, v4, v60
	v_fmac_f32_e32 v29, v96, v86
	s_nop 0
	v_fmac_f32_e32 v29, v95, v85
	v_fmac_f32_e32 v29, v94, v84
	ds_read_b128 v[4:7], v30 offset:12800
	ds_read_b128 v[52:55], v30 offset:8704
	ds_read_b128 v[60:63], v30 offset:4608
	ds_read_b128 v[68:71], v30 offset:512
	ds_read_b128 v[76:79], v30 offset:16896
	ds_read_b32 v97, v33 offset:20608
	v_mul_f32_e32 v59, v59, v92
	v_fmac_f32_e32 v59, v96, v58
	v_fmac_f32_e32 v59, v95, v57
	v_fmac_f32_e32 v59, v94, v56
	v_add_f32_dpp v29, v29, v29 quad_perm:[1,0,3,2] row_mask:0xf bank_mask:0xf bound_ctrl:1
	v_mul_f32_e32 v98, v80, v93
	v_add_f32_dpp v56, v59, v59 quad_perm:[1,0,3,2] row_mask:0xf bank_mask:0xf bound_ctrl:1
	v_add_f32_dpp v29, v29, v29 quad_perm:[2,3,0,1] row_mask:0xf bank_mask:0xf bound_ctrl:1
	s_nop 0
	v_add_f32_dpp v56, v56, v56 quad_perm:[2,3,0,1] row_mask:0xf bank_mask:0xf bound_ctrl:1
	v_add_f32_dpp v29, v29, v29 row_half_mirror row_mask:0xf bank_mask:0xf bound_ctrl:1
	s_nop 0
	v_add_f32_dpp v56, v56, v56 row_half_mirror row_mask:0xf bank_mask:0xf bound_ctrl:1
	v_add_f32_dpp v29, v29, v29 row_mirror row_mask:0xf bank_mask:0xf bound_ctrl:1
	ds_write_b32 v13, v29 offset:21504
	s_nop 0
	v_add_f32_dpp v29, v56, v56 row_mirror row_mask:0xf bank_mask:0xf bound_ctrl:1
	v_fmac_f32_e32 v98, v29, v72
	v_fmac_f32_e32 v98, v94, v64
	v_mul_f32_e32 v94, v81, v93
	v_fmac_f32_e32 v94, v29, v73
	v_fmac_f32_e32 v94, v95, v65
	v_mul_f32_e32 v95, v82, v93
	v_mul_f32_e32 v93, v83, v93
	v_fmac_f32_e32 v93, v29, v75
	v_fmac_f32_e32 v95, v29, v74
	v_fmac_f32_e32 v93, v92, v67
	v_fmac_f32_e32 v95, v96, v66
	s_waitcnt lgkmcnt(7)
	v_mul_f32_e32 v29, v91, v93
	v_fmac_f32_e32 v29, v95, v90
	v_fmac_f32_e32 v29, v94, v89
	v_fmac_f32_e32 v29, v98, v88
	ds_read_b128 v[56:59], v30 offset:13056
	ds_read_b128 v[64:67], v30 offset:8960
	ds_read_b128 v[72:75], v30 offset:4864
	ds_read_b128 v[80:83], v30 offset:768
	ds_read_b128 v[84:87], v30 offset:17152
	ds_read_b32 v88, v33 offset:20672
	s_waitcnt lgkmcnt(12)
	v_mul_f32_e32 v7, v7, v93
	v_fmac_f32_e32 v7, v95, v6
	v_fmac_f32_e32 v7, v94, v5
	v_fmac_f32_e32 v7, v98, v4
	s_waitcnt lgkmcnt(7)
	v_mul_f32_e32 v91, v55, v97
	v_mul_f32_e32 v90, v54, v97
	v_add_f32_dpp v4, v7, v7 quad_perm:[1,0,3,2] row_mask:0xf bank_mask:0xf bound_ctrl:1
	v_add_f32_dpp v5, v29, v29 quad_perm:[1,0,3,2] row_mask:0xf bank_mask:0xf bound_ctrl:1
	v_mul_f32_e32 v89, v53, v97
	v_add_f32_dpp v4, v4, v4 quad_perm:[2,3,0,1] row_mask:0xf bank_mask:0xf bound_ctrl:1
	v_add_f32_dpp v5, v5, v5 quad_perm:[2,3,0,1] row_mask:0xf bank_mask:0xf bound_ctrl:1
	v_mul_f32_e32 v29, v52, v97
	v_add_f32_dpp v4, v4, v4 row_half_mirror row_mask:0xf bank_mask:0xf bound_ctrl:1
	v_add_f32_dpp v5, v5, v5 row_half_mirror row_mask:0xf bank_mask:0xf bound_ctrl:1
	v_add_u32_e32 v6, v2, v51
	v_add_f32_dpp v4, v4, v4 row_mirror row_mask:0xf bank_mask:0xf bound_ctrl:1
	v_fmac_f32_e32 v91, v4, v79
	v_fmac_f32_e32 v90, v4, v78
	v_fmac_f32_e32 v91, v93, v63
	v_fmac_f32_e32 v89, v4, v77
	v_fmac_f32_e32 v90, v95, v62
	v_fmac_f32_e32 v29, v4, v76
	v_mul_f32_e32 v92, v71, v91
	v_fmac_f32_e32 v89, v94, v61
	v_add_f32_dpp v5, v5, v5 row_mirror row_mask:0xf bank_mask:0xf bound_ctrl:1
	v_fmac_f32_e32 v92, v90, v70
	v_fmac_f32_e32 v29, v98, v60
	ds_write_b32 v6, v5 offset:21504
	v_fmac_f32_e32 v92, v89, v69
	s_nop 0
	v_fmac_f32_e32 v92, v29, v68
	ds_read_b128 v[4:7], v30 offset:13312
	ds_read_b128 v[52:55], v30 offset:9216
	ds_read_b128 v[60:63], v30 offset:5120
	ds_read_b128 v[68:71], v30 offset:1024
	ds_read_b128 v[76:79], v30 offset:17408
	ds_read_b32 v93, v33 offset:20736
	s_waitcnt lgkmcnt(12)
	v_mul_f32_e32 v59, v59, v91
	v_fmac_f32_e32 v59, v90, v58
	v_fmac_f32_e32 v59, v89, v57
	v_fmac_f32_e32 v59, v29, v56
	v_add_f32_dpp v57, v92, v92 quad_perm:[1,0,3,2] row_mask:0xf bank_mask:0xf bound_ctrl:1
	s_waitcnt lgkmcnt(7)
	v_mul_f32_e32 v92, v64, v88
	v_add_f32_dpp v56, v59, v59 quad_perm:[1,0,3,2] row_mask:0xf bank_mask:0xf bound_ctrl:1
	v_add_f32_dpp v57, v57, v57 quad_perm:[2,3,0,1] row_mask:0xf bank_mask:0xf bound_ctrl:1
	v_add_u32_e32 v58, v13, v37
	v_add_f32_dpp v56, v56, v56 quad_perm:[2,3,0,1] row_mask:0xf bank_mask:0xf bound_ctrl:1
	v_add_f32_dpp v57, v57, v57 row_half_mirror row_mask:0xf bank_mask:0xf bound_ctrl:1
	s_nop 0
	v_add_f32_dpp v56, v56, v56 row_half_mirror row_mask:0xf bank_mask:0xf bound_ctrl:1
	v_add_f32_dpp v57, v57, v57 row_mirror row_mask:0xf bank_mask:0xf bound_ctrl:1
	ds_write_b32 v58, v57 offset:21504
	v_add_f32_dpp v56, v56, v56 row_mirror row_mask:0xf bank_mask:0xf bound_ctrl:1
	v_fmac_f32_e32 v92, v56, v84
	v_fmac_f32_e32 v92, v29, v72
	v_mul_f32_e32 v29, v65, v88
	v_fmac_f32_e32 v29, v56, v85
	v_fmac_f32_e32 v29, v89, v73
	v_mul_f32_e32 v89, v66, v88
	v_mul_f32_e32 v88, v67, v88
	v_fmac_f32_e32 v88, v56, v87
	v_fmac_f32_e32 v89, v56, v86
	v_fmac_f32_e32 v88, v91, v75
	v_fmac_f32_e32 v89, v90, v74
	s_nop 0
	v_mul_f32_e32 v90, v83, v88
	v_fmac_f32_e32 v90, v89, v82
	v_fmac_f32_e32 v90, v29, v81
	v_fmac_f32_e32 v90, v92, v80
	ds_read_b128 v[56:59], v30 offset:13568
	ds_read_b128 v[64:67], v30 offset:9472
	ds_read_b128 v[72:75], v30 offset:5376
	ds_read_b128 v[80:83], v30 offset:1280
	ds_read_b128 v[84:87], v30 offset:17664
	ds_read_b32 v91, v33 offset:20800
	s_waitcnt lgkmcnt(12)
	v_mul_f32_e32 v7, v7, v88
	v_fmac_f32_e32 v7, v89, v6
	v_fmac_f32_e32 v7, v29, v5
	v_fmac_f32_e32 v7, v92, v4
	v_add_f32_dpp v5, v90, v90 quad_perm:[1,0,3,2] row_mask:0xf bank_mask:0xf bound_ctrl:1
	s_waitcnt lgkmcnt(7)
	v_mul_f32_e32 v90, v52, v93
	v_add_f32_dpp v4, v7, v7 quad_perm:[1,0,3,2] row_mask:0xf bank_mask:0xf bound_ctrl:1
	v_add_f32_dpp v5, v5, v5 quad_perm:[2,3,0,1] row_mask:0xf bank_mask:0xf bound_ctrl:1
	v_add_u32_e32 v6, v13, v38
	v_add_f32_dpp v4, v4, v4 quad_perm:[2,3,0,1] row_mask:0xf bank_mask:0xf bound_ctrl:1
	v_add_f32_dpp v5, v5, v5 row_half_mirror row_mask:0xf bank_mask:0xf bound_ctrl:1
	s_nop 0
	v_add_f32_dpp v4, v4, v4 row_half_mirror row_mask:0xf bank_mask:0xf bound_ctrl:1
	v_add_f32_dpp v5, v5, v5 row_mirror row_mask:0xf bank_mask:0xf bound_ctrl:1
	ds_write_b32 v6, v5 offset:21504
	v_add_f32_dpp v4, v4, v4 row_mirror row_mask:0xf bank_mask:0xf bound_ctrl:1
	v_fmac_f32_e32 v90, v4, v76
	v_fmac_f32_e32 v90, v92, v60
	v_mul_f32_e32 v92, v53, v93
	v_fmac_f32_e32 v92, v4, v77
	v_fmac_f32_e32 v92, v29, v61
	v_mul_f32_e32 v29, v54, v93
	v_fmac_f32_e32 v29, v4, v78
	v_fmac_f32_e32 v29, v89, v62
	v_mul_f32_e32 v89, v55, v93
	v_fmac_f32_e32 v89, v4, v79
	v_fmac_f32_e32 v89, v88, v63
	s_nop 0
	v_mul_f32_e32 v88, v71, v89
	v_fmac_f32_e32 v88, v29, v70
	v_fmac_f32_e32 v88, v92, v69
	v_fmac_f32_e32 v88, v90, v68
	ds_read_b128 v[4:7], v30 offset:13824
	ds_read_b128 v[52:55], v30 offset:9728
	ds_read_b128 v[60:63], v30 offset:5632
	ds_read_b128 v[68:71], v30 offset:1536
	ds_read_b128 v[76:79], v30 offset:17920
	ds_read_b32 v93, v33 offset:20864
	s_waitcnt lgkmcnt(12)
	v_mul_f32_e32 v59, v59, v89
	v_fmac_f32_e32 v59, v29, v58
	v_fmac_f32_e32 v59, v92, v57
	v_fmac_f32_e32 v59, v90, v56
	v_add_f32_dpp v57, v88, v88 quad_perm:[1,0,3,2] row_mask:0xf bank_mask:0xf bound_ctrl:1
	s_waitcnt lgkmcnt(7)
	v_mul_f32_e32 v88, v64, v91
	v_add_f32_dpp v56, v59, v59 quad_perm:[1,0,3,2] row_mask:0xf bank_mask:0xf bound_ctrl:1
	v_add_f32_dpp v57, v57, v57 quad_perm:[2,3,0,1] row_mask:0xf bank_mask:0xf bound_ctrl:1
	v_add_u32_e32 v58, v13, v39
	v_add_f32_dpp v56, v56, v56 quad_perm:[2,3,0,1] row_mask:0xf bank_mask:0xf bound_ctrl:1
	v_add_f32_dpp v57, v57, v57 row_half_mirror row_mask:0xf bank_mask:0xf bound_ctrl:1
	s_nop 0
	v_add_f32_dpp v56, v56, v56 row_half_mirror row_mask:0xf bank_mask:0xf bound_ctrl:1
	v_add_f32_dpp v57, v57, v57 row_mirror row_mask:0xf bank_mask:0xf bound_ctrl:1
	ds_write_b32 v58, v57 offset:21504
	v_add_f32_dpp v56, v56, v56 row_mirror row_mask:0xf bank_mask:0xf bound_ctrl:1
	v_fmac_f32_e32 v88, v56, v84
	v_fmac_f32_e32 v88, v90, v72
	v_mul_f32_e32 v90, v65, v91
	v_fmac_f32_e32 v90, v56, v85
	v_fmac_f32_e32 v90, v92, v73
	v_mul_f32_e32 v92, v66, v91
	v_fmac_f32_e32 v92, v56, v86
	v_fmac_f32_e32 v92, v29, v74
	v_mul_f32_e32 v29, v67, v91
	v_fmac_f32_e32 v29, v56, v87
	v_fmac_f32_e32 v29, v89, v75
	s_nop 0
	v_mul_f32_e32 v89, v83, v29
	v_fmac_f32_e32 v89, v92, v82
	v_fmac_f32_e32 v89, v90, v81
	v_fmac_f32_e32 v89, v88, v80
	ds_read_b128 v[56:59], v30 offset:14080
	ds_read_b128 v[64:67], v30 offset:9984
	ds_read_b128 v[72:75], v30 offset:5888
	ds_read_b128 v[80:83], v30 offset:1792
	ds_read_b128 v[84:87], v30 offset:18176
	ds_read_b32 v91, v33 offset:20928
	s_waitcnt lgkmcnt(12)
	v_mul_f32_e32 v7, v7, v29
	v_fmac_f32_e32 v7, v92, v6
	v_fmac_f32_e32 v7, v90, v5
	v_fmac_f32_e32 v7, v88, v4
	v_add_f32_dpp v5, v89, v89 quad_perm:[1,0,3,2] row_mask:0xf bank_mask:0xf bound_ctrl:1
	s_waitcnt lgkmcnt(7)
	v_mul_f32_e32 v89, v52, v93
	v_add_f32_dpp v4, v7, v7 quad_perm:[1,0,3,2] row_mask:0xf bank_mask:0xf bound_ctrl:1
	v_add_f32_dpp v5, v5, v5 quad_perm:[2,3,0,1] row_mask:0xf bank_mask:0xf bound_ctrl:1
	v_add_u32_e32 v6, v13, v40
	v_add_f32_dpp v4, v4, v4 quad_perm:[2,3,0,1] row_mask:0xf bank_mask:0xf bound_ctrl:1
	v_add_f32_dpp v5, v5, v5 row_half_mirror row_mask:0xf bank_mask:0xf bound_ctrl:1
	s_nop 0
	v_add_f32_dpp v4, v4, v4 row_half_mirror row_mask:0xf bank_mask:0xf bound_ctrl:1
	v_add_f32_dpp v5, v5, v5 row_mirror row_mask:0xf bank_mask:0xf bound_ctrl:1
	ds_write_b32 v6, v5 offset:21504
	v_add_f32_dpp v4, v4, v4 row_mirror row_mask:0xf bank_mask:0xf bound_ctrl:1
	v_fmac_f32_e32 v89, v4, v76
	v_fmac_f32_e32 v89, v88, v60
	v_mul_f32_e32 v88, v53, v93
	v_fmac_f32_e32 v88, v4, v77
	v_fmac_f32_e32 v88, v90, v61
	v_mul_f32_e32 v90, v54, v93
	v_fmac_f32_e32 v90, v4, v78
	v_fmac_f32_e32 v90, v92, v62
	v_mul_f32_e32 v92, v55, v93
	v_fmac_f32_e32 v92, v4, v79
	v_fmac_f32_e32 v92, v29, v63
	s_nop 0
	v_mul_f32_e32 v29, v71, v92
	v_fmac_f32_e32 v29, v90, v70
	v_fmac_f32_e32 v29, v88, v69
	v_fmac_f32_e32 v29, v89, v68
	ds_read_b128 v[4:7], v30 offset:14336
	ds_read_b128 v[52:55], v30 offset:10240
	ds_read_b128 v[60:63], v30 offset:6144
	ds_read_b128 v[68:71], v30 offset:2048
	ds_read_b128 v[76:79], v30 offset:18432
	ds_read_b32 v93, v33 offset:20992
	s_waitcnt lgkmcnt(12)
	v_mul_f32_e32 v59, v59, v92
	v_fmac_f32_e32 v59, v90, v58
	v_fmac_f32_e32 v59, v88, v57
	v_fmac_f32_e32 v59, v89, v56
	v_add_f32_dpp v29, v29, v29 quad_perm:[1,0,3,2] row_mask:0xf bank_mask:0xf bound_ctrl:1
	v_add_u32_e32 v57, v13, v41
	v_add_f32_dpp v56, v59, v59 quad_perm:[1,0,3,2] row_mask:0xf bank_mask:0xf bound_ctrl:1
	v_add_f32_dpp v29, v29, v29 quad_perm:[2,3,0,1] row_mask:0xf bank_mask:0xf bound_ctrl:1
	s_waitcnt lgkmcnt(7)
	v_mul_f32_e32 v94, v64, v91
	v_add_f32_dpp v56, v56, v56 quad_perm:[2,3,0,1] row_mask:0xf bank_mask:0xf bound_ctrl:1
	v_add_f32_dpp v29, v29, v29 row_half_mirror row_mask:0xf bank_mask:0xf bound_ctrl:1
	s_nop 0
	v_add_f32_dpp v56, v56, v56 row_half_mirror row_mask:0xf bank_mask:0xf bound_ctrl:1
	v_add_f32_dpp v29, v29, v29 row_mirror row_mask:0xf bank_mask:0xf bound_ctrl:1
	ds_write_b32 v57, v29 offset:21504
	s_nop 0
	v_add_f32_dpp v29, v56, v56 row_mirror row_mask:0xf bank_mask:0xf bound_ctrl:1
	v_fmac_f32_e32 v94, v29, v84
	v_fmac_f32_e32 v94, v89, v72
	v_mul_f32_e32 v89, v65, v91
	v_fmac_f32_e32 v89, v29, v85
	v_fmac_f32_e32 v89, v88, v73
	v_mul_f32_e32 v88, v66, v91
	v_fmac_f32_e32 v88, v29, v86
	v_fmac_f32_e32 v88, v90, v74
	v_mul_f32_e32 v90, v67, v91
	v_fmac_f32_e32 v90, v29, v87
	v_fmac_f32_e32 v90, v92, v75
	s_nop 0
	v_mul_f32_e32 v29, v83, v90
	v_fmac_f32_e32 v29, v88, v82
	v_fmac_f32_e32 v29, v89, v81
	v_fmac_f32_e32 v29, v94, v80
	ds_read_b128 v[56:59], v30 offset:14592
	ds_read_b128 v[64:67], v30 offset:10496
	ds_read_b128 v[72:75], v30 offset:6400
	ds_read_b128 v[80:83], v30 offset:2304
	ds_read_b128 v[84:87], v30 offset:18688
	ds_read_b32 v91, v33 offset:21056
	s_waitcnt lgkmcnt(12)
	v_mul_f32_e32 v7, v7, v90
	v_fmac_f32_e32 v7, v88, v6
	v_fmac_f32_e32 v7, v89, v5
	v_fmac_f32_e32 v7, v94, v4
	s_waitcnt lgkmcnt(7)
	v_mul_f32_e32 v92, v53, v93
	v_add_f32_dpp v5, v29, v29 quad_perm:[1,0,3,2] row_mask:0xf bank_mask:0xf bound_ctrl:1
	v_add_f32_dpp v4, v7, v7 quad_perm:[1,0,3,2] row_mask:0xf bank_mask:0xf bound_ctrl:1
	v_mul_f32_e32 v29, v52, v93
	v_add_f32_dpp v5, v5, v5 quad_perm:[2,3,0,1] row_mask:0xf bank_mask:0xf bound_ctrl:1
	v_add_f32_dpp v4, v4, v4 quad_perm:[2,3,0,1] row_mask:0xf bank_mask:0xf bound_ctrl:1
	v_add_u32_e32 v6, v13, v43
	v_add_f32_dpp v5, v5, v5 row_half_mirror row_mask:0xf bank_mask:0xf bound_ctrl:1
	v_add_f32_dpp v4, v4, v4 row_half_mirror row_mask:0xf bank_mask:0xf bound_ctrl:1
	s_nop 0
	v_add_f32_dpp v5, v5, v5 row_mirror row_mask:0xf bank_mask:0xf bound_ctrl:1
	v_add_f32_dpp v4, v4, v4 row_mirror row_mask:0xf bank_mask:0xf bound_ctrl:1
	v_fmac_f32_e32 v92, v4, v77
	v_fmac_f32_e32 v92, v89, v61
	v_mul_f32_e32 v89, v54, v93
	v_fmac_f32_e32 v89, v4, v78
	v_fmac_f32_e32 v89, v88, v62
	v_mul_f32_e32 v88, v55, v93
	v_fmac_f32_e32 v88, v4, v79
	v_fmac_f32_e32 v88, v90, v63
	v_fmac_f32_e32 v29, v4, v76
	v_mul_f32_e32 v90, v71, v88
	v_fmac_f32_e32 v29, v94, v60
	v_fmac_f32_e32 v90, v89, v70
	ds_write_b32 v6, v5 offset:21504
	v_fmac_f32_e32 v90, v92, v69
	s_nop 0
	v_fmac_f32_e32 v90, v29, v68
	ds_read_b128 v[4:7], v30 offset:14848
	ds_read_b128 v[52:55], v30 offset:10752
	ds_read_b128 v[60:63], v30 offset:6656
	ds_read_b128 v[68:71], v30 offset:2560
	ds_read_b128 v[76:79], v30 offset:18944
	ds_read_b32 v93, v33 offset:21120
	s_waitcnt lgkmcnt(12)
	v_mul_f32_e32 v59, v59, v88
	v_fmac_f32_e32 v59, v89, v58
	v_fmac_f32_e32 v59, v92, v57
	v_fmac_f32_e32 v59, v29, v56
	v_add_f32_dpp v57, v90, v90 quad_perm:[1,0,3,2] row_mask:0xf bank_mask:0xf bound_ctrl:1
	s_waitcnt lgkmcnt(7)
	v_mul_f32_e32 v90, v64, v91
	v_add_f32_dpp v56, v59, v59 quad_perm:[1,0,3,2] row_mask:0xf bank_mask:0xf bound_ctrl:1
	v_add_f32_dpp v57, v57, v57 quad_perm:[2,3,0,1] row_mask:0xf bank_mask:0xf bound_ctrl:1
	v_add_u32_e32 v58, v13, v44
	v_add_f32_dpp v56, v56, v56 quad_perm:[2,3,0,1] row_mask:0xf bank_mask:0xf bound_ctrl:1
	v_add_f32_dpp v57, v57, v57 row_half_mirror row_mask:0xf bank_mask:0xf bound_ctrl:1
	s_nop 0
	v_add_f32_dpp v56, v56, v56 row_half_mirror row_mask:0xf bank_mask:0xf bound_ctrl:1
	v_add_f32_dpp v57, v57, v57 row_mirror row_mask:0xf bank_mask:0xf bound_ctrl:1
	ds_write_b32 v58, v57 offset:21504
	v_add_f32_dpp v56, v56, v56 row_mirror row_mask:0xf bank_mask:0xf bound_ctrl:1
	v_fmac_f32_e32 v90, v56, v84
	v_fmac_f32_e32 v90, v29, v72
	v_mul_f32_e32 v29, v65, v91
	v_fmac_f32_e32 v29, v56, v85
	v_fmac_f32_e32 v29, v92, v73
	v_mul_f32_e32 v92, v66, v91
	v_fmac_f32_e32 v92, v56, v86
	v_fmac_f32_e32 v92, v89, v74
	v_mul_f32_e32 v89, v67, v91
	v_fmac_f32_e32 v89, v56, v87
	v_fmac_f32_e32 v89, v88, v75
	s_nop 0
	v_mul_f32_e32 v88, v83, v89
	v_fmac_f32_e32 v88, v92, v82
	v_fmac_f32_e32 v88, v29, v81
	v_fmac_f32_e32 v88, v90, v80
	ds_read_b128 v[56:59], v30 offset:15104
	ds_read_b128 v[64:67], v30 offset:11008
	ds_read_b128 v[72:75], v30 offset:6912
	ds_read_b128 v[80:83], v30 offset:2816
	ds_read_b128 v[84:87], v30 offset:19200
	ds_read_b32 v91, v33 offset:21184
	s_waitcnt lgkmcnt(12)
	v_mul_f32_e32 v7, v7, v89
	v_fmac_f32_e32 v7, v92, v6
	v_fmac_f32_e32 v7, v29, v5
	v_fmac_f32_e32 v7, v90, v4
	v_add_f32_dpp v5, v88, v88 quad_perm:[1,0,3,2] row_mask:0xf bank_mask:0xf bound_ctrl:1
	s_waitcnt lgkmcnt(7)
	v_mul_f32_e32 v88, v52, v93
	v_add_f32_dpp v4, v7, v7 quad_perm:[1,0,3,2] row_mask:0xf bank_mask:0xf bound_ctrl:1
	v_add_f32_dpp v5, v5, v5 quad_perm:[2,3,0,1] row_mask:0xf bank_mask:0xf bound_ctrl:1
	v_add_u32_e32 v6, v13, v45
	v_add_f32_dpp v4, v4, v4 quad_perm:[2,3,0,1] row_mask:0xf bank_mask:0xf bound_ctrl:1
	v_add_f32_dpp v5, v5, v5 row_half_mirror row_mask:0xf bank_mask:0xf bound_ctrl:1
	s_nop 0
	v_add_f32_dpp v4, v4, v4 row_half_mirror row_mask:0xf bank_mask:0xf bound_ctrl:1
	v_add_f32_dpp v5, v5, v5 row_mirror row_mask:0xf bank_mask:0xf bound_ctrl:1
	ds_write_b32 v6, v5 offset:21504
	v_add_f32_dpp v4, v4, v4 row_mirror row_mask:0xf bank_mask:0xf bound_ctrl:1
	v_fmac_f32_e32 v88, v4, v76
	v_fmac_f32_e32 v88, v90, v60
	v_mul_f32_e32 v90, v53, v93
	v_fmac_f32_e32 v90, v4, v77
	v_fmac_f32_e32 v90, v29, v61
	v_mul_f32_e32 v29, v54, v93
	v_fmac_f32_e32 v29, v4, v78
	v_fmac_f32_e32 v29, v92, v62
	v_mul_f32_e32 v92, v55, v93
	v_fmac_f32_e32 v92, v4, v79
	v_fmac_f32_e32 v92, v89, v63
	s_nop 0
	v_mul_f32_e32 v89, v71, v92
	v_fmac_f32_e32 v89, v29, v70
	v_fmac_f32_e32 v89, v90, v69
	v_fmac_f32_e32 v89, v88, v68
	ds_read_b128 v[4:7], v30 offset:15360
	ds_read_b128 v[52:55], v30 offset:11264
	ds_read_b128 v[60:63], v30 offset:7168
	ds_read_b128 v[68:71], v30 offset:3072
	ds_read_b128 v[76:79], v30 offset:19456
	ds_read_b32 v93, v33 offset:21248
	s_waitcnt lgkmcnt(12)
	v_mul_f32_e32 v59, v59, v92
	v_fmac_f32_e32 v59, v29, v58
	v_fmac_f32_e32 v59, v90, v57
	v_fmac_f32_e32 v59, v88, v56
	v_add_f32_dpp v57, v89, v89 quad_perm:[1,0,3,2] row_mask:0xf bank_mask:0xf bound_ctrl:1
	s_waitcnt lgkmcnt(7)
	v_mul_f32_e32 v89, v64, v91
	v_add_f32_dpp v56, v59, v59 quad_perm:[1,0,3,2] row_mask:0xf bank_mask:0xf bound_ctrl:1
	v_add_f32_dpp v57, v57, v57 quad_perm:[2,3,0,1] row_mask:0xf bank_mask:0xf bound_ctrl:1
	v_add_u32_e32 v58, v13, v46
	v_add_f32_dpp v56, v56, v56 quad_perm:[2,3,0,1] row_mask:0xf bank_mask:0xf bound_ctrl:1
	v_add_f32_dpp v57, v57, v57 row_half_mirror row_mask:0xf bank_mask:0xf bound_ctrl:1
	s_nop 0
	v_add_f32_dpp v56, v56, v56 row_half_mirror row_mask:0xf bank_mask:0xf bound_ctrl:1
	v_add_f32_dpp v57, v57, v57 row_mirror row_mask:0xf bank_mask:0xf bound_ctrl:1
	ds_write_b32 v58, v57 offset:21504
	v_add_f32_dpp v56, v56, v56 row_mirror row_mask:0xf bank_mask:0xf bound_ctrl:1
	v_fmac_f32_e32 v89, v56, v84
	v_fmac_f32_e32 v89, v88, v72
	v_mul_f32_e32 v88, v65, v91
	v_fmac_f32_e32 v88, v56, v85
	v_fmac_f32_e32 v88, v90, v73
	v_mul_f32_e32 v90, v66, v91
	v_fmac_f32_e32 v90, v56, v86
	v_fmac_f32_e32 v90, v29, v74
	v_mul_f32_e32 v29, v67, v91
	v_fmac_f32_e32 v29, v56, v87
	v_fmac_f32_e32 v29, v92, v75
	s_nop 0
	v_mul_f32_e32 v91, v83, v29
	v_fmac_f32_e32 v91, v90, v82
	v_fmac_f32_e32 v91, v88, v81
	v_fmac_f32_e32 v91, v89, v80
	ds_read_b128 v[56:59], v30 offset:15616
	ds_read_b128 v[64:67], v30 offset:11520
	ds_read_b128 v[72:75], v30 offset:7424
	ds_read_b128 v[80:83], v30 offset:3328
	ds_read_b128 v[84:87], v30 offset:19712
	ds_read_b32 v92, v33 offset:21312
	s_waitcnt lgkmcnt(12)
	v_mul_f32_e32 v7, v7, v29
	v_fmac_f32_e32 v7, v90, v6
	v_fmac_f32_e32 v7, v88, v5
	v_fmac_f32_e32 v7, v89, v4
	v_add_f32_dpp v5, v91, v91 quad_perm:[1,0,3,2] row_mask:0xf bank_mask:0xf bound_ctrl:1
	s_waitcnt lgkmcnt(7)
	v_mul_f32_e32 v91, v52, v93
	v_add_f32_dpp v4, v7, v7 quad_perm:[1,0,3,2] row_mask:0xf bank_mask:0xf bound_ctrl:1
	v_add_f32_dpp v5, v5, v5 quad_perm:[2,3,0,1] row_mask:0xf bank_mask:0xf bound_ctrl:1
	v_add_u32_e32 v6, v13, v47
	v_add_f32_dpp v4, v4, v4 quad_perm:[2,3,0,1] row_mask:0xf bank_mask:0xf bound_ctrl:1
	v_add_f32_dpp v5, v5, v5 row_half_mirror row_mask:0xf bank_mask:0xf bound_ctrl:1
	s_nop 0
	v_add_f32_dpp v4, v4, v4 row_half_mirror row_mask:0xf bank_mask:0xf bound_ctrl:1
	v_add_f32_dpp v5, v5, v5 row_mirror row_mask:0xf bank_mask:0xf bound_ctrl:1
	ds_write_b32 v6, v5 offset:21504
	v_add_f32_dpp v4, v4, v4 row_mirror row_mask:0xf bank_mask:0xf bound_ctrl:1
	v_fmac_f32_e32 v91, v4, v76
	v_fmac_f32_e32 v91, v89, v60
	v_mul_f32_e32 v89, v53, v93
	v_fmac_f32_e32 v89, v4, v77
	v_fmac_f32_e32 v89, v88, v61
	v_mul_f32_e32 v88, v54, v93
	v_fmac_f32_e32 v88, v4, v78
	v_fmac_f32_e32 v88, v90, v62
	v_mul_f32_e32 v90, v55, v93
	v_fmac_f32_e32 v90, v4, v79
	v_fmac_f32_e32 v90, v29, v63
	s_nop 0
	v_mul_f32_e32 v29, v71, v90
	v_fmac_f32_e32 v29, v88, v70
	v_fmac_f32_e32 v29, v89, v69
	v_fmac_f32_e32 v29, v91, v68
	ds_read_b128 v[4:7], v30 offset:15872
	ds_read_b128 v[52:55], v30 offset:11776
	ds_read_b128 v[60:63], v30 offset:7680
	ds_read_b128 v[68:71], v30 offset:3584
	ds_read_b128 v[76:79], v30 offset:19968
	ds_read_b32 v93, v33 offset:21376
	s_waitcnt lgkmcnt(12)
	v_mul_f32_e32 v59, v59, v90
	v_fmac_f32_e32 v59, v88, v58
	v_fmac_f32_e32 v59, v89, v57
	v_fmac_f32_e32 v59, v91, v56
	v_add_f32_dpp v29, v29, v29 quad_perm:[1,0,3,2] row_mask:0xf bank_mask:0xf bound_ctrl:1
	v_add_u32_e32 v57, v13, v48
	v_add_f32_dpp v56, v59, v59 quad_perm:[1,0,3,2] row_mask:0xf bank_mask:0xf bound_ctrl:1
	v_add_f32_dpp v29, v29, v29 quad_perm:[2,3,0,1] row_mask:0xf bank_mask:0xf bound_ctrl:1
	s_waitcnt lgkmcnt(7)
	v_mul_f32_e32 v94, v64, v92
	v_add_f32_dpp v56, v56, v56 quad_perm:[2,3,0,1] row_mask:0xf bank_mask:0xf bound_ctrl:1
	v_add_f32_dpp v29, v29, v29 row_half_mirror row_mask:0xf bank_mask:0xf bound_ctrl:1
	s_nop 0
	v_add_f32_dpp v56, v56, v56 row_half_mirror row_mask:0xf bank_mask:0xf bound_ctrl:1
	v_add_f32_dpp v29, v29, v29 row_mirror row_mask:0xf bank_mask:0xf bound_ctrl:1
	ds_write_b32 v57, v29 offset:21504
	s_nop 0
	v_add_f32_dpp v29, v56, v56 row_mirror row_mask:0xf bank_mask:0xf bound_ctrl:1
	v_fmac_f32_e32 v94, v29, v84
	v_fmac_f32_e32 v94, v91, v72
	v_mul_f32_e32 v91, v65, v92
	v_fmac_f32_e32 v91, v29, v85
	v_fmac_f32_e32 v91, v89, v73
	v_mul_f32_e32 v89, v66, v92
	v_fmac_f32_e32 v89, v29, v86
	v_fmac_f32_e32 v89, v88, v74
	v_mul_f32_e32 v88, v67, v92
	v_fmac_f32_e32 v88, v29, v87
	v_fmac_f32_e32 v88, v90, v75
	s_nop 0
	v_mul_f32_e32 v29, v83, v88
	v_fmac_f32_e32 v29, v89, v82
	v_fmac_f32_e32 v29, v91, v81
	v_fmac_f32_e32 v29, v94, v80
	ds_read_b128 v[56:59], v30 offset:16128
	ds_read_b128 v[64:67], v30 offset:12032
	ds_read_b128 v[72:75], v30 offset:7936
	ds_read_b128 v[80:83], v30 offset:3840
	ds_read_b128 v[84:87], v30 offset:20224
	ds_read_b32 v90, v33 offset:21440
	s_waitcnt lgkmcnt(12)
	v_mul_f32_e32 v7, v7, v88
	v_fmac_f32_e32 v7, v89, v6
	v_fmac_f32_e32 v7, v91, v5
	v_fmac_f32_e32 v7, v94, v4
	v_add_f32_dpp v5, v29, v29 quad_perm:[1,0,3,2] row_mask:0xf bank_mask:0xf bound_ctrl:1
	s_waitcnt lgkmcnt(7)
	v_mul_f32_e32 v29, v55, v93
	v_add_f32_dpp v4, v7, v7 quad_perm:[1,0,3,2] row_mask:0xf bank_mask:0xf bound_ctrl:1
	v_add_f32_dpp v5, v5, v5 quad_perm:[2,3,0,1] row_mask:0xf bank_mask:0xf bound_ctrl:1
	v_add_u32_e32 v6, v13, v49
	v_add_f32_dpp v4, v4, v4 quad_perm:[2,3,0,1] row_mask:0xf bank_mask:0xf bound_ctrl:1
	v_add_f32_dpp v5, v5, v5 row_half_mirror row_mask:0xf bank_mask:0xf bound_ctrl:1
	v_mul_f32_e32 v7, v54, v93
	v_add_f32_dpp v4, v4, v4 row_half_mirror row_mask:0xf bank_mask:0xf bound_ctrl:1
	v_add_f32_dpp v5, v5, v5 row_mirror row_mask:0xf bank_mask:0xf bound_ctrl:1
	ds_write_b32 v6, v5 offset:21504
	v_add_f32_dpp v4, v4, v4 row_mirror row_mask:0xf bank_mask:0xf bound_ctrl:1
	v_fmac_f32_e32 v29, v4, v79
	v_mul_f32_e32 v5, v52, v93
	v_mul_f32_e32 v6, v53, v93
	v_fmac_f32_e32 v7, v4, v78
	v_fmac_f32_e32 v29, v88, v63
	v_fmac_f32_e32 v5, v4, v76
	v_fmac_f32_e32 v6, v4, v77
	v_fmac_f32_e32 v7, v89, v62
	v_fmac_f32_e32 v6, v91, v61
	v_mul_f32_e32 v4, v71, v29
	v_fmac_f32_e32 v5, v94, v60
	v_fmac_f32_e32 v4, v7, v70
	s_nop 0
	v_fmac_f32_e32 v4, v6, v69
	v_fmac_f32_e32 v4, v5, v68
	s_waitcnt lgkmcnt(6)
	v_mul_f32_e32 v52, v59, v29
	v_fmac_f32_e32 v52, v7, v58
	v_fmac_f32_e32 v52, v6, v57
	v_fmac_f32_e32 v52, v5, v56
	v_add_f32_dpp v4, v4, v4 quad_perm:[1,0,3,2] row_mask:0xf bank_mask:0xf bound_ctrl:1
	v_add_u32_e32 v13, v13, v50
	v_add_f32_dpp v52, v52, v52 quad_perm:[1,0,3,2] row_mask:0xf bank_mask:0xf bound_ctrl:1
	v_add_f32_dpp v4, v4, v4 quad_perm:[2,3,0,1] row_mask:0xf bank_mask:0xf bound_ctrl:1
	s_nop 0
	v_add_f32_dpp v52, v52, v52 quad_perm:[2,3,0,1] row_mask:0xf bank_mask:0xf bound_ctrl:1
	v_add_f32_dpp v4, v4, v4 row_half_mirror row_mask:0xf bank_mask:0xf bound_ctrl:1
	s_nop 0
	v_add_f32_dpp v52, v52, v52 row_half_mirror row_mask:0xf bank_mask:0xf bound_ctrl:1
	v_add_f32_dpp v4, v4, v4 row_mirror row_mask:0xf bank_mask:0xf bound_ctrl:1
	ds_write_b32 v13, v4 offset:21504
	v_add_f32_dpp v13, v52, v52 row_mirror row_mask:0xf bank_mask:0xf bound_ctrl:1
	s_waitcnt lgkmcnt(2)
	v_mul_f32_e32 v4, v64, v90
	v_fmac_f32_e32 v4, v13, v84
	v_fmac_f32_e32 v4, v5, v72
	v_mul_f32_e32 v5, v65, v90
	v_fmac_f32_e32 v5, v13, v85
	v_fmac_f32_e32 v5, v6, v73
	v_mul_f32_e32 v6, v66, v90
	v_fmac_f32_e32 v6, v13, v86
	v_fmac_f32_e32 v6, v7, v74
	v_mul_f32_e32 v7, v67, v90
	v_fmac_f32_e32 v7, v13, v87
	v_fmac_f32_e32 v7, v29, v75
	s_nop 0
	v_mul_f32_e32 v13, v83, v7
	v_fmac_f32_e32 v13, v6, v82
	v_fmac_f32_e32 v13, v5, v81
	v_fmac_f32_e32 v13, v4, v80
	s_nop 1
	v_add_f32_dpp v13, v13, v13 quad_perm:[1,0,3,2] row_mask:0xf bank_mask:0xf bound_ctrl:1
	s_nop 1
	v_add_f32_dpp v13, v13, v13 quad_perm:[2,3,0,1] row_mask:0xf bank_mask:0xf bound_ctrl:1
	s_nop 1
	v_add_f32_dpp v13, v13, v13 row_half_mirror row_mask:0xf bank_mask:0xf bound_ctrl:1
	s_nop 1
	v_add_f32_dpp v13, v13, v13 row_mirror row_mask:0xf bank_mask:0xf bound_ctrl:1
	ds_write_b32 v2, v13 offset:21504
	s_addk_i32 s10, 0x100
	s_add_i32 s3, s3, 1
	s_cmp_lg_u32 s11, s10
	v_add_u32_e32 v28, 16, v28
	s_waitcnt lgkmcnt(0)
	s_cbranch_scc0 .Lrw1_exitb
.LBB0_1094:
	v_add_u32_e32 v31, s76, v31
	v_add_u32_e32 v32, s76, v32
	s_waitcnt vmcnt(3)
	v_lshlrev_b32_e32 v2, 16, v14
	v_mul_f32_e32 v2, 0x3fb8aa3b, v2
	v_exp_f32_e32 v56, v2
	v_and_b32_e32 v2, 0xffff0000, v14
	v_mul_f32_e32 v2, 0x3fb8aa3b, v2
	v_exp_f32_e32 v57, v2
	v_lshlrev_b32_e32 v2, 16, v15
	v_mul_f32_e32 v2, 0x3fb8aa3b, v2
	v_exp_f32_e32 v58, v2
	v_and_b32_e32 v2, 0xffff0000, v15
	v_mul_f32_e32 v2, 0x3fb8aa3b, v2
	v_exp_f32_e32 v59, v2
	s_waitcnt vmcnt(2)
	v_and_b32_e32 v53, 0xffff0000, v16
	v_lshlrev_b32_e32 v52, 16, v16
	v_and_b32_e32 v55, 0xffff0000, v17
	v_lshlrev_b32_e32 v54, 16, v17
	ds_write_b128 v31, v[52:55]
	s_waitcnt vmcnt(1)
	v_and_b32_e32 v53, 0xffff0000, v20
	v_lshlrev_b32_e32 v52, 16, v20
	v_and_b32_e32 v55, 0xffff0000, v21
	v_lshlrev_b32_e32 v54, 16, v21
	s_waitcnt vmcnt(2)
	v_and_b32_e32 v2, 0xffff0000, v18
	v_lshlrev_b32_e32 v13, 16, v18
	ds_write_b128 v31, v[52:55] offset:8192
	ds_write_b128 v31, v[56:59] offset:4096
	v_xor_b32_e32 v53, 0x80000000, v2
	v_xor_b32_e32 v52, 0x80000000, v13
	v_and_b32_e32 v2, 0xffff0000, v19
	v_lshlrev_b32_e32 v13, 16, v19
	s_and_b32 s24, s10, 0x100
	v_xor_b32_e32 v55, 0x80000000, v2
	v_xor_b32_e32 v54, 0x80000000, v13
	v_ashrrev_i32_e32 v29, 31, v28
	ds_write_b128 v31, v[52:55] offset:12288
	s_waitcnt vmcnt(1)
	v_and_b32_e32 v53, 0xffff0000, v22
	v_lshlrev_b32_e32 v52, 16, v22
	v_and_b32_e32 v55, 0xffff0000, v23
	v_lshlrev_b32_e32 v54, 16, v23
	s_waitcnt vmcnt(0)
	v_lshlrev_b32_e32 v2, 16, v27
	s_cmp_eq_u32 s10, 0
	ds_write_b128 v31, v[52:55] offset:16384
	ds_write_b32 v32, v2 offset:20480
	s_waitcnt lgkmcnt(0)
	s_barrier
	v_add_u32_e32 v30, s76, v30
	v_add_u32_e32 v33, s76, v33
	s_mul_i32 s76, s76, -1
	s_cbranch_scc1 .LBB0_1096
	s_xor_b32 s14, s24, 0x100
	v_lshl_add_u32 v2, s14, 2, v35
	ds_read_b32 v2, v2 offset:21504
	v_lshlrev_b64 v[52:53], 10, v[28:29]
	s_lshl_b32 s14, s9, 1
	v_lshl_add_u64 v[52:53], s[86:87], 0, v[52:53]
	v_lshl_add_u64 v[52:53], v[52:53], 0, s[14:15]
	s_waitcnt lgkmcnt(0)
	v_cvt_pk_bf16_f32 v13, v2, s0
	v_lshlrev_b32_e32 v2, 1, v10
	v_lshl_add_u64 v[52:53], v[52:53], 0, v[2:3]
	s_lshl_b32 s14, s2, 1
	v_lshl_add_u64 v[52:53], v[52:53], 0, s[14:15]
	v_add_co_u32_e32 v52, vcc, 0xffffc000, v52
	s_nop 1
	v_addc_co_u32_e32 v53, vcc, -1, v53, vcc
	global_store_short v[52:53], v13, off

.LBB0_1098:
	v_readlane_b32 s8, v159, 0
	v_readlane_b32 s9, v159, 1
	s_waitcnt vmcnt(0)
	s_barrier
	s_mov_b64 s[2:3], exec
	v_readlane_b32 s0, v159, 2
	v_readlane_b32 s1, v159, 3
	s_and_b64 s[0:1], s[2:3], s[0:1]
	v_readlane_b32 s72, v158, 22
	v_readlane_b32 s73, v158, 23
	s_mov_b64 exec, s[0:1]
	s_cbranch_execz .LBB0_1142
	s_mov_b64 s[0:1], src_shared_base
	v_mov_b32_e32 v0, 0xc800
	v_mov_b32_e32 v1, s1
	s_waitcnt vmcnt(0) expcnt(0) lgkmcnt(0)
	s_getreg_b32 s0, hwreg(HW_REG_XCC_ID, 0, 4)
	flat_load_dword v2, v[0:1] sc0 sc1
	s_waitcnt vmcnt(0)
	v_mov_b32_e32 v0, 0xc804
	flat_load_dword v0, v[0:1] sc0 sc1
	s_waitcnt vmcnt(0)
	s_and_b32 s33, s0, 15
	s_waitcnt lgkmcnt(0)
	v_cmp_eq_u32_e32 vcc, 0, v2
	s_and_saveexec_b64 s[36:37], vcc
	s_cbranch_execz .LBB0_1113
	s_add_u32 s4, s8, 0x1000
	s_addc_u32 s5, s9, 0
	s_add_u32 s6, s8, 0x1100
	s_addc_u32 s7, s9, 0
	s_add_u32 s10, s8, 0x1200
	s_addc_u32 s11, s9, 0
	s_add_u32 s12, s8, 0x1300
	s_addc_u32 s13, s9, 0
	s_mov_b32 s22, 1
	s_mov_b64 s[0:1], 0
	v_mov_b64_e32 v[0:1], s[8:9]
	v_mov_b64_e32 v[2:3], s[4:5]
	v_mov_b64_e32 v[4:5], s[6:7]
	v_mov_b64_e32 v[6:7], s[10:11]
	v_mov_b64_e32 v[8:9], s[12:13]
	s_branch .LBB0_1103

.LBB0_1339:
	v_readlane_b32 s0, v159, 0
	v_readlane_b32 s1, v159, 1
	s_waitcnt vmcnt(0)
	s_nop 0
	v_writelane_b32 v159, s0, 0
	s_barrier
	s_nop 0
	v_writelane_b32 v159, s1, 1
	s_mov_b64 s[2:3], exec
	v_readlane_b32 s0, v159, 2
	v_readlane_b32 s1, v159, 3
	s_and_b64 s[0:1], s[2:3], s[0:1]
	s_mov_b64 exec, s[0:1]
	s_cbranch_execz .LBB0_1383
	s_mov_b64 s[0:1], src_shared_base
	v_mov_b32_e32 v0, 0xc800
	v_mov_b32_e32 v1, s1
	s_waitcnt vmcnt(0) expcnt(0) lgkmcnt(0)
	s_getreg_b32 s0, hwreg(HW_REG_XCC_ID, 0, 4)
	flat_load_dword v2, v[0:1] sc0 sc1
	s_waitcnt vmcnt(0)
	v_mov_b32_e32 v0, 0xc804
	flat_load_dword v0, v[0:1] sc0 sc1
	s_waitcnt vmcnt(0)
	s_and_b32 s33, s0, 15
	s_waitcnt lgkmcnt(0)
	v_cmp_eq_u32_e32 vcc, 0, v2
	s_and_saveexec_b64 s[34:35], vcc
	s_cbranch_execz .LBB0_1354
	v_readlane_b32 s12, v159, 0
	v_readlane_b32 s13, v159, 1
	s_add_u32 s4, s12, 0x1000
	s_addc_u32 s5, s13, 0
	s_add_u32 s6, s12, 0x1100
	s_addc_u32 s7, s13, 0
	s_add_u32 s8, s12, 0x1200
	s_addc_u32 s9, s13, 0
	s_add_u32 s10, s12, 0x1300
	s_addc_u32 s11, s13, 0
	s_mov_b32 s20, 1
	s_mov_b64 s[0:1], 0
	v_mov_b64_e32 v[0:1], s[12:13]
	v_mov_b64_e32 v[2:3], s[4:5]
	v_mov_b64_e32 v[4:5], s[6:7]
	v_mov_b64_e32 v[6:7], s[8:9]
	v_mov_b64_e32 v[8:9], s[10:11]
	s_branch .LBB0_1344

.LBB0_1353:
	s_or_b64 exec, exec, s[0:1]
	s_cmp_eq_u32 s33, 15
	s_cselect_b64 vcc, -1, 0
	s_cmp_eq_u32 s33, 14
	s_cselect_b64 s[0:1], -1, 0
	s_cmp_eq_u32 s33, 13
	s_cselect_b64 s[4:5], -1, 0
	s_cmp_eq_u32 s33, 12
	s_cselect_b64 s[6:7], -1, 0
	s_cmp_eq_u32 s33, 11
	s_cselect_b64 s[8:9], -1, 0
	s_cmp_eq_u32 s33, 10
	s_cselect_b64 s[10:11], -1, 0
	s_cmp_eq_u32 s33, 9
	s_cselect_b64 s[12:13], -1, 0
	s_cmp_eq_u32 s33, 8
	s_cselect_b64 s[14:15], -1, 0
	s_cmp_eq_u32 s33, 7
	s_cselect_b64 s[16:17], -1, 0
	s_cmp_eq_u32 s33, 6
	s_cselect_b64 s[18:19], -1, 0
	s_cmp_eq_u32 s33, 5
	s_cselect_b64 s[20:21], -1, 0
	s_cmp_eq_u32 s33, 4
	s_cselect_b64 s[22:23], -1, 0
	s_cmp_eq_u32 s33, 3
	s_cselect_b64 s[24:25], -1, 0
	s_cmp_eq_u32 s33, 2
	s_cselect_b64 s[26:27], -1, 0
	s_cmp_eq_u32 s33, 1
	s_cselect_b64 s[28:29], -1, 0
	s_cmp_eq_u32 s33, 0
	s_cselect_b64 s[30:31], -1, 0
	v_cndmask_b32_e64 v0, 0, v25, s[30:31]
	v_cndmask_b32_e64 v0, v0, v10, s[28:29]
	v_cndmask_b32_e64 v0, v0, v11, s[26:27]
	v_cndmask_b32_e64 v0, v0, v12, s[24:25]
	v_cndmask_b32_e64 v0, v0, v13, s[22:23]
	v_cndmask_b32_e64 v0, v0, v14, s[20:21]
	v_cndmask_b32_e64 v0, v0, v15, s[18:19]
	v_cndmask_b32_e64 v0, v0, v16, s[16:17]
	v_cndmask_b32_e64 v0, v0, v17, s[14:15]
	v_cndmask_b32_e64 v0, v0, v18, s[12:13]
	v_cndmask_b32_e64 v0, v0, v19, s[10:11]
	v_cndmask_b32_e64 v0, v0, v20, s[8:9]
	v_cndmask_b32_e64 v0, v0, v21, s[6:7]
	v_cndmask_b32_e64 v0, v0, v22, s[4:5]
	v_cndmask_b32_e64 v0, v0, v23, s[0:1]
	v_cndmask_b32_e32 v0, v0, v24, vcc
	v_cmp_ne_u32_e32 vcc, 0, v25
	s_mov_b64 s[36:37], src_shared_base
	v_mov_b32_e32 v4, 0xc800
	v_cndmask_b32_e64 v1, 0, 1, vcc
	v_cmp_ne_u32_e32 vcc, 0, v10
	v_mov_b32_e32 v5, s37
	s_nop 0
	v_addc_co_u32_e32 v1, vcc, 0, v1, vcc
	v_cmp_ne_u32_e32 vcc, 0, v11
	s_nop 1
	v_cndmask_b32_e64 v2, 0, 1, vcc
	v_cmp_ne_u32_e32 vcc, 0, v12
	s_nop 1
	v_addc_co_u32_e32 v1, vcc, v1, v2, vcc
	v_cmp_ne_u32_e32 vcc, 0, v13
	s_nop 1
	v_cndmask_b32_e64 v2, 0, 1, vcc
	v_cmp_ne_u32_e32 vcc, 0, v14
	s_nop 1
	v_addc_co_u32_e32 v1, vcc, v1, v2, vcc
	v_cmp_ne_u32_e32 vcc, 0, v15
	s_nop 1
	v_cndmask_b32_e64 v2, 0, 1, vcc
	v_cmp_ne_u32_e32 vcc, 0, v16
	s_nop 1
	v_addc_co_u32_e32 v1, vcc, v1, v2, vcc
	v_cmp_ne_u32_e32 vcc, 0, v17
	s_nop 1
	v_cndmask_b32_e64 v2, 0, 1, vcc
	v_cmp_ne_u32_e32 vcc, 0, v18
	s_nop 1
	v_addc_co_u32_e32 v1, vcc, v1, v2, vcc
	v_cmp_ne_u32_e32 vcc, 0, v19
	s_nop 1
	v_cndmask_b32_e64 v2, 0, 1, vcc
	v_cmp_ne_u32_e32 vcc, 0, v20
	s_nop 1
	v_addc_co_u32_e32 v1, vcc, v1, v2, vcc
	v_cmp_ne_u32_e32 vcc, 0, v21
	s_nop 1
	v_cndmask_b32_e64 v2, 0, 1, vcc
	v_cmp_ne_u32_e32 vcc, 0, v22
	s_nop 1
	v_addc_co_u32_e32 v1, vcc, v1, v2, vcc
	v_cmp_ne_u32_e32 vcc, 0, v23
	s_nop 1
	v_cndmask_b32_e64 v2, 0, 1, vcc
	v_cmp_ne_u32_e32 vcc, 0, v24
	s_nop 1
	v_addc_co_u32_e32 v1, vcc, v1, v2, vcc
	v_max_u32_e32 v2, 1, v0
	v_max_u32_e32 v0, 1, v1
	flat_store_dword v[4:5], v2 sc0 sc1
	s_waitcnt vmcnt(0)
	v_mov_b32_e32 v4, 0xc804
	flat_store_dword v[4:5], v0 sc0 sc1
	s_waitcnt vmcnt(0)

	.amdhsa_kernel _Z6k_mega6Params
		.amdhsa_group_segment_fixed_size 51712
		.amdhsa_private_segment_fixed_size 0
		.amdhsa_kernarg_size 616
		.amdhsa_user_sgpr_count 2
		.amdhsa_user_sgpr_dispatch_ptr 0
		.amdhsa_user_sgpr_queue_ptr 0
		.amdhsa_user_sgpr_kernarg_segment_ptr 1
		.amdhsa_user_sgpr_dispatch_id 0
		.amdhsa_user_sgpr_kernarg_preload_length 0
		.amdhsa_user_sgpr_kernarg_preload_offset 0
		.amdhsa_user_sgpr_private_segment_size 0
		.amdhsa_uses_dynamic_stack 0
		.amdhsa_enable_private_segment 0
		.amdhsa_system_sgpr_workgroup_id_x 1
		.amdhsa_system_sgpr_workgroup_id_y 0
		.amdhsa_system_sgpr_workgroup_id_z 0
		.amdhsa_system_sgpr_workgroup_info 0
		.amdhsa_system_vgpr_workitem_id 2
		.amdhsa_next_free_vgpr 168
		.amdhsa_next_free_sgpr 98
		.amdhsa_accum_offset 168
		.amdhsa_reserve_vcc 1
		.amdhsa_float_round_mode_32 0
		.amdhsa_float_round_mode_16_64 0
		.amdhsa_float_denorm_mode_32 3
		.amdhsa_float_denorm_mode_16_64 3
		.amdhsa_dx10_clamp 1
		.amdhsa_ieee_mode 1
		.amdhsa_fp16_overflow 0
		.amdhsa_tg_split 0
		.amdhsa_exception_fp_ieee_invalid_op 0
		.amdhsa_exception_fp_denorm_src 0
		.amdhsa_exception_fp_ieee_div_zero 0
		.amdhsa_exception_fp_ieee_overflow 0
		.amdhsa_exception_fp_ieee_underflow 0
		.amdhsa_exception_fp_ieee_inexact 0
		.amdhsa_exception_int_div_zero 0
	.end_amdhsa_kernel

amdhsa.kernels:
  - .agpr_count:     0
    .args:
      - .offset:         0
        .size:           360
        .value_kind:     by_value
      - .offset:         360
        .size:           4
        .value_kind:     hidden_block_count_x
      - .offset:         364
        .size:           4
        .value_kind:     hidden_block_count_y
      - .offset:         368
        .size:           4
        .value_kind:     hidden_block_count_z
      - .offset:         372
        .size:           2
        .value_kind:     hidden_group_size_x
      - .offset:         374
        .size:           2
        .value_kind:     hidden_group_size_y
      - .offset:         376
        .size:           2
        .value_kind:     hidden_group_size_z
      - .offset:         378
        .size:           2
        .value_kind:     hidden_remainder_x
      - .offset:         380
        .size:           2
        .value_kind:     hidden_remainder_y
      - .offset:         382
        .size:           2
        .value_kind:     hidden_remainder_z
      - .offset:         400
        .size:           8
        .value_kind:     hidden_global_offset_x
      - .offset:         408
        .size:           8
        .value_kind:     hidden_global_offset_y
      - .offset:         416
        .size:           8
        .value_kind:     hidden_global_offset_z
      - .offset:         424
        .size:           2
        .value_kind:     hidden_grid_dims
      - .offset:         448
        .size:           8
        .value_kind:     hidden_multigrid_sync_arg
    .group_segment_fixed_size: 51712
    .kernarg_segment_align: 8
    .kernarg_segment_size: 616
    .language:       OpenCL C
    .language_version:
      - 2
      - 0
    .max_flat_workgroup_size: 256
    .name:           _Z6k_mega6Params
    .private_segment_fixed_size: 0
    .sgpr_count:     104
    .sgpr_spill_count: 130
    .symbol:         _Z6k_mega6Params.kd
    .uniform_work_group_size: 1
    .uses_dynamic_stack: false
    .vgpr_count:     168
    .vgpr_spill_count: 0
    .wavefront_size: 64
